# v30 with wave priorities swapped kernel-wide: MFMA bursts run at priority 0, all other code (address math, LDS reads, DMA issue, epilogues) at 1 or higher
# baseline (speedup 1.0000x reference)
.LBB0_303:
	s_setprio 3
	s_and_b32 s1, s0, 0x2000
	s_xor_b32 s8, s1, 0x2000
	s_lshl_b32 s101, s8, 1
	s_add_u32 s101, s101, s100
	s_add_u32 m0, s101, 0x0
	s_nop 0
	global_load_lds_dwordx4 v[184:185], off
	s_add_u32 m0, s101, 0x1000
	v_lshl_add_u64 v[184:185], v[184:185], 0, vcc
	global_load_lds_dwordx4 v[186:187], off
	s_add_u32 m0, s101, 0x2000
	v_lshl_add_u64 v[186:187], v[186:187], 0, vcc
	global_load_lds_dwordx4 v[188:189], off
	s_add_u32 m0, s101, 0x3000
	v_lshl_add_u64 v[188:189], v[188:189], 0, vcc
	global_load_lds_dwordx4 v[190:191], off
	s_add_u32 m0, s101, 0x8000
	v_lshl_add_u64 v[190:191], v[190:191], 0, vcc
	global_load_lds_dwordx4 v[192:193], off
	s_add_u32 m0, s101, 0x9000
	v_lshl_add_u64 v[192:193], v[192:193], 0, vcc
	global_load_lds_dwordx4 v[194:195], off
	s_add_u32 m0, s101, 0xa000
	v_lshl_add_u64 v[194:195], v[194:195], 0, vcc
	global_load_lds_dwordx4 v[196:197], off
	s_add_u32 m0, s101, 0xb000
	v_lshl_add_u64 v[196:197], v[196:197], 0, vcc
	global_load_lds_dwordx4 v[198:199], off
	v_lshl_add_u64 v[198:199], v[198:199], 0, vcc
	s_lshl_b32 s1, s1, 1
	v_add_u32_e32 v82, s1, v86
	v_add_u32_e32 v83, s1, v85
	v_add_u32_e32 v95, v82, v93
	ds_read_b128 v[96:99], v95
	ds_read_b128 v[100:103], v95 offset:2048
	ds_read_b128 v[120:123], v95 offset:4096
	ds_read_b128 v[124:127], v95 offset:6144
	v_add_u32_e32 v95, v83, v93
	ds_read_b128 v[128:131], v95 offset:32768
	ds_read_b128 v[132:135], v95 offset:34816
	ds_read_b128 v[136:139], v95 offset:36864
	ds_read_b128 v[140:143], v95 offset:38912
	s_setprio 0
	s_waitcnt lgkmcnt(0)
	v_mfma_f32_16x16x32_bf16 v[60:63], v[128:131], v[96:99], v[60:63]
	v_mfma_f32_16x16x32_bf16 v[56:59], v[132:135], v[96:99], v[56:59]
	v_mfma_f32_16x16x32_bf16 v[52:55], v[136:139], v[96:99], v[52:55]
	v_mfma_f32_16x16x32_bf16 v[48:51], v[140:143], v[96:99], v[48:51]
	v_mfma_f32_16x16x32_bf16 v[44:47], v[128:131], v[100:103], v[44:47]
	v_mfma_f32_16x16x32_bf16 v[40:43], v[132:135], v[100:103], v[40:43]
	v_mfma_f32_16x16x32_bf16 v[36:39], v[136:139], v[100:103], v[36:39]
	v_mfma_f32_16x16x32_bf16 v[32:35], v[140:143], v[100:103], v[32:35]
	v_mfma_f32_16x16x32_bf16 v[28:31], v[128:131], v[120:123], v[28:31]
	v_mfma_f32_16x16x32_bf16 v[24:27], v[132:135], v[120:123], v[24:27]
	v_mfma_f32_16x16x32_bf16 v[20:23], v[136:139], v[120:123], v[20:23]
	v_mfma_f32_16x16x32_bf16 v[16:19], v[140:143], v[120:123], v[16:19]
	v_mfma_f32_16x16x32_bf16 v[12:15], v[128:131], v[124:127], v[12:15]
	v_mfma_f32_16x16x32_bf16 v[8:11], v[132:135], v[124:127], v[8:11]
	v_mfma_f32_16x16x32_bf16 v[4:7], v[136:139], v[124:127], v[4:7]
	v_mfma_f32_16x16x32_bf16 v[0:3], v[140:143], v[124:127], v[0:3]
	s_setprio 2
	v_add_u32_e32 v82, v82, v94
	ds_read_b128 v[96:99], v82
	ds_read_b128 v[100:103], v82 offset:2048
	ds_read_b128 v[120:123], v82 offset:4096
	ds_read_b128 v[124:127], v82 offset:6144
	v_add_u32_e32 v82, v83, v94
	ds_read_b128 v[128:131], v82 offset:32768
	ds_read_b128 v[132:135], v82 offset:34816
	ds_read_b128 v[136:139], v82 offset:36864
	ds_read_b128 v[140:143], v82 offset:38912
	s_setprio 0
	s_waitcnt lgkmcnt(0)
	v_mfma_f32_16x16x32_bf16 v[60:63], v[128:131], v[96:99], v[60:63]
	v_mfma_f32_16x16x32_bf16 v[56:59], v[132:135], v[96:99], v[56:59]
	v_mfma_f32_16x16x32_bf16 v[52:55], v[136:139], v[96:99], v[52:55]
	v_mfma_f32_16x16x32_bf16 v[48:51], v[140:143], v[96:99], v[48:51]
	v_mfma_f32_16x16x32_bf16 v[44:47], v[128:131], v[100:103], v[44:47]
	v_mfma_f32_16x16x32_bf16 v[40:43], v[132:135], v[100:103], v[40:43]
	v_mfma_f32_16x16x32_bf16 v[36:39], v[136:139], v[100:103], v[36:39]
	v_mfma_f32_16x16x32_bf16 v[32:35], v[140:143], v[100:103], v[32:35]
	v_mfma_f32_16x16x32_bf16 v[28:31], v[128:131], v[120:123], v[28:31]
	v_mfma_f32_16x16x32_bf16 v[24:27], v[132:135], v[120:123], v[24:27]
	v_mfma_f32_16x16x32_bf16 v[20:23], v[136:139], v[120:123], v[20:23]
	v_mfma_f32_16x16x32_bf16 v[16:19], v[140:143], v[120:123], v[16:19]
	v_mfma_f32_16x16x32_bf16 v[12:15], v[128:131], v[124:127], v[12:15]
	v_mfma_f32_16x16x32_bf16 v[8:11], v[132:135], v[124:127], v[8:11]
	v_mfma_f32_16x16x32_bf16 v[4:7], v[136:139], v[124:127], v[4:7]
	v_mfma_f32_16x16x32_bf16 v[0:3], v[140:143], v[124:127], v[0:3]
	s_setprio 1
	s_addk_i32 s0, 0x2000
	s_waitcnt vmcnt(0)
	s_add_u32 s20, s20, 0x80
	s_addc_u32 s21, s21, 0
	s_cmpk_lg_i32 s20, 0x780
	s_waitcnt vmcnt(0)
	s_barrier
	s_cbranch_scc1 .LBB0_303
	ds_read_b128 v[78:81], v89 offset:55296
	ds_read_b128 v[96:99], v89 offset:53248
	ds_read_b128 v[100:103], v89 offset:51200
	ds_read_b128 v[120:123], v89 offset:49152
	ds_read_b128 v[124:127], v90 offset:22528
	ds_read_b128 v[128:131], v90 offset:20480
	ds_read_b128 v[132:135], v90 offset:18432
	ds_read_b128 v[136:139], v90 offset:16384
	s_setprio 0
	s_waitcnt lgkmcnt(0)
	v_mfma_f32_16x16x32_bf16 v[60:63], v[120:123], v[136:139], v[60:63]
	v_mfma_f32_16x16x32_bf16 v[56:59], v[100:103], v[136:139], v[56:59]
	v_mfma_f32_16x16x32_bf16 v[52:55], v[96:99], v[136:139], v[52:55]
	v_mfma_f32_16x16x32_bf16 v[48:51], v[78:81], v[136:139], v[48:51]
	v_mfma_f32_16x16x32_bf16 v[44:47], v[120:123], v[132:135], v[44:47]
	v_mfma_f32_16x16x32_bf16 v[40:43], v[100:103], v[132:135], v[40:43]
	v_mfma_f32_16x16x32_bf16 v[36:39], v[96:99], v[132:135], v[36:39]
	v_mfma_f32_16x16x32_bf16 v[32:35], v[78:81], v[132:135], v[32:35]
	v_mfma_f32_16x16x32_bf16 v[28:31], v[120:123], v[128:131], v[28:31]
	v_mfma_f32_16x16x32_bf16 v[24:27], v[100:103], v[128:131], v[24:27]
	v_mfma_f32_16x16x32_bf16 v[20:23], v[96:99], v[128:131], v[20:23]
	v_mfma_f32_16x16x32_bf16 v[16:19], v[78:81], v[128:131], v[16:19]
	v_mfma_f32_16x16x32_bf16 v[12:15], v[120:123], v[124:127], v[12:15]
	v_mfma_f32_16x16x32_bf16 v[8:11], v[100:103], v[124:127], v[8:11]
	v_mfma_f32_16x16x32_bf16 v[4:7], v[96:99], v[124:127], v[4:7]
	v_mfma_f32_16x16x32_bf16 v[0:3], v[78:81], v[124:127], v[0:3]
	s_setprio 1
	ds_read_b128 v[78:81], v91 offset:16384
	ds_read_b128 v[96:99], v91 offset:18432
	ds_read_b128 v[100:103], v91 offset:20480
	ds_read_b128 v[120:123], v91 offset:22528
	ds_read_b128 v[124:127], v92 offset:49152
	ds_read_b128 v[128:131], v92 offset:51200
	ds_read_b128 v[132:135], v92 offset:53248
	ds_read_b128 v[136:139], v92 offset:55296
	s_setprio 0
	s_waitcnt lgkmcnt(3)
	v_mfma_f32_16x16x32_bf16 v[60:63], v[124:127], v[78:81], v[60:63]
	s_waitcnt lgkmcnt(2)
	v_mfma_f32_16x16x32_bf16 v[56:59], v[128:131], v[78:81], v[56:59]
	s_waitcnt lgkmcnt(1)
	v_mfma_f32_16x16x32_bf16 v[52:55], v[132:135], v[78:81], v[52:55]
	s_waitcnt lgkmcnt(0)
	v_mfma_f32_16x16x32_bf16 v[48:51], v[136:139], v[78:81], v[48:51]
	v_mfma_f32_16x16x32_bf16 v[44:47], v[124:127], v[96:99], v[44:47]
	v_mfma_f32_16x16x32_bf16 v[40:43], v[128:131], v[96:99], v[40:43]
	v_mfma_f32_16x16x32_bf16 v[36:39], v[132:135], v[96:99], v[36:39]
	v_mfma_f32_16x16x32_bf16 v[32:35], v[136:139], v[96:99], v[32:35]
	v_mfma_f32_16x16x32_bf16 v[28:31], v[124:127], v[100:103], v[28:31]
	v_mfma_f32_16x16x32_bf16 v[24:27], v[128:131], v[100:103], v[24:27]
	v_mfma_f32_16x16x32_bf16 v[20:23], v[132:135], v[100:103], v[20:23]
	v_mfma_f32_16x16x32_bf16 v[16:19], v[136:139], v[100:103], v[16:19]
	v_mfma_f32_16x16x32_bf16 v[12:15], v[124:127], v[120:123], v[12:15]
	v_mfma_f32_16x16x32_bf16 v[8:11], v[128:131], v[120:123], v[8:11]
	v_mfma_f32_16x16x32_bf16 v[4:7], v[132:135], v[120:123], v[4:7]
	v_mfma_f32_16x16x32_bf16 v[0:3], v[136:139], v[120:123], v[0:3]
	s_setprio 1
	s_waitcnt vmcnt(0)
	s_cmp_lt_i32 s10, 32
	s_mov_b64 s[0:1], -1
	s_barrier
	s_cbranch_scc1 .LBB0_594
	s_cmp_eq_u32 s10, 32
	s_cselect_b64 s[0:1], -1, 0
	s_and_b64 vcc, exec, s[0:1]
	v_mov_b32_e32 v79, v63
	v_mov_b32_e32 v82, v62
	v_mov_b32_e32 v83, v61
	v_mov_b32_e32 v95, v60
	s_cbranch_vccz .LBB0_323
	v_cmp_nlt_f32_e64 s[8:9], |v60|, s33
	s_and_saveexec_b64 s[12:13], s[8:9]
	s_xor_b64 s[8:9], exec, s[12:13]
	s_cbranch_execz .LBB0_308
	v_add_f32_e64 v78, |v60|, |v60|
	v_mul_f32_e32 v79, 0x3fb8aa3b, v78
	v_rndne_f32_e32 v80, v79
	s_mov_b32 s11, 0x3fb8aa3b
	v_sub_f32_e32 v81, v79, v80
	v_fma_f32 v79, v78, s11, -v79
	v_fmac_f32_e32 v79, 0x32a5705f, v78
	v_add_f32_e32 v79, v81, v79
	v_cvt_i32_f32_e32 v80, v80
	v_exp_f32_e32 v79, v79
	s_mov_b32 s11, 0xc2ce8ed0
	v_cmp_ngt_f32_e32 vcc, s11, v78
	s_mov_b32 s11, 0x42b17218
	v_ldexp_f32 v79, v79, v80
	v_cndmask_b32_e32 v79, 0, v79, vcc
	v_cmp_nlt_f32_e32 vcc, s11, v78
	s_nop 1
	v_cndmask_b32_e32 v78, v112, v79, vcc
	v_add_f32_e32 v78, 1.0, v78
	v_rcp_f32_e32 v78, v78
	s_nop 0
	v_fma_f32 v78, v78, -2.0, 1.0

.LBB0_648:
	s_and_b32 s0, s10, 7
	s_mulk_i32 s0, 0x210
	s_ashr_i32 s1, s10, 3
	s_add_i32 s11, s0, s1
	s_mul_hi_i32 s0, s11, 0x3e0f83e1
	s_lshr_b32 s1, s0, 31
	s_ashr_i32 s0, s0, 8
	s_add_i32 s20, s0, s1
	s_mul_i32 s0, s20, 0x420
	s_sub_i32 s1, s11, s0
	s_lshl_b32 s0, s1, 4
	s_and_b32 s0, s0, 0xffffff80
	s_lshl_b32 s1, s1, 7
	s_and_b32 s18, s1, 0x380
	s_ashr_i32 s1, s0, 31
	s_lshl_b64 s[8:9], s[0:1], 9
	v_readlane_b32 s12, v182, 27
	v_readlane_b32 s13, v182, 28
	s_add_u32 s1, s12, s8
	s_addc_u32 s12, s13, s9
	s_lshl_b32 s8, s20, 6
	s_ashr_i32 s9, s8, 31
	s_lshl_b64 s[8:9], s[8:9], 1
	s_add_u32 s8, s1, s8
	s_addc_u32 s9, s12, s9
	s_ashr_i32 s21, s20, 31
	s_lshl_b64 s[12:13], s[20:21], 17
	v_readlane_b32 s1, v183, 55
	s_add_u32 s1, s1, s12
	v_readlane_b32 s12, v183, 56
	s_addc_u32 s13, s12, s13
	s_lshl_b32 s12, s18, 7
	s_add_u32 s12, s1, s12
	v_lshl_add_u64 v[0:1], s[8:9], 0, v[72:73]
	v_readfirstlane_b32 s1, v92
	v_add_u32_e32 v6, 0x1000, v92
	v_lshl_add_u64 v[0:1], v[0:1], 0, v[68:69]
	s_mov_b32 m0, s1
	s_mov_b64 s[8:9], 0x4000
	v_readfirstlane_b32 s1, v6
	v_add_u32_e32 v6, 0x2000, v92
	global_load_lds_dwordx4 v[0:1], off
	v_lshl_add_u64 v[4:5], v[0:1], 0, s[8:9]
	s_mov_b32 m0, s1
	s_mov_b64 s[8:9], 0x8000
	v_readfirstlane_b32 s1, v6
	global_load_lds_dwordx4 v[4:5], off
	v_lshl_add_u64 v[4:5], v[0:1], 0, s[8:9]
	s_mov_b32 m0, s1
	s_mov_b64 s[8:9], 0xc000
	global_load_lds_dwordx4 v[4:5], off
	v_add_u32_e32 v4, 0x3000, v92
	v_lshl_add_u64 v[0:1], v[0:1], 0, s[8:9]
	v_readfirstlane_b32 s1, v4
	s_mov_b32 m0, s1
	s_addc_u32 s13, s13, 0
	global_load_lds_dwordx4 v[0:1], off
	v_add_u32_e32 v0, 0x8000, v92
	v_lshl_add_u64 v[2:3], s[12:13], 0, v[74:75]
	v_readfirstlane_b32 s1, v0
	v_add_u32_e32 v4, 0x9000, v92
	v_lshl_add_u64 v[2:3], v[2:3], 0, v[68:69]
	s_mov_b32 m0, s1
	s_mov_b64 s[8:9], 0x1000
	v_readfirstlane_b32 s1, v4
	v_add_u32_e32 v4, 0xa000, v92
	global_load_lds_dwordx4 v[2:3], off
	v_lshl_add_u64 v[0:1], v[2:3], 0, s[8:9]
	s_mov_b32 m0, s1
	s_mov_b64 s[8:9], 0x2000
	v_readfirstlane_b32 s1, v4
	global_load_lds_dwordx4 v[0:1], off
	v_lshl_add_u64 v[0:1], v[2:3], 0, s[8:9]
	s_mov_b32 m0, s1
	s_mov_b64 s[8:9], 0x3000
	global_load_lds_dwordx4 v[0:1], off
	v_lshl_add_u64 v[0:1], v[2:3], 0, s[8:9]
	v_add_u32_e32 v2, 0xb000, v92
	s_nop 0
	v_readfirstlane_b32 s1, v2
	s_mov_b32 m0, s1
	s_nop 0
	global_load_lds_dwordx4 v[0:1], off
	s_waitcnt vmcnt(0)
	s_waitcnt vmcnt(0) lgkmcnt(0)
	s_barrier
	ds_read_b128 v[0:3], v88
	ds_read_b128 v[4:7], v88 offset:2048
	ds_read_b128 v[8:11], v88 offset:4096
	ds_read_b128 v[12:15], v88 offset:6144
	ds_read_b128 v[16:19], v89 offset:32768
	ds_read_b128 v[20:23], v89 offset:34816
	ds_read_b128 v[24:27], v89 offset:36864
	ds_read_b128 v[28:31], v89 offset:38912
	s_setprio 0
	s_waitcnt lgkmcnt(3)
	v_mfma_f32_16x16x32_bf16 v[32:35], v[16:19], v[0:3], 0
	s_waitcnt lgkmcnt(2)
	v_mfma_f32_16x16x32_bf16 v[36:39], v[20:23], v[0:3], 0
	s_waitcnt lgkmcnt(1)
	v_mfma_f32_16x16x32_bf16 v[40:43], v[24:27], v[0:3], 0
	s_waitcnt lgkmcnt(0)
	v_mfma_f32_16x16x32_bf16 v[0:3], v[28:31], v[0:3], 0
	v_mfma_f32_16x16x32_bf16 v[48:51], v[16:19], v[4:7], 0
	v_mfma_f32_16x16x32_bf16 v[52:55], v[20:23], v[4:7], 0
	v_mfma_f32_16x16x32_bf16 v[56:59], v[24:27], v[4:7], 0
	v_mfma_f32_16x16x32_bf16 v[4:7], v[28:31], v[4:7], 0
	v_mfma_f32_16x16x32_bf16 v[76:79], v[16:19], v[8:11], 0
	v_mfma_f32_16x16x32_bf16 v[80:83], v[20:23], v[8:11], 0
	v_mfma_f32_16x16x32_bf16 v[16:19], v[16:19], v[12:15], 0
	v_mfma_f32_16x16x32_bf16 v[94:97], v[24:27], v[8:11], 0
	v_mfma_f32_16x16x32_bf16 v[98:101], v[28:31], v[8:11], 0
	v_mfma_f32_16x16x32_bf16 v[120:123], v[20:23], v[12:15], 0
	v_mfma_f32_16x16x32_bf16 v[124:127], v[24:27], v[12:15], 0
	v_mfma_f32_16x16x32_bf16 v[128:131], v[28:31], v[12:15], 0
	s_setprio 1
	ds_read_b128 v[8:11], v90
	ds_read_b128 v[20:23], v90 offset:2048
	ds_read_b128 v[132:135], v90 offset:4096
	ds_read_b128 v[136:139], v90 offset:6144
	ds_read_b128 v[140:143], v91 offset:32768
	ds_read_b128 v[144:147], v91 offset:34816
	ds_read_b128 v[148:151], v91 offset:36864
	ds_read_b128 v[152:155], v91 offset:38912
	s_setprio 0
	s_waitcnt lgkmcnt(3)
	v_mfma_f32_16x16x32_bf16 v[156:159], v[140:143], v[8:11], v[32:35]
	s_waitcnt lgkmcnt(2)
	v_mfma_f32_16x16x32_bf16 v[44:47], v[144:147], v[8:11], v[36:39]
	s_waitcnt lgkmcnt(1)
	v_mfma_f32_16x16x32_bf16 v[28:31], v[148:151], v[8:11], v[40:43]
	s_waitcnt lgkmcnt(0)
	v_mfma_f32_16x16x32_bf16 v[12:15], v[152:155], v[8:11], v[0:3]
	v_mfma_f32_16x16x32_bf16 v[60:63], v[140:143], v[20:23], v[48:51]
	v_mfma_f32_16x16x32_bf16 v[40:43], v[144:147], v[20:23], v[52:55]
	v_mfma_f32_16x16x32_bf16 v[24:27], v[148:151], v[20:23], v[56:59]
	v_mfma_f32_16x16x32_bf16 v[8:11], v[152:155], v[20:23], v[4:7]
	v_mfma_f32_16x16x32_bf16 v[56:59], v[140:143], v[132:135], v[76:79]
	v_mfma_f32_16x16x32_bf16 v[36:39], v[144:147], v[132:135], v[80:83]
	v_mfma_f32_16x16x32_bf16 v[20:23], v[148:151], v[132:135], v[94:97]
	v_mfma_f32_16x16x32_bf16 v[4:7], v[152:155], v[132:135], v[98:101]
	v_mfma_f32_16x16x32_bf16 v[48:51], v[140:143], v[136:139], v[16:19]
	v_mfma_f32_16x16x32_bf16 v[32:35], v[144:147], v[136:139], v[120:123]
	v_mfma_f32_16x16x32_bf16 v[16:19], v[148:151], v[136:139], v[124:127]
	v_mfma_f32_16x16x32_bf16 v[0:3], v[152:155], v[136:139], v[128:131]
	s_setprio 1
	s_and_b32 s1, s20, 1
	s_cmpk_gt_i32 s11, 0x83f
	s_cselect_b64 s[24:25], -1, 0
	s_cmpk_lt_i32 s11, 0x840
	s_cselect_b64 s[36:37], -1, 0
	v_readlane_b32 s40, v183, 35
	s_and_b64 s[8:9], s[36:37], exec
	v_readlane_b32 s44, v183, 39
	v_readlane_b32 s45, v183, 40
	v_readlane_b32 s50, v183, 45
	v_readlane_b32 s51, v183, 46
	s_cselect_b32 s8, s45, s51
	s_cselect_b32 s9, s44, s50
	s_lshl_b32 s11, s1, 12
	s_add_u32 s20, s9, s11
	v_or_b32_e32 v79, s18, v87
	s_addc_u32 s21, s8, 0
	v_lshlrev_b32_e32 v78, 2, v79
	s_waitcnt vmcnt(0)
	s_barrier
	global_load_dwordx4 v[52:55], v78, s[20:21]
	global_load_dwordx4 v[184:187], v78, s[20:21] offset:64
	global_load_dwordx4 v[188:191], v78, s[20:21] offset:128
	global_load_dwordx4 v[192:195], v78, s[20:21] offset:192
	s_mov_b64 s[8:9], -1
	s_and_b64 vcc, exec, s[24:25]
	v_readlane_b32 s41, v183, 36
	v_readlane_b32 s42, v183, 37
	v_readlane_b32 s43, v183, 38
	v_readlane_b32 s46, v183, 41
	v_readlane_b32 s47, v183, 42
	v_readlane_b32 s48, v183, 43
	v_readlane_b32 s49, v183, 44
	v_readlane_b32 s52, v183, 47
	v_readlane_b32 s53, v183, 48
	v_readlane_b32 s54, v183, 49
	v_readlane_b32 s55, v183, 50
	s_waitcnt vmcnt(0)
	v_add_f32_e32 v76, v156, v52
	v_mul_f32_e32 v76, 0xbfb8aa3b, v76
	v_exp_f32_e32 v76, v76
	v_add_f32_e32 v77, v157, v53
	v_add_f32_e32 v80, v158, v54
	v_add_f32_e32 v81, v159, v55
	v_mul_f32_e32 v77, 0xbfb8aa3b, v77
	v_mul_f32_e32 v80, 0xbfb8aa3b, v80
	v_mul_f32_e32 v83, 0xbfb8aa3b, v81
	v_add_f32_e32 v76, 1.0, v76
	v_exp_f32_e32 v82, v77
	v_exp_f32_e32 v81, v80
	v_rcp_f32_e32 v76, v76
	v_exp_f32_e32 v80, v83
	s_cbranch_vccz .LBB0_650
	v_add_f32_e32 v77, 1.0, v82
	v_rcp_f32_e32 v84, v77
	v_add_f32_e32 v77, 1.0, v81
	v_rcp_f32_e32 v85, v77
	v_add_f32_e32 v77, 1.0, v80
	v_rcp_f32_e32 v77, v77
	s_mov_b64 s[8:9], 0

.LBB0_882:
	s_setprio 3
	s_and_b32 s6, s0, 0x2000
	s_xor_b32 s8, s6, 0x2000
	s_lshl_b32 s101, s8, 1
	s_add_u32 s101, s101, s100
	s_add_u32 m0, s101, 0x0
	s_nop 0
	global_load_lds_dwordx4 v[184:185], off
	s_add_u32 m0, s101, 0x1000
	v_lshl_add_u64 v[184:185], v[184:185], 0, vcc
	global_load_lds_dwordx4 v[186:187], off
	s_add_u32 m0, s101, 0x2000
	v_lshl_add_u64 v[186:187], v[186:187], 0, vcc
	global_load_lds_dwordx4 v[188:189], off
	s_add_u32 m0, s101, 0x3000
	v_lshl_add_u64 v[188:189], v[188:189], 0, vcc
	global_load_lds_dwordx4 v[190:191], off
	s_add_u32 m0, s101, 0x8000
	v_lshl_add_u64 v[190:191], v[190:191], 0, vcc
	global_load_lds_dwordx4 v[192:193], off
	s_add_u32 m0, s101, 0x9000
	v_lshl_add_u64 v[192:193], v[192:193], 0, vcc
	global_load_lds_dwordx4 v[194:195], off
	s_add_u32 m0, s101, 0xa000
	v_lshl_add_u64 v[194:195], v[194:195], 0, vcc
	global_load_lds_dwordx4 v[196:197], off
	s_add_u32 m0, s101, 0xb000
	v_lshl_add_u64 v[196:197], v[196:197], 0, vcc
	global_load_lds_dwordx4 v[198:199], off
	v_lshl_add_u64 v[198:199], v[198:199], 0, vcc
	s_lshl_b32 s6, s6, 1
	v_add_u32_e32 v102, s6, v90
	v_add_u32_e32 v103, s6, v71
	v_add_u32_e32 v128, v102, v96
	v_add_u32_e32 v144, v103, v96
	ds_read_b128 v[98:101], v128
	ds_read_b128 v[120:123], v128 offset:2048
	ds_read_b128 v[124:127], v128 offset:4096
	ds_read_b128 v[128:131], v128 offset:6144
	ds_read_b128 v[132:135], v144 offset:32768
	ds_read_b128 v[136:139], v144 offset:34816
	ds_read_b128 v[140:143], v144 offset:36864
	ds_read_b128 v[144:147], v144 offset:38912
	s_setprio 0
	s_waitcnt lgkmcnt(0)
	v_mfma_f32_16x16x32_bf16 v[60:63], v[132:135], v[98:101], v[60:63]
	v_mfma_f32_16x16x32_bf16 v[56:59], v[136:139], v[98:101], v[56:59]
	v_mfma_f32_16x16x32_bf16 v[52:55], v[140:143], v[98:101], v[52:55]
	v_mfma_f32_16x16x32_bf16 v[48:51], v[144:147], v[98:101], v[48:51]
	v_mfma_f32_16x16x32_bf16 v[44:47], v[132:135], v[120:123], v[44:47]
	v_mfma_f32_16x16x32_bf16 v[40:43], v[136:139], v[120:123], v[40:43]
	v_mfma_f32_16x16x32_bf16 v[36:39], v[140:143], v[120:123], v[36:39]
	v_mfma_f32_16x16x32_bf16 v[32:35], v[144:147], v[120:123], v[32:35]
	v_mfma_f32_16x16x32_bf16 v[28:31], v[132:135], v[124:127], v[28:31]
	v_mfma_f32_16x16x32_bf16 v[24:27], v[136:139], v[124:127], v[24:27]
	v_mfma_f32_16x16x32_bf16 v[20:23], v[140:143], v[124:127], v[20:23]
	v_mfma_f32_16x16x32_bf16 v[16:19], v[144:147], v[124:127], v[16:19]
	v_mfma_f32_16x16x32_bf16 v[12:15], v[132:135], v[128:131], v[12:15]
	v_mfma_f32_16x16x32_bf16 v[8:11], v[136:139], v[128:131], v[8:11]
	v_mfma_f32_16x16x32_bf16 v[4:7], v[140:143], v[128:131], v[4:7]
	v_mfma_f32_16x16x32_bf16 v[0:3], v[144:147], v[128:131], v[0:3]
	s_setprio 2
	v_add_u32_e32 v102, v102, v97
	ds_read_b128 v[98:101], v102
	ds_read_b128 v[120:123], v102 offset:2048
	ds_read_b128 v[124:127], v102 offset:4096
	ds_read_b128 v[128:131], v102 offset:6144
	v_add_u32_e32 v102, v103, v97
	ds_read_b128 v[132:135], v102 offset:32768
	ds_read_b128 v[136:139], v102 offset:34816
	ds_read_b128 v[140:143], v102 offset:36864
	ds_read_b128 v[144:147], v102 offset:38912
	s_setprio 0
	s_waitcnt lgkmcnt(0)
	v_mfma_f32_16x16x32_bf16 v[60:63], v[132:135], v[98:101], v[60:63]
	v_mfma_f32_16x16x32_bf16 v[56:59], v[136:139], v[98:101], v[56:59]
	v_mfma_f32_16x16x32_bf16 v[52:55], v[140:143], v[98:101], v[52:55]
	v_mfma_f32_16x16x32_bf16 v[48:51], v[144:147], v[98:101], v[48:51]
	v_mfma_f32_16x16x32_bf16 v[44:47], v[132:135], v[120:123], v[44:47]
	v_mfma_f32_16x16x32_bf16 v[40:43], v[136:139], v[120:123], v[40:43]
	v_mfma_f32_16x16x32_bf16 v[36:39], v[140:143], v[120:123], v[36:39]
	v_mfma_f32_16x16x32_bf16 v[32:35], v[144:147], v[120:123], v[32:35]
	v_mfma_f32_16x16x32_bf16 v[28:31], v[132:135], v[124:127], v[28:31]
	v_mfma_f32_16x16x32_bf16 v[24:27], v[136:139], v[124:127], v[24:27]
	v_mfma_f32_16x16x32_bf16 v[20:23], v[140:143], v[124:127], v[20:23]
	v_mfma_f32_16x16x32_bf16 v[16:19], v[144:147], v[124:127], v[16:19]
	v_mfma_f32_16x16x32_bf16 v[12:15], v[132:135], v[128:131], v[12:15]
	v_mfma_f32_16x16x32_bf16 v[8:11], v[136:139], v[128:131], v[8:11]
	v_mfma_f32_16x16x32_bf16 v[4:7], v[140:143], v[128:131], v[4:7]
	v_mfma_f32_16x16x32_bf16 v[0:3], v[144:147], v[128:131], v[0:3]
	s_setprio 1
	s_waitcnt vmcnt(0)
	s_add_u32 s36, s36, 0x80
	s_addc_u32 s37, s37, 0
	s_addk_i32 s0, 0x2000
	s_cmpk_lg_i32 s36, 0x780
	s_waitcnt vmcnt(0)
	s_barrier
	s_cbranch_scc1 .LBB0_882
	ds_read_b128 v[86:89], v92 offset:16384
	ds_read_b128 v[98:101], v92 offset:18432
	ds_read_b128 v[120:123], v92 offset:20480
	ds_read_b128 v[124:127], v92 offset:22528
	ds_read_b128 v[128:131], v93 offset:49152
	ds_read_b128 v[132:135], v93 offset:51200
	ds_read_b128 v[136:139], v93 offset:53248
	ds_read_b128 v[140:143], v93 offset:55296
	s_setprio 0
	s_waitcnt lgkmcnt(3)
	v_mfma_f32_16x16x32_bf16 v[60:63], v[128:131], v[86:89], v[60:63]
	s_waitcnt lgkmcnt(2)
	v_mfma_f32_16x16x32_bf16 v[56:59], v[132:135], v[86:89], v[56:59]
	s_waitcnt lgkmcnt(1)
	v_mfma_f32_16x16x32_bf16 v[52:55], v[136:139], v[86:89], v[52:55]
	s_waitcnt lgkmcnt(0)
	v_mfma_f32_16x16x32_bf16 v[48:51], v[140:143], v[86:89], v[48:51]
	v_mfma_f32_16x16x32_bf16 v[40:43], v[132:135], v[98:101], v[40:43]
	v_mfma_f32_16x16x32_bf16 v[36:39], v[136:139], v[98:101], v[36:39]
	v_mfma_f32_16x16x32_bf16 v[32:35], v[140:143], v[98:101], v[32:35]
	v_mfma_f32_16x16x32_bf16 v[20:23], v[136:139], v[120:123], v[20:23]
	v_mfma_f32_16x16x32_bf16 v[16:19], v[140:143], v[120:123], v[16:19]
	v_mfma_f32_16x16x32_bf16 v[0:3], v[140:143], v[124:127], v[0:3]
	v_mfma_f32_16x16x32_bf16 v[86:89], v[128:131], v[98:101], v[44:47]
	v_mfma_f32_16x16x32_bf16 v[98:101], v[128:131], v[120:123], v[28:31]
	v_mfma_f32_16x16x32_bf16 v[144:147], v[132:135], v[120:123], v[24:27]
	v_mfma_f32_16x16x32_bf16 v[120:123], v[128:131], v[124:127], v[12:15]
	v_mfma_f32_16x16x32_bf16 v[128:131], v[132:135], v[124:127], v[8:11]
	v_mfma_f32_16x16x32_bf16 v[132:135], v[136:139], v[124:127], v[4:7]
	s_setprio 1
	s_nop 1
	ds_read_b128 v[4:7], v94 offset:16384
	ds_read_b128 v[8:11], v94 offset:18432
	ds_read_b128 v[124:127], v94 offset:20480
	ds_read_b128 v[136:139], v94 offset:22528
	ds_read_b128 v[140:143], v95 offset:49152
	ds_read_b128 v[148:151], v95 offset:51200
	ds_read_b128 v[152:155], v95 offset:53248
	ds_read_b128 v[156:159], v95 offset:55296
	s_setprio 0
	s_waitcnt lgkmcnt(3)
	v_mfma_f32_16x16x32_bf16 v[60:63], v[140:143], v[4:7], v[60:63]
	s_waitcnt lgkmcnt(2)
	v_mfma_f32_16x16x32_bf16 v[44:47], v[148:151], v[4:7], v[56:59]
	s_waitcnt lgkmcnt(1)
	v_mfma_f32_16x16x32_bf16 v[28:31], v[152:155], v[4:7], v[52:55]
	s_waitcnt lgkmcnt(0)
	v_mfma_f32_16x16x32_bf16 v[12:15], v[156:159], v[4:7], v[48:51]
	v_mfma_f32_16x16x32_bf16 v[56:59], v[140:143], v[8:11], v[86:89]
	v_mfma_f32_16x16x32_bf16 v[40:43], v[148:151], v[8:11], v[40:43]
	v_mfma_f32_16x16x32_bf16 v[24:27], v[152:155], v[8:11], v[36:39]
	v_mfma_f32_16x16x32_bf16 v[8:11], v[156:159], v[8:11], v[32:35]
	v_mfma_f32_16x16x32_bf16 v[52:55], v[140:143], v[124:127], v[98:101]
	v_mfma_f32_16x16x32_bf16 v[36:39], v[148:151], v[124:127], v[144:147]
	v_mfma_f32_16x16x32_bf16 v[20:23], v[152:155], v[124:127], v[20:23]
	v_mfma_f32_16x16x32_bf16 v[4:7], v[156:159], v[124:127], v[16:19]
	v_mfma_f32_16x16x32_bf16 v[48:51], v[140:143], v[136:139], v[120:123]
	v_mfma_f32_16x16x32_bf16 v[32:35], v[148:151], v[136:139], v[128:131]
	v_mfma_f32_16x16x32_bf16 v[16:19], v[152:155], v[136:139], v[132:135]
	v_mfma_f32_16x16x32_bf16 v[0:3], v[156:159], v[136:139], v[0:3]
	s_setprio 1
	s_waitcnt vmcnt(0)
	s_cmpk_gt_i32 s1, 0x7f
	s_barrier
	s_cbranch_scc0 .LBB0_885
	s_add_i32 s0, s24, 0xffffc000
	s_lshr_b32 s0, s0, 8
	v_readlane_b32 s6, v180, 24
	s_add_i32 s6, s0, s6
	s_and_b32 s10, s24, 0x80
	s_lshl_b64 s[8:9], s[6:7], 8
	v_readlane_b32 s36, v182, 19
	s_or_b32 s8, s8, s10
	s_mov_b64 s[10:11], 0
	v_readlane_b32 s37, v182, 20
	s_branch .LBB0_886

.LBB0_895:
	s_setprio 3
	s_and_b32 s0, s10, 0x2000
	s_xor_b32 s1, s0, 0x2000
	s_lshl_b32 s101, s1, 1
	s_add_u32 s101, s101, s100
	s_add_u32 m0, s101, 0x0
	s_nop 0
	global_load_lds_dwordx4 v[184:185], off
	s_add_u32 m0, s101, 0x1000
	v_lshl_add_u64 v[184:185], v[184:185], 0, vcc
	global_load_lds_dwordx4 v[186:187], off
	s_add_u32 m0, s101, 0x2000
	v_lshl_add_u64 v[186:187], v[186:187], 0, vcc
	global_load_lds_dwordx4 v[188:189], off
	s_add_u32 m0, s101, 0x3000
	v_lshl_add_u64 v[188:189], v[188:189], 0, vcc
	global_load_lds_dwordx4 v[190:191], off
	s_add_u32 m0, s101, 0x8000
	v_lshl_add_u64 v[190:191], v[190:191], 0, vcc
	global_load_lds_dwordx4 v[192:193], off
	s_add_u32 m0, s101, 0x9000
	v_lshl_add_u64 v[192:193], v[192:193], 0, vcc
	global_load_lds_dwordx4 v[194:195], off
	s_add_u32 m0, s101, 0xa000
	v_lshl_add_u64 v[194:195], v[194:195], 0, vcc
	global_load_lds_dwordx4 v[196:197], off
	s_add_u32 m0, s101, 0xb000
	v_lshl_add_u64 v[196:197], v[196:197], 0, vcc
	global_load_lds_dwordx4 v[198:199], off
	v_lshl_add_u64 v[198:199], v[198:199], 0, vcc
	s_lshl_b32 s0, s0, 1
	v_add_u32_e32 v68, s0, v120
	v_add_u32_e32 v102, s0, v121
	v_add_u32_e32 v98, v68, v133
	v_add_u32_e32 v103, v102, v133
	ds_read_b128 v[86:89], v98
	ds_read_b128 v[90:93], v98 offset:2048
	ds_read_b128 v[94:97], v98 offset:4096
	ds_read_b128 v[98:101], v98 offset:6144
	ds_read_b128 v[144:147], v103 offset:32768
	ds_read_b128 v[148:151], v103 offset:34816
	ds_read_b128 v[152:155], v103 offset:36864
	ds_read_b128 v[156:159], v103 offset:38912
	s_setprio 0
	s_waitcnt lgkmcnt(0)
	v_mfma_f32_16x16x32_bf16 v[60:63], v[86:89], v[144:147], v[60:63]
	v_mfma_f32_16x16x32_bf16 v[56:59], v[86:89], v[148:151], v[56:59]
	v_mfma_f32_16x16x32_bf16 v[52:55], v[86:89], v[152:155], v[52:55]
	v_mfma_f32_16x16x32_bf16 v[48:51], v[86:89], v[156:159], v[48:51]
	v_mfma_f32_16x16x32_bf16 v[44:47], v[90:93], v[144:147], v[44:47]
	v_mfma_f32_16x16x32_bf16 v[40:43], v[90:93], v[148:151], v[40:43]
	v_mfma_f32_16x16x32_bf16 v[36:39], v[90:93], v[152:155], v[36:39]
	v_mfma_f32_16x16x32_bf16 v[32:35], v[90:93], v[156:159], v[32:35]
	v_mfma_f32_16x16x32_bf16 v[28:31], v[94:97], v[144:147], v[28:31]
	v_mfma_f32_16x16x32_bf16 v[24:27], v[94:97], v[148:151], v[24:27]
	v_mfma_f32_16x16x32_bf16 v[20:23], v[94:97], v[152:155], v[20:23]
	v_mfma_f32_16x16x32_bf16 v[16:19], v[94:97], v[156:159], v[16:19]
	v_mfma_f32_16x16x32_bf16 v[12:15], v[98:101], v[144:147], v[12:15]
	v_mfma_f32_16x16x32_bf16 v[8:11], v[98:101], v[148:151], v[8:11]
	v_mfma_f32_16x16x32_bf16 v[4:7], v[98:101], v[152:155], v[4:7]
	v_mfma_f32_16x16x32_bf16 v[0:3], v[98:101], v[156:159], v[0:3]
	s_setprio 2
	v_add_u32_e32 v68, v68, v134
	ds_read_b128 v[86:89], v68
	ds_read_b128 v[90:93], v68 offset:2048
	ds_read_b128 v[94:97], v68 offset:4096
	ds_read_b128 v[98:101], v68 offset:6144
	v_add_u32_e32 v68, v102, v134
	ds_read_b128 v[144:147], v68 offset:32768
	ds_read_b128 v[148:151], v68 offset:34816
	ds_read_b128 v[152:155], v68 offset:36864
	ds_read_b128 v[156:159], v68 offset:38912
	s_setprio 0
	s_waitcnt lgkmcnt(0)
	v_mfma_f32_16x16x32_bf16 v[60:63], v[86:89], v[144:147], v[60:63]
	v_mfma_f32_16x16x32_bf16 v[56:59], v[86:89], v[148:151], v[56:59]
	v_mfma_f32_16x16x32_bf16 v[52:55], v[86:89], v[152:155], v[52:55]
	v_mfma_f32_16x16x32_bf16 v[48:51], v[86:89], v[156:159], v[48:51]
	v_mfma_f32_16x16x32_bf16 v[44:47], v[90:93], v[144:147], v[44:47]
	v_mfma_f32_16x16x32_bf16 v[40:43], v[90:93], v[148:151], v[40:43]
	v_mfma_f32_16x16x32_bf16 v[36:39], v[90:93], v[152:155], v[36:39]
	v_mfma_f32_16x16x32_bf16 v[32:35], v[90:93], v[156:159], v[32:35]
	v_mfma_f32_16x16x32_bf16 v[28:31], v[94:97], v[144:147], v[28:31]
	v_mfma_f32_16x16x32_bf16 v[24:27], v[94:97], v[148:151], v[24:27]
	v_mfma_f32_16x16x32_bf16 v[20:23], v[94:97], v[152:155], v[20:23]
	v_mfma_f32_16x16x32_bf16 v[16:19], v[94:97], v[156:159], v[16:19]
	v_mfma_f32_16x16x32_bf16 v[12:15], v[98:101], v[144:147], v[12:15]
	v_mfma_f32_16x16x32_bf16 v[8:11], v[98:101], v[148:151], v[8:11]
	v_mfma_f32_16x16x32_bf16 v[4:7], v[98:101], v[152:155], v[4:7]
	v_mfma_f32_16x16x32_bf16 v[0:3], v[98:101], v[156:159], v[0:3]
	s_setprio 1
	s_addk_i32 s10, 0x2000
	s_waitcnt vmcnt(0)
	s_add_u32 s36, s36, 0x80
	s_addc_u32 s37, s37, 0
	s_cmpk_lg_i32 s36, 0x780
	s_waitcnt vmcnt(0)
	s_barrier
	s_cbranch_scc1 .LBB0_895
	ds_read_b128 v[82:85], v122 offset:55296
	ds_read_b128 v[86:89], v122 offset:53248
	ds_read_b128 v[90:93], v122 offset:51200
	ds_read_b128 v[94:97], v122 offset:49152
	ds_read_b128 v[98:101], v123 offset:22528
	ds_read_b128 v[144:147], v123 offset:20480
	ds_read_b128 v[148:151], v123 offset:18432
	ds_read_b128 v[152:155], v123 offset:16384
	s_setprio 0
	s_waitcnt lgkmcnt(0)
	v_mfma_f32_16x16x32_bf16 v[60:63], v[152:155], v[94:97], v[60:63]
	v_mfma_f32_16x16x32_bf16 v[52:55], v[152:155], v[86:89], v[52:55]
	v_mfma_f32_16x16x32_bf16 v[48:51], v[152:155], v[82:85], v[48:51]
	v_mfma_f32_16x16x32_bf16 v[44:47], v[148:151], v[94:97], v[44:47]
	v_mfma_f32_16x16x32_bf16 v[40:43], v[148:151], v[90:93], v[40:43]
	v_mfma_f32_16x16x32_bf16 v[36:39], v[148:151], v[86:89], v[36:39]
	v_mfma_f32_16x16x32_bf16 v[32:35], v[148:151], v[82:85], v[32:35]
	v_mfma_f32_16x16x32_bf16 v[4:7], v[98:101], v[86:89], v[4:7]
	v_mfma_f32_16x16x32_bf16 v[156:159], v[152:155], v[90:93], v[56:59]
	v_mfma_f32_16x16x32_bf16 v[148:151], v[144:147], v[94:97], v[28:31]
	v_mfma_f32_16x16x32_bf16 v[152:155], v[144:147], v[90:93], v[24:27]
	v_mfma_f32_16x16x32_bf16 v[160:163], v[144:147], v[86:89], v[20:23]
	v_mfma_f32_16x16x32_bf16 v[144:147], v[144:147], v[82:85], v[16:19]
	v_mfma_f32_16x16x32_bf16 v[94:97], v[98:101], v[94:97], v[12:15]
	v_mfma_f32_16x16x32_bf16 v[90:93], v[98:101], v[90:93], v[8:11]
	v_mfma_f32_16x16x32_bf16 v[82:85], v[98:101], v[82:85], v[0:3]
	s_setprio 1
	s_nop 1
	ds_read_b128 v[0:3], v124 offset:16384
	ds_read_b128 v[8:11], v124 offset:18432
	ds_read_b128 v[12:15], v124 offset:20480
	ds_read_b128 v[86:89], v124 offset:22528
	ds_read_b128 v[98:101], v125 offset:49152
	ds_read_b128 v[164:167], v125 offset:51200
	ds_read_b128 v[168:171], v125 offset:53248
	ds_read_b128 v[172:175], v125 offset:55296
	s_setprio 0
	s_waitcnt lgkmcnt(3)
	v_mfma_f32_16x16x32_bf16 v[56:59], v[0:3], v[98:101], v[60:63]
	s_waitcnt lgkmcnt(2)
	v_mfma_f32_16x16x32_bf16 v[60:63], v[0:3], v[164:167], v[156:159]
	s_waitcnt lgkmcnt(1)
	v_mfma_f32_16x16x32_bf16 v[24:27], v[0:3], v[168:171], v[52:55]
	s_waitcnt lgkmcnt(0)
	v_mfma_f32_16x16x32_bf16 v[28:31], v[0:3], v[172:175], v[48:51]
	v_mfma_f32_16x16x32_bf16 v[52:55], v[8:11], v[98:101], v[44:47]
	v_mfma_f32_16x16x32_bf16 v[48:51], v[8:11], v[164:167], v[40:43]
	v_mfma_f32_16x16x32_bf16 v[16:19], v[8:11], v[168:171], v[36:39]
	v_mfma_f32_16x16x32_bf16 v[20:23], v[8:11], v[172:175], v[32:35]
	v_mfma_f32_16x16x32_bf16 v[40:43], v[12:15], v[98:101], v[148:151]
	v_mfma_f32_16x16x32_bf16 v[44:47], v[12:15], v[164:167], v[152:155]
	v_mfma_f32_16x16x32_bf16 v[8:11], v[12:15], v[168:171], v[160:163]
	v_mfma_f32_16x16x32_bf16 v[12:15], v[12:15], v[172:175], v[144:147]
	v_mfma_f32_16x16x32_bf16 v[32:35], v[86:89], v[98:101], v[94:97]
	v_mfma_f32_16x16x32_bf16 v[36:39], v[86:89], v[164:167], v[90:93]
	v_mfma_f32_16x16x32_bf16 v[0:3], v[86:89], v[168:171], v[4:7]
	v_mfma_f32_16x16x32_bf16 v[4:7], v[86:89], v[172:175], v[82:85]
	s_setprio 1
	s_waitcnt vmcnt(0)
	s_cmpk_lt_i32 s9, 0x80
	s_cselect_b64 s[42:43], -1, 0
	s_cmpk_gt_i32 s9, 0x7f
	s_mov_b64 s[0:1], -1
	s_barrier
	s_cbranch_scc0 .LBB0_904
	s_and_b32 s10, s20, 0x80
	s_cbranch_execz .LBB0_905

.LBB0_1239:
	s_setprio 3
	s_and_b32 s9, s8, 0x2000
	s_xor_b32 s18, s9, 0x2000
	s_lshl_b32 s101, s18, 1
	s_add_u32 s101, s101, s100
	s_add_u32 m0, s101, 0x0
	s_nop 0
	global_load_lds_dwordx4 v[184:185], off
	s_add_u32 m0, s101, 0x1000
	v_lshl_add_u64 v[184:185], v[184:185], 0, vcc
	global_load_lds_dwordx4 v[186:187], off
	s_add_u32 m0, s101, 0x2000
	v_lshl_add_u64 v[186:187], v[186:187], 0, vcc
	global_load_lds_dwordx4 v[188:189], off
	s_add_u32 m0, s101, 0x3000
	v_lshl_add_u64 v[188:189], v[188:189], 0, vcc
	global_load_lds_dwordx4 v[190:191], off
	s_add_u32 m0, s101, 0x8000
	v_lshl_add_u64 v[190:191], v[190:191], 0, vcc
	global_load_lds_dwordx4 v[192:193], off
	s_add_u32 m0, s101, 0x9000
	v_lshl_add_u64 v[192:193], v[192:193], 0, vcc
	global_load_lds_dwordx4 v[194:195], off
	s_add_u32 m0, s101, 0xa000
	v_lshl_add_u64 v[194:195], v[194:195], 0, vcc
	global_load_lds_dwordx4 v[196:197], off
	s_add_u32 m0, s101, 0xb000
	v_lshl_add_u64 v[196:197], v[196:197], 0, vcc
	global_load_lds_dwordx4 v[198:199], off
	v_lshl_add_u64 v[198:199], v[198:199], 0, vcc
	s_lshl_b32 s9, s9, 1
	v_add_u32_e32 v136, s9, v84
	v_add_u32_e32 v137, s9, v83
	v_add_u32_e32 v100, v136, v86
	v_add_u32_e32 v132, v137, v86
	ds_read_b128 v[88:91], v100
	ds_read_b128 v[92:95], v100 offset:2048
	ds_read_b128 v[96:99], v100 offset:4096
	ds_read_b128 v[100:103], v100 offset:6144
	ds_read_b128 v[120:123], v132 offset:32768
	ds_read_b128 v[124:127], v132 offset:34816
	ds_read_b128 v[128:131], v132 offset:36864
	ds_read_b128 v[132:135], v132 offset:38912
	s_setprio 0
	s_waitcnt lgkmcnt(0)
	v_mfma_f32_16x16x32_bf16 v[60:63], v[120:123], v[88:91], v[60:63]
	v_mfma_f32_16x16x32_bf16 v[56:59], v[124:127], v[88:91], v[56:59]
	v_mfma_f32_16x16x32_bf16 v[52:55], v[128:131], v[88:91], v[52:55]
	v_mfma_f32_16x16x32_bf16 v[48:51], v[132:135], v[88:91], v[48:51]
	v_mfma_f32_16x16x32_bf16 v[44:47], v[120:123], v[92:95], v[44:47]
	v_mfma_f32_16x16x32_bf16 v[40:43], v[124:127], v[92:95], v[40:43]
	v_mfma_f32_16x16x32_bf16 v[36:39], v[128:131], v[92:95], v[36:39]
	v_mfma_f32_16x16x32_bf16 v[32:35], v[132:135], v[92:95], v[32:35]
	v_mfma_f32_16x16x32_bf16 v[28:31], v[120:123], v[96:99], v[28:31]
	v_mfma_f32_16x16x32_bf16 v[24:27], v[124:127], v[96:99], v[24:27]
	v_mfma_f32_16x16x32_bf16 v[20:23], v[128:131], v[96:99], v[20:23]
	v_mfma_f32_16x16x32_bf16 v[16:19], v[132:135], v[96:99], v[16:19]
	v_mfma_f32_16x16x32_bf16 v[12:15], v[120:123], v[100:103], v[12:15]
	v_mfma_f32_16x16x32_bf16 v[8:11], v[124:127], v[100:103], v[8:11]
	v_mfma_f32_16x16x32_bf16 v[4:7], v[128:131], v[100:103], v[4:7]
	v_mfma_f32_16x16x32_bf16 v[0:3], v[132:135], v[100:103], v[0:3]
	s_setprio 2
	v_add_u32_e32 v100, v136, v87
	v_add_u32_e32 v132, v137, v87
	ds_read_b128 v[88:91], v100
	ds_read_b128 v[92:95], v100 offset:2048
	ds_read_b128 v[96:99], v100 offset:4096
	ds_read_b128 v[100:103], v100 offset:6144
	ds_read_b128 v[120:123], v132 offset:32768
	ds_read_b128 v[124:127], v132 offset:34816
	ds_read_b128 v[128:131], v132 offset:36864
	ds_read_b128 v[132:135], v132 offset:38912
	s_setprio 0
	s_waitcnt lgkmcnt(0)
	v_mfma_f32_16x16x32_bf16 v[60:63], v[120:123], v[88:91], v[60:63]
	v_mfma_f32_16x16x32_bf16 v[56:59], v[124:127], v[88:91], v[56:59]
	v_mfma_f32_16x16x32_bf16 v[52:55], v[128:131], v[88:91], v[52:55]
	v_mfma_f32_16x16x32_bf16 v[48:51], v[132:135], v[88:91], v[48:51]
	v_mfma_f32_16x16x32_bf16 v[44:47], v[120:123], v[92:95], v[44:47]
	v_mfma_f32_16x16x32_bf16 v[40:43], v[124:127], v[92:95], v[40:43]
	v_mfma_f32_16x16x32_bf16 v[36:39], v[128:131], v[92:95], v[36:39]
	v_mfma_f32_16x16x32_bf16 v[32:35], v[132:135], v[92:95], v[32:35]
	v_mfma_f32_16x16x32_bf16 v[28:31], v[120:123], v[96:99], v[28:31]
	v_mfma_f32_16x16x32_bf16 v[24:27], v[124:127], v[96:99], v[24:27]
	v_mfma_f32_16x16x32_bf16 v[20:23], v[128:131], v[96:99], v[20:23]
	v_mfma_f32_16x16x32_bf16 v[16:19], v[132:135], v[96:99], v[16:19]
	v_mfma_f32_16x16x32_bf16 v[12:15], v[120:123], v[100:103], v[12:15]
	v_mfma_f32_16x16x32_bf16 v[8:11], v[124:127], v[100:103], v[8:11]
	v_mfma_f32_16x16x32_bf16 v[4:7], v[128:131], v[100:103], v[4:7]
	v_mfma_f32_16x16x32_bf16 v[0:3], v[132:135], v[100:103], v[0:3]
	s_setprio 1
	s_waitcnt vmcnt(0)
	s_add_u32 s20, s20, 0x80
	s_addc_u32 s21, s21, 0
	s_addk_i32 s8, 0x2000
	s_cmp_lg_u32 s1, s20
	s_waitcnt vmcnt(0)
	s_barrier
	s_cbranch_scc1 .LBB0_1239
	s_lshl_b32 s1, s36, 14
	s_addk_i32 s1, 0x4000
	s_and_b32 s1, s1, 0x4000
	v_add_u32_e32 v132, s1, v84
	v_add_u32_e32 v133, s1, v83
	v_add_u32_e32 v96, v132, v86
	v_add_u32_e32 v128, v133, v86
	ds_read_b128 v[78:81], v96
	ds_read_b128 v[88:91], v96 offset:2048
	ds_read_b128 v[92:95], v96 offset:4096
	ds_read_b128 v[96:99], v96 offset:6144
	ds_read_b128 v[100:103], v128 offset:32768
	ds_read_b128 v[120:123], v128 offset:34816
	ds_read_b128 v[124:127], v128 offset:36864
	ds_read_b128 v[128:131], v128 offset:38912
	s_setprio 0
	s_waitcnt lgkmcnt(3)
	v_mfma_f32_16x16x32_bf16 v[60:63], v[100:103], v[78:81], v[60:63]
	s_waitcnt lgkmcnt(2)
	v_mfma_f32_16x16x32_bf16 v[56:59], v[120:123], v[78:81], v[56:59]
	s_waitcnt lgkmcnt(1)
	v_mfma_f32_16x16x32_bf16 v[52:55], v[124:127], v[78:81], v[52:55]
	s_waitcnt lgkmcnt(0)
	v_mfma_f32_16x16x32_bf16 v[48:51], v[128:131], v[78:81], v[48:51]
	v_mfma_f32_16x16x32_bf16 v[44:47], v[100:103], v[88:91], v[44:47]
	v_mfma_f32_16x16x32_bf16 v[40:43], v[120:123], v[88:91], v[40:43]
	v_mfma_f32_16x16x32_bf16 v[36:39], v[124:127], v[88:91], v[36:39]
	v_mfma_f32_16x16x32_bf16 v[32:35], v[128:131], v[88:91], v[32:35]
	v_mfma_f32_16x16x32_bf16 v[28:31], v[100:103], v[92:95], v[28:31]
	v_mfma_f32_16x16x32_bf16 v[24:27], v[120:123], v[92:95], v[24:27]
	v_mfma_f32_16x16x32_bf16 v[20:23], v[124:127], v[92:95], v[20:23]
	v_mfma_f32_16x16x32_bf16 v[16:19], v[128:131], v[92:95], v[16:19]
	v_mfma_f32_16x16x32_bf16 v[12:15], v[100:103], v[96:99], v[12:15]
	v_mfma_f32_16x16x32_bf16 v[8:11], v[120:123], v[96:99], v[8:11]
	v_mfma_f32_16x16x32_bf16 v[4:7], v[124:127], v[96:99], v[4:7]
	v_mfma_f32_16x16x32_bf16 v[0:3], v[128:131], v[96:99], v[0:3]
	s_setprio 1
	v_add_u32_e32 v96, v132, v87
	v_add_u32_e32 v128, v133, v87
	ds_read_b128 v[78:81], v96
	ds_read_b128 v[88:91], v96 offset:2048
	ds_read_b128 v[92:95], v96 offset:4096
	ds_read_b128 v[96:99], v96 offset:6144
	ds_read_b128 v[100:103], v128 offset:32768
	ds_read_b128 v[120:123], v128 offset:34816
	ds_read_b128 v[124:127], v128 offset:36864
	ds_read_b128 v[128:131], v128 offset:38912
	s_setprio 0
	s_waitcnt lgkmcnt(3)
	v_mfma_f32_16x16x32_bf16 v[60:63], v[100:103], v[78:81], v[60:63]
	s_waitcnt lgkmcnt(2)
	v_mfma_f32_16x16x32_bf16 v[56:59], v[120:123], v[78:81], v[56:59]
	s_waitcnt lgkmcnt(1)
	v_mfma_f32_16x16x32_bf16 v[52:55], v[124:127], v[78:81], v[52:55]
	s_waitcnt lgkmcnt(0)
	v_mfma_f32_16x16x32_bf16 v[48:51], v[128:131], v[78:81], v[48:51]
	v_mfma_f32_16x16x32_bf16 v[44:47], v[100:103], v[88:91], v[44:47]
	v_mfma_f32_16x16x32_bf16 v[40:43], v[120:123], v[88:91], v[40:43]
	v_mfma_f32_16x16x32_bf16 v[36:39], v[124:127], v[88:91], v[36:39]
	v_mfma_f32_16x16x32_bf16 v[32:35], v[128:131], v[88:91], v[32:35]
	v_mfma_f32_16x16x32_bf16 v[28:31], v[100:103], v[92:95], v[28:31]
	v_mfma_f32_16x16x32_bf16 v[24:27], v[120:123], v[92:95], v[24:27]
	v_mfma_f32_16x16x32_bf16 v[20:23], v[124:127], v[92:95], v[20:23]
	v_mfma_f32_16x16x32_bf16 v[16:19], v[128:131], v[92:95], v[16:19]
	v_mfma_f32_16x16x32_bf16 v[12:15], v[100:103], v[96:99], v[12:15]
	v_mfma_f32_16x16x32_bf16 v[8:11], v[120:123], v[96:99], v[8:11]
	v_mfma_f32_16x16x32_bf16 v[4:7], v[124:127], v[96:99], v[4:7]
	v_mfma_f32_16x16x32_bf16 v[0:3], v[128:131], v[96:99], v[0:3]
	s_setprio 1
	s_lshl_b32 s1, s25, 3
	s_lshl_b32 s8, s11, 1
	s_or_b32 s1, s8, s1
	s_or_b32 s1, s1, s13
	s_lshl_b32 s1, s1, 4
	s_or_b32 s8, s1, s24
	s_ashr_i32 s9, s8, 31
	s_lshl_b64 s[8:9], s[8:9], 18
	s_add_u32 s8, s52, s8
	v_add_lshl_u32 v78, s10, v71, 8
	s_addc_u32 s9, s53, s9
	v_or_b32_e32 v80, s0, v85
	v_ashrrev_i32_e32 v79, 31, v78
	v_lshl_add_u64 v[78:79], v[78:79], 1, s[8:9]
	v_cvt_pk_bf16_f32 v60, v60, v61
	v_cvt_pk_bf16_f32 v61, v62, v63
	v_lshlrev_b32_e32 v62, 1, v80
	v_mov_b32_e32 v63, v69
	v_lshl_add_u64 v[80:81], v[78:79], 0, v[62:63]
	v_cvt_pk_bf16_f32 v48, v48, v49
	v_cvt_pk_bf16_f32 v49, v50, v51
	s_mov_b64 s[0:1], 0x2000
	s_waitcnt vmcnt(0)
	s_barrier
	global_store_dwordx2 v[80:81], v[48:49], off offset:96
	v_lshl_add_u64 v[48:49], v[78:79], 0, s[0:1]
	v_cvt_pk_bf16_f32 v44, v44, v45
	v_cvt_pk_bf16_f32 v45, v46, v47
	v_lshl_add_u64 v[46:47], v[48:49], 0, v[62:63]
	v_cvt_pk_bf16_f32 v40, v40, v41
	v_cvt_pk_bf16_f32 v41, v42, v43
	v_or_b32_e32 v42, 32, v62
	v_mov_b32_e32 v43, v69
	global_store_dwordx2 v[46:47], v[44:45], off
	v_lshl_add_u64 v[44:45], v[48:49], 0, v[42:43]
	v_cvt_pk_bf16_f32 v36, v36, v37
	v_cvt_pk_bf16_f32 v37, v38, v39
	v_or_b32_e32 v38, 64, v62
	v_mov_b32_e32 v39, v69
	global_store_dwordx2 v[44:45], v[40:41], off
	v_lshl_add_u64 v[40:41], v[48:49], 0, v[38:39]
	v_cvt_pk_bf16_f32 v32, v32, v33
	v_cvt_pk_bf16_f32 v33, v34, v35
	v_or_b32_e32 v34, 0x60, v62
	v_mov_b32_e32 v35, v69
	global_store_dwordx2 v[40:41], v[36:37], off
	v_lshl_add_u64 v[36:37], v[48:49], 0, v[34:35]
	s_mov_b64 s[0:1], 0x4000
	global_store_dwordx2 v[36:37], v[32:33], off
	v_lshl_add_u64 v[32:33], v[78:79], 0, s[0:1]
	v_cvt_pk_bf16_f32 v16, v16, v17
	v_cvt_pk_bf16_f32 v17, v18, v19
	v_lshl_add_u64 v[18:19], v[32:33], 0, v[34:35]
	s_mov_b64 s[0:1], 0x6000
	global_store_dwordx2 v[18:19], v[16:17], off
	v_lshl_add_u64 v[16:17], v[78:79], 0, s[0:1]
	v_readlane_b32 s0, v181, 50
	s_add_i32 s6, s6, s84
	s_add_i32 s12, s12, s0
	v_cvt_pk_bf16_f32 v56, v56, v57
	v_cvt_pk_bf16_f32 v57, v58, v59
	v_cvt_pk_bf16_f32 v52, v52, v53
	v_cvt_pk_bf16_f32 v53, v54, v55
	v_cvt_pk_bf16_f32 v28, v28, v29
	v_cvt_pk_bf16_f32 v29, v30, v31
	v_lshl_add_u64 v[30:31], v[32:33], 0, v[62:63]
	v_cvt_pk_bf16_f32 v24, v24, v25
	v_cvt_pk_bf16_f32 v25, v26, v27
	v_lshl_add_u64 v[26:27], v[32:33], 0, v[42:43]
	v_cvt_pk_bf16_f32 v20, v20, v21
	v_cvt_pk_bf16_f32 v21, v22, v23
	v_lshl_add_u64 v[22:23], v[32:33], 0, v[38:39]
	v_cvt_pk_bf16_f32 v12, v12, v13
	v_cvt_pk_bf16_f32 v13, v14, v15
	v_lshl_add_u64 v[14:15], v[16:17], 0, v[62:63]
	v_cvt_pk_bf16_f32 v8, v8, v9
	v_cvt_pk_bf16_f32 v9, v10, v11
	v_lshl_add_u64 v[10:11], v[16:17], 0, v[42:43]
	v_cvt_pk_bf16_f32 v4, v4, v5
	v_cvt_pk_bf16_f32 v5, v6, v7
	v_lshl_add_u64 v[6:7], v[16:17], 0, v[38:39]
	v_cvt_pk_bf16_f32 v0, v0, v1
	v_cvt_pk_bf16_f32 v1, v2, v3
	v_lshl_add_u64 v[2:3], v[16:17], 0, v[34:35]
	s_cmpk_lt_i32 s6, 0x800
	global_store_dwordx2 v[80:81], v[60:61], off
	global_store_dwordx2 v[80:81], v[56:57], off offset:32
	global_store_dwordx2 v[80:81], v[52:53], off offset:64
	global_store_dwordx2 v[30:31], v[28:29], off
	global_store_dwordx2 v[26:27], v[24:25], off
	global_store_dwordx2 v[22:23], v[20:21], off
	global_store_dwordx2 v[14:15], v[12:13], off
	global_store_dwordx2 v[10:11], v[8:9], off
	global_store_dwordx2 v[6:7], v[4:5], off
	global_store_dwordx2 v[2:3], v[0:1], off
	s_cbranch_scc1 .LBB0_1234
	v_readlane_b32 s50, v180, 0
	s_mov_b32 s18, 0x42ce8ed0
	s_mov_b32 s19, 0xc2b17218
	s_mov_b32 s48, s5
	v_readlane_b32 s51, v180, 1

.LBB0_1295:
	s_lshl_b32 s1, s12, 7
	s_add_i32 s12, s18, s1
	s_and_b32 s0, s13, s11
	s_ashr_i32 s13, s12, 31
	s_and_b32 s11, s10, 3
	s_lshl_b64 s[12:13], s[12:13], 11
	s_add_u32 s12, s2, s12
	s_addc_u32 s13, s3, s13
	s_lshl_b32 s21, s11, 9
	s_add_u32 s12, s12, s21
	s_addc_u32 s13, s13, 0
	s_lshl_b32 s0, s0, 7
	s_add_i32 s18, s18, s0
	s_ashr_i32 s19, s18, 31
	s_lshl_b64 s[18:19], s[18:19], 11
	v_readlane_b32 s22, v181, 42
	v_readlane_b32 s23, v181, 43
	s_add_u32 s18, s22, s18
	s_addc_u32 s19, s23, s19
	s_add_u32 s18, s18, s21
	v_lshl_add_u64 v[0:1], s[12:13], 0, v[72:73]
	v_readfirstlane_b32 s12, v94
	v_add_u32_e32 v4, 0x1000, v94
	s_addc_u32 s19, s19, 0
	v_lshl_add_u64 v[62:63], v[0:1], 0, v[68:69]
	s_mov_b32 m0, s12
	s_mov_b64 s[22:23], 0x10000
	v_readfirstlane_b32 s13, v4
	v_add_u32_e32 v4, 0x2000, v94
	v_lshl_add_u64 v[0:1], s[18:19], 0, v[72:73]
	global_load_lds_dwordx4 v[62:63], off
	v_lshl_add_u64 v[2:3], v[62:63], 0, s[22:23]
	s_mov_b32 m0, s13
	v_readfirstlane_b32 s18, v4
	v_add_u32_e32 v4, 0x3000, v94
	global_load_lds_dwordx4 v[2:3], off
	v_lshl_add_u64 v[2:3], v[62:63], 0, s[28:29]
	s_mov_b32 m0, s18
	s_mov_b64 s[24:25], 0x30000
	v_readfirstlane_b32 s19, v4
	global_load_lds_dwordx4 v[2:3], off
	v_lshl_add_u64 v[2:3], v[62:63], 0, s[24:25]
	s_mov_b32 m0, s19
	v_lshl_add_u64 v[0:1], v[0:1], 0, v[68:69]
	global_load_lds_dwordx4 v[2:3], off
	v_add_u32_e32 v2, 0x8000, v94
	v_add_u32_e32 v4, 0x9000, v94
	v_readfirstlane_b32 s21, v2
	s_mov_b32 m0, s21
	v_lshl_add_u64 v[2:3], v[0:1], 0, s[22:23]
	v_readfirstlane_b32 s22, v4
	v_add_u32_e32 v4, 0xa000, v94
	global_load_lds_dwordx4 v[0:1], off
	s_mov_b32 m0, s22
	v_readfirstlane_b32 s23, v4
	global_load_lds_dwordx4 v[2:3], off
	v_lshl_add_u64 v[2:3], v[0:1], 0, s[28:29]
	s_mov_b32 m0, s23
	v_add_u32_e32 v4, 0xb000, v94
	global_load_lds_dwordx4 v[2:3], off
	v_lshl_add_u64 v[2:3], v[0:1], 0, s[24:25]
	v_readfirstlane_b32 s24, v4
	v_add_u32_e32 v4, 0x4000, v94
	s_mov_b32 m0, s24
	v_readfirstlane_b32 s25, v4
	v_add_u32_e32 v4, 0x5000, v94
	global_load_lds_dwordx4 v[2:3], off
	v_lshl_add_u64 v[2:3], v[62:63], 0, s[92:93]
	s_mov_b32 m0, s25
	v_readfirstlane_b32 s36, v4
	v_add_u32_e32 v4, 0x6000, v94
	s_waitcnt vmcnt(0)
	s_waitcnt vmcnt(0) lgkmcnt(0)
	s_barrier
	global_load_lds_dwordx4 v[2:3], off
	v_lshl_add_u64 v[2:3], v[62:63], 0, s[96:97]
	s_mov_b32 m0, s36
	v_readfirstlane_b32 s37, v4
	v_add_u32_e32 v4, 0x7000, v94
	global_load_lds_dwordx4 v[2:3], off
	v_lshl_add_u64 v[2:3], v[62:63], 0, s[30:31]
	s_mov_b32 m0, s37
	v_readfirstlane_b32 s38, v4
	v_add_u32_e32 v4, 0xc000, v94
	global_load_lds_dwordx4 v[2:3], off
	v_lshl_add_u64 v[2:3], v[62:63], 0, s[14:15]
	s_mov_b32 m0, s38
	v_readfirstlane_b32 s39, v4
	v_add_u32_e32 v4, 0xd000, v94
	global_load_lds_dwordx4 v[2:3], off
	v_lshl_add_u64 v[2:3], v[0:1], 0, s[92:93]
	s_mov_b32 m0, s39
	v_readfirstlane_b32 s40, v4
	v_add_u32_e32 v4, 0xe000, v94
	global_load_lds_dwordx4 v[2:3], off
	v_lshl_add_u64 v[2:3], v[0:1], 0, s[96:97]
	s_mov_b32 m0, s40
	v_readfirstlane_b32 s41, v4
	v_add_u32_e32 v4, 0xf000, v94
	global_load_lds_dwordx4 v[2:3], off
	v_lshl_add_u64 v[2:3], v[0:1], 0, s[30:31]
	s_mov_b32 m0, s41
	v_readfirstlane_b32 s42, v4
	global_load_lds_dwordx4 v[2:3], off
	v_lshl_add_u64 v[2:3], v[0:1], 0, s[14:15]
	s_mov_b32 m0, s42
	s_nop 0
	global_load_lds_dwordx4 v[2:3], off
	ds_read_b128 v[2:5], v90
	ds_read_b128 v[6:9], v90 offset:2048
	ds_read_b128 v[10:13], v90 offset:4096
	ds_read_b128 v[14:17], v90 offset:6144
	ds_read_b128 v[18:21], v91 offset:32768
	ds_read_b128 v[22:25], v91 offset:34816
	ds_read_b128 v[26:29], v91 offset:36864
	ds_read_b128 v[30:33], v91 offset:38912
	s_setprio 0
	s_waitcnt lgkmcnt(0)
	v_mfma_f32_16x16x32_bf16 v[34:37], v[18:21], v[2:5], 0
	v_mfma_f32_16x16x32_bf16 v[38:41], v[22:25], v[2:5], 0
	v_mfma_f32_16x16x32_bf16 v[42:45], v[26:29], v[2:5], 0
	v_mfma_f32_16x16x32_bf16 v[2:5], v[30:33], v[2:5], 0
	v_mfma_f32_16x16x32_bf16 v[46:49], v[18:21], v[6:9], 0
	v_mfma_f32_16x16x32_bf16 v[50:53], v[22:25], v[6:9], 0
	v_mfma_f32_16x16x32_bf16 v[54:57], v[26:29], v[6:9], 0
	v_mfma_f32_16x16x32_bf16 v[6:9], v[30:33], v[6:9], 0
	v_mfma_f32_16x16x32_bf16 v[58:61], v[18:21], v[10:13], 0
	v_mfma_f32_16x16x32_bf16 v[74:77], v[22:25], v[10:13], 0
	v_mfma_f32_16x16x32_bf16 v[78:81], v[26:29], v[10:13], 0
	v_mfma_f32_16x16x32_bf16 v[10:13], v[30:33], v[10:13], 0
	v_mfma_f32_16x16x32_bf16 v[18:21], v[18:21], v[14:17], 0
	v_mfma_f32_16x16x32_bf16 v[22:25], v[22:25], v[14:17], 0
	v_mfma_f32_16x16x32_bf16 v[26:29], v[26:29], v[14:17], 0
	v_mfma_f32_16x16x32_bf16 v[14:17], v[30:33], v[14:17], 0
	s_setprio 1
	ds_read_b128 v[30:33], v92
	ds_read_b128 v[82:85], v92 offset:2048
	ds_read_b128 v[96:99], v92 offset:4096
	ds_read_b128 v[100:103], v92 offset:6144
	ds_read_b128 v[120:123], v93 offset:32768
	ds_read_b128 v[124:127], v93 offset:34816
	ds_read_b128 v[128:131], v93 offset:36864
	ds_read_b128 v[132:135], v93 offset:38912
	s_setprio 0
	s_waitcnt lgkmcnt(0)
	v_mfma_f32_16x16x32_bf16 v[34:37], v[120:123], v[30:33], v[34:37]
	v_mfma_f32_16x16x32_bf16 v[38:41], v[124:127], v[30:33], v[38:41]
	v_mfma_f32_16x16x32_bf16 v[42:45], v[128:131], v[30:33], v[42:45]
	v_mfma_f32_16x16x32_bf16 v[2:5], v[132:135], v[30:33], v[2:5]
	v_mfma_f32_16x16x32_bf16 v[30:33], v[120:123], v[82:85], v[46:49]
	v_mfma_f32_16x16x32_bf16 v[46:49], v[124:127], v[82:85], v[50:53]
	v_mfma_f32_16x16x32_bf16 v[50:53], v[128:131], v[82:85], v[54:57]
	v_mfma_f32_16x16x32_bf16 v[6:9], v[132:135], v[82:85], v[6:9]
	v_mfma_f32_16x16x32_bf16 v[54:57], v[120:123], v[96:99], v[58:61]
	v_mfma_f32_16x16x32_bf16 v[58:61], v[124:127], v[96:99], v[74:77]
	v_mfma_f32_16x16x32_bf16 v[74:77], v[128:131], v[96:99], v[78:81]
	v_mfma_f32_16x16x32_bf16 v[10:13], v[132:135], v[96:99], v[10:13]
	v_mfma_f32_16x16x32_bf16 v[18:21], v[120:123], v[100:103], v[18:21]
	v_mfma_f32_16x16x32_bf16 v[22:25], v[124:127], v[100:103], v[22:25]
	v_mfma_f32_16x16x32_bf16 v[26:29], v[128:131], v[100:103], v[26:29]
	v_mfma_f32_16x16x32_bf16 v[14:17], v[132:135], v[100:103], v[14:17]
	s_setprio 1
	s_mov_b64 s[44:45], 0x100
	s_mov_b32 m0, s12
	v_lshl_add_u64 v[78:79], v[62:63], 0, s[44:45]
	s_mov_b64 s[46:47], 0x10100
	s_waitcnt vmcnt(0)
	s_waitcnt vmcnt(0)
	s_barrier
	global_load_lds_dwordx4 v[78:79], off
	v_lshl_add_u64 v[78:79], v[62:63], 0, s[46:47]
	s_mov_b32 m0, s13
	s_mov_b64 s[12:13], 0x20100
	global_load_lds_dwordx4 v[78:79], off
	v_lshl_add_u64 v[78:79], v[62:63], 0, s[12:13]
	s_mov_b32 m0, s18
	s_mov_b64 s[48:49], 0x30100
	global_load_lds_dwordx4 v[78:79], off
	v_lshl_add_u64 v[78:79], v[62:63], 0, s[48:49]
	s_mov_b32 m0, s19
	s_nop 0
	global_load_lds_dwordx4 v[78:79], off
	v_lshl_add_u64 v[78:79], v[0:1], 0, s[44:45]
	s_mov_b32 m0, s21
	s_nop 0
	global_load_lds_dwordx4 v[78:79], off
	v_lshl_add_u64 v[78:79], v[0:1], 0, s[46:47]
	s_mov_b32 m0, s22
	s_nop 0
	global_load_lds_dwordx4 v[78:79], off
	v_lshl_add_u64 v[78:79], v[0:1], 0, s[12:13]
	s_mov_b32 m0, s23
	s_nop 0
	global_load_lds_dwordx4 v[78:79], off
	v_lshl_add_u64 v[78:79], v[0:1], 0, s[48:49]
	s_mov_b32 m0, s24
	s_nop 0
	global_load_lds_dwordx4 v[78:79], off
	ds_read_b128 v[78:81], v90 offset:16384
	ds_read_b128 v[82:85], v90 offset:18432
	ds_read_b128 v[96:99], v90 offset:20480
	ds_read_b128 v[100:103], v90 offset:22528
	ds_read_b128 v[120:123], v91 offset:49152
	ds_read_b128 v[124:127], v91 offset:51200
	ds_read_b128 v[128:131], v91 offset:53248
	ds_read_b128 v[132:135], v91 offset:55296
	s_setprio 0
	s_waitcnt lgkmcnt(0)
	v_mfma_f32_16x16x32_bf16 v[34:37], v[120:123], v[78:81], v[34:37]
	v_mfma_f32_16x16x32_bf16 v[38:41], v[124:127], v[78:81], v[38:41]
	v_mfma_f32_16x16x32_bf16 v[42:45], v[128:131], v[78:81], v[42:45]
	v_mfma_f32_16x16x32_bf16 v[2:5], v[132:135], v[78:81], v[2:5]
	v_mfma_f32_16x16x32_bf16 v[30:33], v[120:123], v[82:85], v[30:33]
	v_mfma_f32_16x16x32_bf16 v[46:49], v[124:127], v[82:85], v[46:49]
	v_mfma_f32_16x16x32_bf16 v[50:53], v[128:131], v[82:85], v[50:53]
	v_mfma_f32_16x16x32_bf16 v[6:9], v[132:135], v[82:85], v[6:9]
	v_mfma_f32_16x16x32_bf16 v[54:57], v[120:123], v[96:99], v[54:57]
	v_mfma_f32_16x16x32_bf16 v[58:61], v[124:127], v[96:99], v[58:61]
	v_mfma_f32_16x16x32_bf16 v[74:77], v[128:131], v[96:99], v[74:77]
	v_mfma_f32_16x16x32_bf16 v[10:13], v[132:135], v[96:99], v[10:13]
	v_mfma_f32_16x16x32_bf16 v[18:21], v[120:123], v[100:103], v[18:21]
	v_mfma_f32_16x16x32_bf16 v[22:25], v[124:127], v[100:103], v[22:25]
	v_mfma_f32_16x16x32_bf16 v[26:29], v[128:131], v[100:103], v[26:29]
	v_mfma_f32_16x16x32_bf16 v[14:17], v[132:135], v[100:103], v[14:17]
	s_setprio 1
	ds_read_b128 v[78:81], v92 offset:16384
	ds_read_b128 v[82:85], v92 offset:18432
	ds_read_b128 v[96:99], v92 offset:20480
	ds_read_b128 v[100:103], v92 offset:22528
	ds_read_b128 v[120:123], v93 offset:49152
	ds_read_b128 v[124:127], v93 offset:51200
	ds_read_b128 v[128:131], v93 offset:53248
	ds_read_b128 v[132:135], v93 offset:55296
	s_setprio 0
	s_waitcnt lgkmcnt(0)
	v_mfma_f32_16x16x32_bf16 v[34:37], v[120:123], v[78:81], v[34:37]
	v_mfma_f32_16x16x32_bf16 v[38:41], v[124:127], v[78:81], v[38:41]
	v_mfma_f32_16x16x32_bf16 v[42:45], v[128:131], v[78:81], v[42:45]
	v_mfma_f32_16x16x32_bf16 v[2:5], v[132:135], v[78:81], v[2:5]
	v_mfma_f32_16x16x32_bf16 v[30:33], v[120:123], v[82:85], v[30:33]
	v_mfma_f32_16x16x32_bf16 v[46:49], v[124:127], v[82:85], v[46:49]
	v_mfma_f32_16x16x32_bf16 v[50:53], v[128:131], v[82:85], v[50:53]
	v_mfma_f32_16x16x32_bf16 v[6:9], v[132:135], v[82:85], v[6:9]
	v_mfma_f32_16x16x32_bf16 v[54:57], v[120:123], v[96:99], v[54:57]
	v_mfma_f32_16x16x32_bf16 v[58:61], v[124:127], v[96:99], v[58:61]
	v_mfma_f32_16x16x32_bf16 v[74:77], v[128:131], v[96:99], v[74:77]
	v_mfma_f32_16x16x32_bf16 v[10:13], v[132:135], v[96:99], v[10:13]
	v_mfma_f32_16x16x32_bf16 v[18:21], v[120:123], v[100:103], v[18:21]
	v_mfma_f32_16x16x32_bf16 v[22:25], v[124:127], v[100:103], v[22:25]
	v_mfma_f32_16x16x32_bf16 v[26:29], v[128:131], v[100:103], v[26:29]
	v_mfma_f32_16x16x32_bf16 v[14:17], v[132:135], v[100:103], v[14:17]
	s_setprio 1
	s_mov_b64 s[12:13], 0x180
	s_mov_b32 m0, s25
	v_lshl_add_u64 v[78:79], v[62:63], 0, s[12:13]
	s_mov_b64 s[18:19], 0x10180
	s_waitcnt vmcnt(0)
	s_waitcnt vmcnt(0)
	s_barrier
	global_load_lds_dwordx4 v[78:79], off
	v_lshl_add_u64 v[78:79], v[62:63], 0, s[18:19]
	s_mov_b32 m0, s36
	s_mov_b64 s[22:23], 0x20180
	global_load_lds_dwordx4 v[78:79], off
	v_lshl_add_u64 v[78:79], v[62:63], 0, s[22:23]
	s_mov_b32 m0, s37
	s_mov_b64 s[24:25], 0x30180
	global_load_lds_dwordx4 v[78:79], off
	v_lshl_add_u64 v[62:63], v[62:63], 0, s[24:25]
	s_mov_b32 m0, s38
	s_nop 0
	global_load_lds_dwordx4 v[62:63], off
	v_lshl_add_u64 v[62:63], v[0:1], 0, s[12:13]
	s_mov_b32 m0, s39
	s_nop 0
	global_load_lds_dwordx4 v[62:63], off
	v_lshl_add_u64 v[62:63], v[0:1], 0, s[18:19]
	s_mov_b32 m0, s40
	s_nop 0
	global_load_lds_dwordx4 v[62:63], off
	v_lshl_add_u64 v[62:63], v[0:1], 0, s[22:23]
	s_mov_b32 m0, s41
	v_lshl_add_u64 v[0:1], v[0:1], 0, s[24:25]
	global_load_lds_dwordx4 v[62:63], off
	s_mov_b32 m0, s42
	s_nop 0
	global_load_lds_dwordx4 v[0:1], off
	ds_read_b128 v[78:81], v90
	ds_read_b128 v[82:85], v90 offset:2048
	ds_read_b128 v[96:99], v90 offset:4096
	ds_read_b128 v[100:103], v90 offset:6144
	ds_read_b128 v[120:123], v91 offset:32768
	ds_read_b128 v[124:127], v91 offset:34816
	ds_read_b128 v[128:131], v91 offset:36864
	ds_read_b128 v[132:135], v91 offset:38912
	s_setprio 0
	s_waitcnt lgkmcnt(0)
	v_mfma_f32_16x16x32_bf16 v[34:37], v[120:123], v[78:81], v[34:37]
	v_mfma_f32_16x16x32_bf16 v[38:41], v[124:127], v[78:81], v[38:41]
	v_mfma_f32_16x16x32_bf16 v[42:45], v[128:131], v[78:81], v[42:45]
	v_mfma_f32_16x16x32_bf16 v[0:3], v[132:135], v[78:81], v[2:5]
	v_mfma_f32_16x16x32_bf16 v[30:33], v[120:123], v[82:85], v[30:33]
	v_mfma_f32_16x16x32_bf16 v[46:49], v[124:127], v[82:85], v[46:49]
	v_mfma_f32_16x16x32_bf16 v[50:53], v[128:131], v[82:85], v[50:53]
	v_mfma_f32_16x16x32_bf16 v[4:7], v[132:135], v[82:85], v[6:9]
	v_mfma_f32_16x16x32_bf16 v[54:57], v[120:123], v[96:99], v[54:57]
	v_mfma_f32_16x16x32_bf16 v[58:61], v[124:127], v[96:99], v[58:61]
	v_mfma_f32_16x16x32_bf16 v[74:77], v[128:131], v[96:99], v[74:77]
	v_mfma_f32_16x16x32_bf16 v[8:11], v[132:135], v[96:99], v[10:13]
	v_mfma_f32_16x16x32_bf16 v[18:21], v[120:123], v[100:103], v[18:21]
	v_mfma_f32_16x16x32_bf16 v[22:25], v[124:127], v[100:103], v[22:25]
	v_mfma_f32_16x16x32_bf16 v[26:29], v[128:131], v[100:103], v[26:29]
	v_mfma_f32_16x16x32_bf16 v[12:15], v[132:135], v[100:103], v[14:17]
	s_setprio 1
	ds_read_b128 v[78:81], v92
	ds_read_b128 v[82:85], v92 offset:2048
	ds_read_b128 v[96:99], v92 offset:4096
	ds_read_b128 v[100:103], v92 offset:6144
	ds_read_b128 v[120:123], v93 offset:32768
	ds_read_b128 v[124:127], v93 offset:34816
	ds_read_b128 v[128:131], v93 offset:36864
	ds_read_b128 v[132:135], v93 offset:38912
	s_setprio 0
	s_waitcnt lgkmcnt(0)
	v_mfma_f32_16x16x32_bf16 v[34:37], v[120:123], v[78:81], v[34:37]
	v_mfma_f32_16x16x32_bf16 v[38:41], v[124:127], v[78:81], v[38:41]
	v_mfma_f32_16x16x32_bf16 v[42:45], v[128:131], v[78:81], v[42:45]
	v_mfma_f32_16x16x32_bf16 v[0:3], v[132:135], v[78:81], v[0:3]
	v_mfma_f32_16x16x32_bf16 v[30:33], v[120:123], v[82:85], v[30:33]
	v_mfma_f32_16x16x32_bf16 v[46:49], v[124:127], v[82:85], v[46:49]
	v_mfma_f32_16x16x32_bf16 v[50:53], v[128:131], v[82:85], v[50:53]
	v_mfma_f32_16x16x32_bf16 v[4:7], v[132:135], v[82:85], v[4:7]
	v_mfma_f32_16x16x32_bf16 v[54:57], v[120:123], v[96:99], v[54:57]
	v_mfma_f32_16x16x32_bf16 v[58:61], v[124:127], v[96:99], v[58:61]
	v_mfma_f32_16x16x32_bf16 v[74:77], v[128:131], v[96:99], v[74:77]
	v_mfma_f32_16x16x32_bf16 v[8:11], v[132:135], v[96:99], v[8:11]
	v_mfma_f32_16x16x32_bf16 v[16:19], v[120:123], v[100:103], v[18:21]
	v_mfma_f32_16x16x32_bf16 v[20:23], v[124:127], v[100:103], v[22:25]
	v_mfma_f32_16x16x32_bf16 v[24:27], v[128:131], v[100:103], v[26:29]
	v_mfma_f32_16x16x32_bf16 v[12:15], v[132:135], v[100:103], v[12:15]
	s_setprio 1
	s_waitcnt vmcnt(0)
	s_waitcnt vmcnt(0)
	s_barrier
	ds_read_b128 v[78:81], v91 offset:55296
	ds_read_b128 v[82:85], v91 offset:53248
	ds_read_b128 v[96:99], v91 offset:51200
	ds_read_b128 v[100:103], v91 offset:49152
	ds_read_b128 v[120:123], v90 offset:22528
	ds_read_b128 v[124:127], v90 offset:20480
	ds_read_b128 v[128:131], v90 offset:18432
	ds_read_b128 v[132:135], v90 offset:16384
	s_setprio 0
	s_waitcnt lgkmcnt(0)
	v_mfma_f32_16x16x32_bf16 v[34:37], v[100:103], v[132:135], v[34:37]
	v_mfma_f32_16x16x32_bf16 v[136:139], v[96:99], v[132:135], v[38:41]
	v_mfma_f32_16x16x32_bf16 v[40:43], v[82:85], v[132:135], v[42:45]
	v_mfma_f32_16x16x32_bf16 v[0:3], v[78:81], v[132:135], v[0:3]
	v_mfma_f32_16x16x32_bf16 v[28:31], v[100:103], v[128:131], v[30:33]
	v_mfma_f32_16x16x32_bf16 v[132:135], v[96:99], v[128:131], v[46:49]
	v_mfma_f32_16x16x32_bf16 v[140:143], v[82:85], v[128:131], v[50:53]
	v_mfma_f32_16x16x32_bf16 v[4:7], v[78:81], v[128:131], v[4:7]
	v_mfma_f32_16x16x32_bf16 v[52:55], v[100:103], v[124:127], v[54:57]
	v_mfma_f32_16x16x32_bf16 v[128:131], v[96:99], v[124:127], v[58:61]
	v_mfma_f32_16x16x32_bf16 v[74:77], v[82:85], v[124:127], v[74:77]
	v_mfma_f32_16x16x32_bf16 v[124:127], v[78:81], v[124:127], v[8:11]
	v_mfma_f32_16x16x32_bf16 v[100:103], v[100:103], v[120:123], v[16:19]
	v_mfma_f32_16x16x32_bf16 v[96:99], v[96:99], v[120:123], v[20:23]
	v_mfma_f32_16x16x32_bf16 v[82:85], v[82:85], v[120:123], v[24:27]
	v_mfma_f32_16x16x32_bf16 v[78:81], v[78:81], v[120:123], v[12:15]
	s_setprio 1
	ds_read_b128 v[8:11], v92 offset:16384
	s_nop 0
	ds_read_b128 v[12:15], v92 offset:18432
	ds_read_b128 v[120:123], v92 offset:20480
	ds_read_b128 v[144:147], v92 offset:22528
	ds_read_b128 v[148:151], v93 offset:49152
	ds_read_b128 v[152:155], v93 offset:51200
	ds_read_b128 v[156:159], v93 offset:53248
	ds_read_b128 v[160:163], v93 offset:55296
	s_setprio 0
	s_waitcnt lgkmcnt(3)
	v_mfma_f32_16x16x32_bf16 v[36:39], v[148:151], v[8:11], v[34:37]
	s_waitcnt lgkmcnt(2)
	v_mfma_f32_16x16x32_bf16 v[44:47], v[152:155], v[8:11], v[136:139]
	s_waitcnt lgkmcnt(1)
	v_mfma_f32_16x16x32_bf16 v[48:51], v[156:159], v[8:11], v[40:43]
	s_waitcnt lgkmcnt(0)
	v_mfma_f32_16x16x32_bf16 v[32:35], v[160:163], v[8:11], v[0:3]
	v_mfma_f32_16x16x32_bf16 v[60:63], v[148:151], v[12:15], v[28:31]
	v_mfma_f32_16x16x32_bf16 v[24:27], v[152:155], v[12:15], v[132:135]
	v_mfma_f32_16x16x32_bf16 v[20:23], v[156:159], v[12:15], v[140:143]
	v_mfma_f32_16x16x32_bf16 v[16:19], v[160:163], v[12:15], v[4:7]
	v_mfma_f32_16x16x32_bf16 v[56:59], v[148:151], v[120:123], v[52:55]
	v_mfma_f32_16x16x32_bf16 v[12:15], v[152:155], v[120:123], v[128:131]
	v_mfma_f32_16x16x32_bf16 v[8:11], v[156:159], v[120:123], v[74:77]
	v_mfma_f32_16x16x32_bf16 v[28:31], v[160:163], v[120:123], v[124:127]
	v_mfma_f32_16x16x32_bf16 v[52:55], v[148:151], v[144:147], v[100:103]
	v_mfma_f32_16x16x32_bf16 v[40:43], v[152:155], v[144:147], v[96:99]
	v_mfma_f32_16x16x32_bf16 v[4:7], v[156:159], v[144:147], v[82:85]
	v_mfma_f32_16x16x32_bf16 v[0:3], v[160:163], v[144:147], v[78:81]
	s_setprio 1
	s_or_b32 s11, s11, s5
	s_lshl_b32 s11, s11, 2
	v_mov_b32_e32 v71, s11
	s_waitcnt vmcnt(0)
	s_barrier
	global_load_dword v74, v71, s[58:59]
	s_nop 0
	global_load_dword v71, v71, s[58:59] offset:16
	s_mov_b32 s11, 0xbfb8aa3b
	s_mov_b32 s12, 0x33800000
	v_or_b32_e32 v124, s0, v89
	v_add_u32_e32 v103, s1, v88
	v_or_b32_e32 v122, 2, v124
	v_or_b32_e32 v123, 1, v124
	s_waitcnt vmcnt(1)
	v_mul_f32_e32 v75, 0xbfb8aa3b, v74
	s_waitcnt vmcnt(0)
	v_mul_f32_e32 v76, 0xbfb8aa3b, v71
	v_fma_f32 v77, v74, s11, -v75
	v_rndne_f32_e32 v78, v75
	v_fma_f32 v79, v71, s11, -v76
	v_rndne_f32_e32 v80, v76
	v_fmac_f32_e32 v77, 0xb2a5705f, v74
	v_sub_f32_e32 v75, v75, v78
	v_fmac_f32_e32 v79, 0xb2a5705f, v71
	v_sub_f32_e32 v76, v76, v80
	v_add_f32_e32 v75, v75, v77
	v_cvt_i32_f32_e32 v78, v78
	v_add_f32_e32 v76, v76, v79
	v_exp_f32_e32 v75, v75
	v_cvt_i32_f32_e32 v80, v80
	v_exp_f32_e32 v76, v76
	s_mov_b32 s11, 0x42ce8ed0
	v_ldexp_f32 v75, v75, v78
	v_cmp_nlt_f32_e32 vcc, s11, v74
	v_ldexp_f32 v76, v76, v80
	s_nop 0
	v_cndmask_b32_e32 v75, 0, v75, vcc
	v_cmp_nlt_f32_e32 vcc, s11, v71
	s_mov_b32 s11, 0xc2b17218
	s_nop 0
	v_cndmask_b32_e32 v76, 0, v76, vcc
	v_cmp_ngt_f32_e32 vcc, s11, v74
	s_nop 1
	v_cndmask_b32_e32 v75, v112, v75, vcc
	v_cmp_ngt_f32_e32 vcc, s11, v71
	v_add_f32_e32 v71, 1.0, v75
	v_frexp_mant_f32_e32 v82, v71
	v_cndmask_b32_e32 v74, v112, v76, vcc
	v_cvt_f64_f32_e32 v[76:77], v71
	s_mov_b32 s11, 0x3f2aaaab
	v_add_f32_e32 v80, 1.0, v74
	v_add_f32_e32 v81, -1.0, v71
	v_frexp_exp_i32_f64_e32 v76, v[76:77]
	v_cmp_gt_f32_e32 vcc, s11, v82
	v_add_f32_e32 v83, -1.0, v80
	v_frexp_mant_f32_e32 v84, v80
	v_cvt_f64_f32_e32 v[78:79], v80
	v_sub_f32_e32 v85, v81, v71
	v_subbrev_co_u32_e32 v76, vcc, 0, v76, vcc
	v_sub_f32_e32 v81, v75, v81
	v_sub_f32_e32 v77, v83, v80
	v_frexp_exp_i32_f64_e32 v78, v[78:79]
	v_add_f32_e32 v79, 1.0, v85
	v_cmp_gt_f32_e32 vcc, s11, v84
	v_sub_f32_e32 v83, v74, v83
	v_add_f32_e32 v77, 1.0, v77
	v_subbrev_co_u32_e32 v100, vcc, 0, v78, vcc
	v_add_f32_e32 v78, v81, v79
	v_sub_u32_e32 v79, 0, v76
	v_add_f32_e32 v77, v83, v77
	v_sub_u32_e32 v81, 0, v100
	v_ldexp_f32 v71, v71, v79
	v_ldexp_f32 v101, v80, v81
	v_ldexp_f32 v102, v77, v81
	v_add_f32_e32 v77, -1.0, v71
	v_add_f32_e32 v80, 1.0, v71
	v_ldexp_f32 v78, v78, v79
	v_add_f32_e32 v79, 1.0, v77
	v_add_f32_e32 v81, -1.0, v80
	v_sub_f32_e32 v79, v71, v79
	v_sub_f32_e32 v71, v71, v81
	v_add_f32_e32 v71, v78, v71
	v_add_f32_e32 v84, v80, v71
	v_rcp_f32_e32 v85, v84
	v_add_f32_e32 v81, v78, v79
	v_add_f32_e32 v79, v77, v81
	v_sub_f32_e32 v78, v80, v84
	v_mul_f32_e32 v86, v79, v85
	v_mul_f32_e32 v80, v84, v86
	v_add_f32_e32 v71, v71, v78
	v_fma_f32 v82, v86, v84, -v80
	v_fmac_f32_e32 v82, v86, v71
	v_sub_f32_e32 v77, v77, v79
	v_add_f32_e32 v78, v80, v82
	v_add_f32_e32 v77, v81, v77
	v_sub_f32_e32 v81, v79, v78
	v_mov_b32_e32 v83, v78
	v_pk_add_f32 v[78:79], v[78:79], v[80:81] neg_lo:[0,1] neg_hi:[0,1]
	v_cvt_f32_i32_e32 v76, v76
	v_pk_add_f32 v[78:79], v[78:79], v[82:83] neg_lo:[0,1] neg_hi:[0,1]
	s_mov_b32 s11, 0x3f317218
	v_add_f32_e32 v77, v77, v79
	v_add_f32_e32 v77, v78, v77
	v_add_f32_e32 v79, v81, v77
	v_mul_f32_e32 v78, v85, v79
	v_mul_f32_e32 v80, v84, v78
	v_sub_f32_e32 v81, v81, v79
	v_add_f32_e32 v87, v86, v78
	v_fma_f32 v82, v78, v84, -v80
	v_add_f32_e32 v77, v77, v81
	v_sub_f32_e32 v81, v87, v86
	v_fmac_f32_e32 v82, v78, v71
	v_sub_f32_e32 v71, v78, v81
	v_add_f32_e32 v78, v80, v82
	v_sub_f32_e32 v81, v79, v78
	v_mov_b32_e32 v83, v78
	v_pk_add_f32 v[78:79], v[78:79], v[80:81] neg_lo:[0,1] neg_hi:[0,1]
	v_cmp_neq_f32_e32 vcc, s4, v75
	v_pk_add_f32 v[78:79], v[78:79], v[82:83] neg_lo:[0,1] neg_hi:[0,1]
	s_nop 0
	v_add_f32_e32 v77, v77, v79
	v_add_f32_e32 v77, v78, v77
	v_add_f32_e32 v77, v81, v77
	v_mul_f32_e32 v77, v85, v77
	v_add_f32_e32 v71, v71, v77
	v_add_f32_e32 v77, v87, v71
	v_mul_f32_e32 v78, v77, v77
	v_sub_f32_e32 v80, v77, v87
	v_fmamk_f32 v81, v78, 0x3e9b6dac, v109
	v_ldexp_f32 v79, v77, 1
	v_sub_f32_e32 v80, v71, v80
	v_mul_f32_e32 v77, v77, v78
	v_fmaak_f32 v71, v78, v81, 0x3f2aaada
	v_ldexp_f32 v83, v80, 1
	v_pk_mul_f32 v[80:81], v[76:77], v[70:71]
	s_nop 0
	v_fma_f32 v78, v76, s11, -v80
	v_fmac_f32_e32 v78, 0xb102e308, v76
	v_pk_add_f32 v[76:77], v[80:81], v[78:79]
	v_mov_b32_e32 v82, v80
	v_sub_f32_e32 v71, v77, v79
	v_sub_f32_e32 v71, v81, v71
	v_add_f32_e32 v83, v83, v71
	v_pk_add_f32 v[84:85], v[76:77], v[80:81] neg_lo:[0,1] neg_hi:[0,1]
	v_pk_add_f32 v[96:97], v[76:77], v[82:83]
	v_mov_b32_e32 v79, v76
	v_mov_b32_e32 v85, v97
	v_pk_add_f32 v[98:99], v[78:79], v[84:85] neg_lo:[0,1] neg_hi:[0,1]
	v_pk_add_f32 v[78:79], v[78:79], v[84:85]
	v_mov_b32_e32 v80, v77
	v_mov_b32_e32 v87, v76
	v_pk_add_f32 v[76:77], v[78:79], v[76:77] op_sel:[1,0] op_sel_hi:[0,1] neg_lo:[0,1] neg_hi:[0,1]
	v_mov_b32_e32 v86, v83
	v_mov_b32_e32 v82, v97
	v_mov_b32_e32 v83, v79
	v_mov_b32_e32 v81, v76
	v_pk_add_f32 v[84:85], v[96:97], v[76:77] op_sel_hi:[1,0] neg_lo:[0,1] neg_hi:[0,1]
	v_pk_add_f32 v[76:77], v[82:83], v[80:81] neg_lo:[0,1] neg_hi:[0,1]
	v_mov_b32_e32 v84, v98
	v_pk_add_f32 v[76:77], v[86:87], v[76:77] neg_lo:[0,1] neg_hi:[0,1]
	v_mov_b32_e32 v99, v79
	v_pk_add_f32 v[80:81], v[84:85], v[76:77]
	s_nop 0
	v_pk_add_f32 v[82:83], v[80:81], v[80:81] op_sel:[0,1] op_sel_hi:[1,0]
	s_nop 0
	v_pk_add_f32 v[78:79], v[78:79], v[82:83] op_sel:[1,0] op_sel_hi:[0,1]
	v_mov_b32_e32 v81, v78
	v_mov_b32_e32 v77, v82
	v_pk_add_f32 v[82:83], v[80:81], v[98:99] neg_lo:[0,1] neg_hi:[0,1]
	s_nop 0
	v_sub_f32_e32 v71, v80, v82
	v_pk_add_f32 v[76:77], v[76:77], v[82:83] neg_lo:[0,1] neg_hi:[0,1]
	v_sub_f32_e32 v71, v98, v71
	v_add_f32_e32 v71, v76, v71
	v_add_f32_e32 v71, v71, v77
	v_add_f32_e32 v71, v78, v71
	v_add_f32_e32 v76, 1.0, v101
	v_cndmask_b32_e32 v71, v112, v71, vcc
	v_cmp_lt_f32_e64 vcc, |v75|, s12
	v_add_f32_e32 v77, -1.0, v76
	v_sub_f32_e32 v77, v101, v77
	v_cndmask_b32_e32 v71, v71, v75, vcc
	v_mul_f32_e32 v95, 0xbfb8aa3b, v71
	v_add_f32_e32 v71, -1.0, v101
	v_add_f32_e32 v77, v102, v77
	v_add_f32_e32 v75, 1.0, v71
	v_add_f32_e32 v84, v76, v77
	v_sub_f32_e32 v75, v101, v75
	v_rcp_f32_e32 v86, v84
	v_add_f32_e32 v75, v102, v75
	v_sub_f32_e32 v76, v76, v84
	v_add_f32_e32 v85, v77, v76
	v_add_f32_e32 v77, v71, v75
	v_sub_f32_e32 v71, v71, v77
	v_add_f32_e32 v71, v75, v71
	v_mul_f32_e32 v75, v77, v86
	v_mul_f32_e32 v78, v84, v75
	v_fma_f32 v80, v75, v84, -v78
	v_fmac_f32_e32 v80, v75, v85
	v_add_f32_e32 v76, v78, v80
	v_sub_f32_e32 v79, v77, v76
	v_pk_add_f32 v[82:83], v[76:77], v[78:79] neg_lo:[0,1] neg_hi:[0,1]
	v_mov_b32_e32 v81, v76
	v_pk_add_f32 v[76:77], v[82:83], v[80:81] neg_lo:[0,1] neg_hi:[0,1]
	v_cmp_neq_f32_e32 vcc, s4, v74
	v_add_f32_e32 v71, v71, v77
	v_add_f32_e32 v71, v76, v71
	v_add_f32_e32 v77, v79, v71
	v_mul_f32_e32 v87, v86, v77
	v_mul_f32_e32 v78, v84, v87
	v_fma_f32 v80, v87, v84, -v78
	v_fmac_f32_e32 v80, v87, v85
	v_sub_f32_e32 v76, v79, v77
	v_add_f32_e32 v71, v71, v76
	v_add_f32_e32 v76, v78, v80
	v_sub_f32_e32 v79, v77, v76
	v_pk_add_f32 v[82:83], v[76:77], v[78:79] neg_lo:[0,1] neg_hi:[0,1]
	v_mov_b32_e32 v81, v76
	v_pk_add_f32 v[76:77], v[82:83], v[80:81] neg_lo:[0,1] neg_hi:[0,1]
	s_nop 0
	v_add_f32_e32 v71, v71, v77
	v_add_f32_e32 v71, v76, v71
	v_add_f32_e32 v77, v75, v87
	v_add_f32_e32 v71, v79, v71
	v_sub_f32_e32 v75, v77, v75
	v_mul_f32_e32 v71, v86, v71
	v_sub_f32_e32 v75, v87, v75
	v_add_f32_e32 v75, v75, v71
	v_add_f32_e32 v78, v77, v75
	v_cvt_f32_i32_e32 v76, v100
	v_mul_f32_e32 v80, v78, v78
	v_fmamk_f32 v71, v80, 0x3e9b6dac, v109
	v_sub_f32_e32 v77, v78, v77
	v_fmaak_f32 v71, v80, v71, 0x3f2aaada
	v_sub_f32_e32 v75, v75, v77
	v_mul_f32_e32 v77, v78, v80
	v_pk_mul_f32 v[80:81], v[76:77], v[70:71]
	v_ldexp_f32 v79, v78, 1
	v_fma_f32 v78, v76, s11, -v80
	v_fmac_f32_e32 v78, 0xb102e308, v76
	v_pk_add_f32 v[76:77], v[80:81], v[78:79]
	v_ldexp_f32 v75, v75, 1
	v_sub_f32_e32 v71, v77, v79
	v_sub_f32_e32 v71, v81, v71
	v_add_f32_e32 v83, v75, v71
	v_mov_b32_e32 v82, v80
	v_pk_add_f32 v[80:81], v[76:77], v[80:81] neg_lo:[0,1] neg_hi:[0,1]
	v_pk_add_f32 v[84:85], v[76:77], v[82:83]
	v_mov_b32_e32 v79, v76
	v_mov_b32_e32 v81, v85
	v_pk_add_f32 v[86:87], v[78:79], v[80:81] neg_lo:[0,1] neg_hi:[0,1]
	v_pk_add_f32 v[78:79], v[78:79], v[80:81]
	v_mov_b32_e32 v98, v77
	v_pk_add_f32 v[80:81], v[78:79], v[76:77] op_sel:[1,0] op_sel_hi:[0,1] neg_lo:[0,1] neg_hi:[0,1]
	v_pk_add_f32 v[96:97], v[84:85], v[80:81] op_sel_hi:[1,0] neg_lo:[0,1] neg_hi:[0,1]
	v_mov_b32_e32 v84, v85
	v_mov_b32_e32 v85, v79
	v_mov_b32_e32 v99, v80
	v_pk_add_f32 v[80:81], v[84:85], v[98:99] neg_lo:[0,1] neg_hi:[0,1]
	v_mov_b32_e32 v82, v83
	v_mov_b32_e32 v83, v76
	v_pk_add_f32 v[76:77], v[82:83], v[80:81] neg_lo:[0,1] neg_hi:[0,1]
	v_mov_b32_e32 v96, v86
	v_pk_add_f32 v[80:81], v[96:97], v[76:77]
	v_mov_b32_e32 v87, v79
	v_pk_add_f32 v[82:83], v[80:81], v[80:81] op_sel:[0,1] op_sel_hi:[1,0]
	v_or_b32_e32 v99, 3, v124
	v_pk_add_f32 v[78:79], v[78:79], v[82:83] op_sel:[1,0] op_sel_hi:[0,1]
	v_mov_b32_e32 v81, v78
	v_pk_add_f32 v[84:85], v[80:81], v[86:87] neg_lo:[0,1] neg_hi:[0,1]
	v_mov_b32_e32 v77, v82
	v_sub_f32_e32 v71, v80, v84
	v_pk_add_f32 v[76:77], v[76:77], v[84:85] neg_lo:[0,1] neg_hi:[0,1]
	v_sub_f32_e32 v71, v86, v71
	v_add_f32_e32 v71, v76, v71
	v_sub_u32_e32 v82, v103, v99
	v_add_f32_e32 v71, v71, v77
	v_cvt_f32_u32_e32 v83, v82
	v_sub_u32_e32 v84, 0, v82
	v_add_f32_e32 v71, v78, v71
	v_cvt_f32_u32_e32 v84, v84
	v_cndmask_b32_e32 v71, v112, v71, vcc
	v_cmp_lt_f32_e64 vcc, |v74|, s12
	v_mul_f32_e32 v83, v95, v83
	v_exp_f32_e32 v83, v83
	v_cndmask_b32_e32 v71, v71, v74, vcc
	v_mul_f32_e32 v71, 0xbfb8aa3b, v71
	v_mul_f32_e32 v84, v71, v84
	v_exp_f32_e32 v84, v84
	v_cmp_lt_i32_e32 vcc, -1, v82
	v_sub_u32_e32 v100, v103, v123
	v_sub_u32_e32 v87, 0, v100
	v_cndmask_b32_e32 v83, 0, v83, vcc
	v_cmp_gt_i32_e32 vcc, 1, v82
	v_cvt_f32_u32_e32 v86, v100
	v_cvt_f32_u32_e32 v87, v87
	v_cndmask_b32_e32 v82, 0, v84, vcc
	v_add_f32_e32 v82, v83, v82
	v_mul_f32_e32 v39, v39, v82
	v_cvt_pk_bf16_f32 v102, v39, s0
	v_sub_u32_e32 v39, v103, v122
	v_cvt_f32_u32_e32 v101, v39
	v_sub_u32_e32 v120, 0, v39
	v_cvt_f32_u32_e32 v120, v120
	v_mul_f32_e32 v86, v95, v86
	v_mul_f32_e32 v101, v95, v101
	v_exp_f32_e32 v101, v101
	v_mul_f32_e32 v87, v71, v87
	v_cmp_lt_i32_e32 vcc, -1, v39
	v_exp_f32_e32 v86, v86
	v_exp_f32_e32 v121, v87
	v_cndmask_b32_e32 v87, 0, v101, vcc
	v_mul_f32_e32 v101, v71, v120
	v_exp_f32_e32 v101, v101
	s_mul_hi_i32 s11, s10, 0x820000
	s_mul_i32 s10, s10, 0x820000
	v_readlane_b32 s12, v182, 21
	v_readlane_b32 s13, v182, 22
	s_add_u32 s12, s12, s10
	v_cmp_lt_i32_e32 vcc, -1, v100
	s_addc_u32 s13, s13, s11
	s_lshl_b64 s[10:11], s[6:7], 19
	v_cndmask_b32_e32 v86, 0, v86, vcc
	v_cmp_gt_i32_e32 vcc, 1, v39
	s_add_u32 s10, s12, s10
	s_addc_u32 s11, s13, s11
	v_cndmask_b32_e32 v101, 0, v101, vcc
	v_cmp_gt_i32_e32 vcc, 1, v100
	v_mad_i64_i32 v[74:75], s[12:13], s20, v103, 0
	s_nop 0
	v_cndmask_b32_e32 v100, 0, v121, vcc
	v_lshl_add_u64 v[80:81], v[74:75], 1, s[10:11]
	v_lshlrev_b32_e32 v84, 1, v124
	v_mov_b32_e32 v85, v69
	v_pk_add_f32 v[86:87], v[86:87], v[100:101]
	v_mov_b32_e32 v100, v37
	v_mov_b32_e32 v101, v38
	v_or_b32_e32 v98, 16, v103
	v_lshl_add_u64 v[82:83], v[80:81], 0, v[84:85]
	v_pk_mul_f32 v[38:39], v[100:101], v[86:87]
	v_sub_u32_e32 v100, v98, v123
	v_cvt_pk_bf16_f32 v37, v38, v39
	global_store_short v[82:83], v102, off offset:6
	global_store_dword v[82:83], v37, off offset:2
	v_sub_u32_e32 v102, v98, v124
	v_sub_u32_e32 v39, 0, v102
	v_cvt_f32_u32_e32 v39, v39
	v_sub_u32_e32 v87, 0, v100
	v_cvt_f32_u32_e32 v86, v100
	v_cvt_f32_u32_e32 v87, v87
	v_mul_f32_e32 v39, v71, v39
	v_sub_u32_e32 v37, v98, v122
	v_exp_f32_e32 v121, v39
	v_mul_f32_e32 v39, v95, v86
	v_mul_f32_e32 v86, v71, v87
	v_cvt_f32_u32_e32 v87, v37
	v_exp_f32_e32 v101, v86
	v_sub_u32_e32 v86, 0, v37
	v_cvt_f32_u32_e32 v38, v102
	v_sub_u32_e32 v120, v98, v99
	v_cvt_f32_u32_e32 v86, v86
	v_cvt_f32_u32_e32 v125, v120
	v_mul_f32_e32 v87, v95, v87
	v_mul_f32_e32 v38, v95, v38
	v_exp_f32_e32 v39, v39
	v_exp_f32_e32 v126, v87
	v_mul_f32_e32 v86, v71, v86
	v_sub_u32_e32 v87, 0, v120
	v_exp_f32_e32 v38, v38
	v_exp_f32_e32 v127, v86
	v_mul_f32_e32 v86, v95, v125
	v_cvt_f32_u32_e32 v125, v87
	v_exp_f32_e32 v86, v86
	v_cmp_lt_i32_e32 vcc, -1, v100
	v_or_b32_e32 v97, 32, v103
	v_mul_f32_e32 v125, v71, v125
	v_cndmask_b32_e32 v39, 0, v39, vcc
	v_cmp_lt_i32_e32 vcc, -1, v102
	v_exp_f32_e32 v125, v125
	v_or_b32_e32 v96, 48, v103
	v_cndmask_b32_e32 v38, 0, v38, vcc
	v_cmp_lt_i32_e32 vcc, -1, v120
	v_mad_i64_i32 v[74:75], s[12:13], s20, v98, 0
	s_nop 0
	v_cndmask_b32_e32 v87, 0, v86, vcc
	v_cmp_lt_i32_e32 vcc, -1, v37
	v_lshl_add_u64 v[78:79], v[74:75], 1, s[10:11]
	v_mad_i64_i32 v[74:75], s[12:13], s20, v97, 0
	v_cndmask_b32_e32 v86, 0, v126, vcc
	v_cmp_gt_i32_e32 vcc, 1, v100
	v_lshl_add_u64 v[76:77], v[74:75], 1, s[10:11]
	v_mad_i64_i32 v[74:75], s[12:13], s20, v96, 0
	v_cndmask_b32_e32 v101, 0, v101, vcc
	v_cmp_gt_i32_e32 vcc, 1, v102
	v_sub_u32_e32 v102, v97, v124
	v_lshl_add_u64 v[74:75], v[74:75], 1, s[10:11]
	v_cndmask_b32_e32 v100, 0, v121, vcc
	v_cmp_gt_i32_e32 vcc, 1, v120
	v_pk_add_f32 v[38:39], v[38:39], v[100:101]
	v_sub_u32_e32 v100, v97, v123
	v_cndmask_b32_e32 v121, 0, v125, vcc
	v_cmp_gt_i32_e32 vcc, 1, v37
	v_pk_mul_f32 v[38:39], v[60:61], v[38:39]
	v_sub_u32_e32 v37, v97, v122
	v_cndmask_b32_e32 v120, 0, v127, vcc
	v_pk_add_f32 v[86:87], v[86:87], v[120:121]
	v_sub_u32_e32 v120, v97, v99
	v_pk_mul_f32 v[60:61], v[62:63], v[86:87]
	v_sub_u32_e32 v87, 0, v100
	v_cvt_pk_bf16_f32 v61, v60, v61
	v_cvt_pk_bf16_f32 v60, v38, v39
	v_sub_u32_e32 v39, 0, v102
	v_cvt_f32_u32_e32 v39, v39
	v_cvt_f32_u32_e32 v86, v100
	v_cvt_f32_u32_e32 v87, v87
	v_cvt_f32_u32_e32 v38, v102
	v_mul_f32_e32 v39, v71, v39
	v_exp_f32_e32 v121, v39
	v_mul_f32_e32 v39, v95, v86
	v_mul_f32_e32 v86, v71, v87
	v_cvt_f32_u32_e32 v87, v37
	v_exp_f32_e32 v101, v86
	v_sub_u32_e32 v86, 0, v37
	v_cvt_f32_u32_e32 v86, v86
	v_cvt_f32_u32_e32 v125, v120
	v_mul_f32_e32 v87, v95, v87
	v_mul_f32_e32 v38, v95, v38
	v_exp_f32_e32 v39, v39
	v_exp_f32_e32 v126, v87
	v_mul_f32_e32 v86, v71, v86
	v_sub_u32_e32 v87, 0, v120
	v_exp_f32_e32 v38, v38
	v_exp_f32_e32 v127, v86
	v_mul_f32_e32 v86, v95, v125
	v_cvt_f32_u32_e32 v125, v87
	v_exp_f32_e32 v86, v86
	v_cmp_lt_i32_e32 vcc, -1, v100
	v_sub_u32_e32 v99, v96, v99
	v_mul_f32_e32 v125, v71, v125
	v_cndmask_b32_e32 v39, 0, v39, vcc
	v_cmp_lt_i32_e32 vcc, -1, v102
	v_exp_f32_e32 v125, v125
	v_lshl_add_u64 v[62:63], v[78:79], 0, v[84:85]
	v_cndmask_b32_e32 v38, 0, v38, vcc
	v_cmp_lt_i32_e32 vcc, -1, v120
	s_add_i32 s8, s8, s84
	s_nop 0
	v_cndmask_b32_e32 v87, 0, v86, vcc
	v_cmp_lt_i32_e32 vcc, -1, v37
	s_nop 1
	v_cndmask_b32_e32 v86, 0, v126, vcc
	v_cmp_gt_i32_e32 vcc, 1, v100
	s_nop 1
	v_cndmask_b32_e32 v101, 0, v101, vcc
	v_cmp_gt_i32_e32 vcc, 1, v102
	v_sub_u32_e32 v102, v96, v124
	s_nop 0
	v_cndmask_b32_e32 v100, 0, v121, vcc
	v_cmp_gt_i32_e32 vcc, 1, v120
	v_pk_add_f32 v[38:39], v[38:39], v[100:101]
	v_sub_u32_e32 v100, v96, v123
	v_cndmask_b32_e32 v121, 0, v125, vcc
	v_cmp_gt_i32_e32 vcc, 1, v37
	v_pk_mul_f32 v[38:39], v[56:57], v[38:39]
	v_sub_u32_e32 v37, v96, v122
	v_cndmask_b32_e32 v120, 0, v127, vcc
	v_pk_add_f32 v[86:87], v[86:87], v[120:121]
	v_cvt_f32_u32_e32 v121, v99
	v_pk_mul_f32 v[56:57], v[58:59], v[86:87]
	v_sub_u32_e32 v87, 0, v100
	v_cvt_pk_bf16_f32 v57, v56, v57
	v_cvt_pk_bf16_f32 v56, v38, v39
	v_sub_u32_e32 v39, 0, v102
	v_cvt_f32_u32_e32 v39, v39
	v_cvt_f32_u32_e32 v86, v100
	v_cvt_f32_u32_e32 v87, v87
	v_cvt_f32_u32_e32 v38, v102
	v_mul_f32_e32 v39, v71, v39
	v_exp_f32_e32 v120, v39
	v_mul_f32_e32 v39, v95, v86
	v_mul_f32_e32 v86, v71, v87
	v_cvt_f32_u32_e32 v87, v37
	v_exp_f32_e32 v101, v86
	v_sub_u32_e32 v86, 0, v37
	v_cvt_f32_u32_e32 v86, v86
	v_mul_f32_e32 v87, v95, v87
	v_mul_f32_e32 v38, v95, v38
	v_exp_f32_e32 v39, v39
	v_exp_f32_e32 v122, v87
	v_mul_f32_e32 v86, v71, v86
	v_sub_u32_e32 v87, 0, v99
	v_exp_f32_e32 v38, v38
	v_exp_f32_e32 v123, v86
	v_mul_f32_e32 v86, v95, v121
	v_cvt_f32_u32_e32 v121, v87
	v_exp_f32_e32 v86, v86
	v_cmp_lt_i32_e32 vcc, -1, v100
	v_lshl_add_u64 v[58:59], v[76:77], 0, v[84:85]
	v_mul_f32_e32 v121, v71, v121
	v_cndmask_b32_e32 v39, 0, v39, vcc
	v_cmp_lt_i32_e32 vcc, -1, v102
	v_exp_f32_e32 v121, v121
	s_nop 0
	v_cndmask_b32_e32 v38, 0, v38, vcc
	v_cmp_lt_i32_e32 vcc, -1, v99
	s_nop 1
	v_cndmask_b32_e32 v87, 0, v86, vcc
	v_cmp_lt_i32_e32 vcc, -1, v37
	s_nop 1
	v_cndmask_b32_e32 v86, 0, v122, vcc
	v_cmp_gt_i32_e32 vcc, 1, v100
	s_nop 1
	v_cndmask_b32_e32 v101, 0, v101, vcc
	v_cmp_gt_i32_e32 vcc, 1, v102
	v_or_b32_e32 v102, 35, v124
	s_nop 0
	v_cndmask_b32_e32 v100, 0, v120, vcc
	v_cmp_gt_i32_e32 vcc, 1, v99
	v_pk_add_f32 v[38:39], v[38:39], v[100:101]
	v_or_b32_e32 v101, 32, v124
	v_cndmask_b32_e32 v121, 0, v121, vcc
	v_cmp_gt_i32_e32 vcc, 1, v37
	v_or_b32_e32 v99, 33, v124
	v_sub_u32_e32 v122, v103, v101
	v_cndmask_b32_e32 v120, 0, v123, vcc
	v_pk_add_f32 v[86:87], v[86:87], v[120:121]
	v_pk_mul_f32 v[38:39], v[52:53], v[38:39]
	v_pk_mul_f32 v[52:53], v[54:55], v[86:87]
	v_sub_u32_e32 v87, 0, v122
	v_sub_u32_e32 v123, v103, v99
	v_cvt_f32_u32_e32 v87, v87
	v_sub_u32_e32 v121, 0, v123
	v_cvt_f32_u32_e32 v120, v123
	v_cvt_f32_u32_e32 v121, v121
	v_or_b32_e32 v100, 34, v124
	v_mul_f32_e32 v87, v71, v87
	v_sub_u32_e32 v125, v103, v100
	v_exp_f32_e32 v126, v87
	v_mul_f32_e32 v87, v95, v120
	v_mul_f32_e32 v120, v71, v121
	v_cvt_f32_u32_e32 v121, v125
	v_exp_f32_e32 v127, v120
	v_sub_u32_e32 v120, 0, v125
	v_sub_u32_e32 v37, v103, v102
	v_cvt_f32_u32_e32 v86, v122
	v_cvt_f32_u32_e32 v120, v120
	v_cvt_f32_u32_e32 v128, v37
	v_mul_f32_e32 v121, v95, v121
	v_mul_f32_e32 v86, v95, v86
	v_exp_f32_e32 v87, v87
	v_exp_f32_e32 v129, v121
	v_mul_f32_e32 v120, v71, v120
	v_sub_u32_e32 v121, 0, v37
	v_exp_f32_e32 v86, v86
	v_exp_f32_e32 v130, v120
	v_mul_f32_e32 v120, v95, v128
	v_cvt_f32_u32_e32 v128, v121
	v_exp_f32_e32 v120, v120
	v_cmp_lt_i32_e32 vcc, -1, v123
	v_cvt_pk_bf16_f32 v53, v52, v53
	v_mul_f32_e32 v128, v71, v128
	v_cndmask_b32_e32 v87, 0, v87, vcc
	v_cmp_lt_i32_e32 vcc, -1, v122
	v_exp_f32_e32 v128, v128
	v_cvt_pk_bf16_f32 v52, v38, v39
	v_cndmask_b32_e32 v86, 0, v86, vcc
	v_cmp_lt_i32_e32 vcc, -1, v37
	v_lshlrev_b32_e32 v38, 1, v101
	v_mov_b32_e32 v39, v69
	v_cndmask_b32_e32 v121, 0, v120, vcc
	v_cmp_lt_i32_e32 vcc, -1, v125
	v_lshl_add_u64 v[54:55], v[74:75], 0, v[84:85]
	v_lshl_add_u64 v[84:85], v[80:81], 0, v[38:39]
	v_cndmask_b32_e32 v120, 0, v129, vcc
	v_cmp_gt_i32_e32 vcc, 1, v123
	s_nop 1
	v_cndmask_b32_e32 v123, 0, v127, vcc
	v_cmp_gt_i32_e32 vcc, 1, v122
	s_nop 1
	v_cndmask_b32_e32 v122, 0, v126, vcc
	v_cmp_gt_i32_e32 vcc, 1, v37
	v_pk_add_f32 v[86:87], v[86:87], v[122:123]
	v_sub_u32_e32 v37, v97, v102
	v_cndmask_b32_e32 v127, 0, v128, vcc
	v_cmp_gt_i32_e32 vcc, 1, v125
	v_pk_mul_f32 v[48:49], v[48:49], v[86:87]
	v_or_b32_e32 v122, 16, v124
	v_cndmask_b32_e32 v126, 0, v130, vcc
	v_pk_add_f32 v[120:121], v[120:121], v[126:127]
	v_sub_u32_e32 v130, v103, v122
	v_pk_mul_f32 v[50:51], v[50:51], v[120:121]
	v_or_b32_e32 v120, 17, v124
	v_cvt_pk_bf16_f32 v51, v50, v51
	v_cvt_pk_bf16_f32 v50, v48, v49
	v_cvt_f32_u32_e32 v48, v37
	v_sub_u32_e32 v49, 0, v37
	v_cvt_f32_u32_e32 v49, v49
	v_sub_u32_e32 v127, 0, v130
	v_mul_f32_e32 v48, v95, v48
	v_sub_u32_e32 v131, v103, v120
	v_exp_f32_e32 v48, v48
	v_mul_f32_e32 v49, v71, v49
	v_cvt_f32_u32_e32 v127, v127
	v_sub_u32_e32 v129, 0, v131
	v_exp_f32_e32 v49, v49
	v_cvt_f32_u32_e32 v128, v131
	v_cvt_f32_u32_e32 v129, v129
	v_cmp_lt_i32_e32 vcc, -1, v37
	v_or_b32_e32 v121, 18, v124
	v_mul_f32_e32 v127, v71, v127
	v_cndmask_b32_e32 v48, 0, v48, vcc
	v_cmp_gt_i32_e32 vcc, 1, v37
	v_sub_u32_e32 v125, v103, v121
	v_exp_f32_e32 v132, v127
	v_cndmask_b32_e32 v37, 0, v49, vcc
	v_mul_f32_e32 v127, v95, v128
	v_mul_f32_e32 v128, v71, v129
	v_add_f32_e32 v37, v48, v37
	v_or_b32_e32 v123, 19, v124
	v_cvt_f32_u32_e32 v129, v125
	v_exp_f32_e32 v133, v128
	v_sub_u32_e32 v128, 0, v125
	v_mul_f32_e32 v11, v11, v37
	v_sub_u32_e32 v37, v103, v123
	v_cvt_f32_u32_e32 v126, v130
	v_cvt_f32_u32_e32 v128, v128
	v_cvt_f32_u32_e32 v134, v37
	v_mul_f32_e32 v129, v95, v129
	v_mul_f32_e32 v126, v95, v126
	v_exp_f32_e32 v127, v127
	v_exp_f32_e32 v135, v129
	v_mul_f32_e32 v128, v71, v128
	v_sub_u32_e32 v129, 0, v37
	v_exp_f32_e32 v126, v126
	v_exp_f32_e32 v136, v128
	v_mul_f32_e32 v128, v95, v134
	v_cvt_f32_u32_e32 v134, v129
	v_exp_f32_e32 v128, v128
	v_cmp_lt_i32_e32 vcc, -1, v131
	global_store_dwordx2 v[84:85], v[50:51], off
	v_mul_f32_e32 v134, v71, v134
	v_cndmask_b32_e32 v127, 0, v127, vcc
	v_cmp_lt_i32_e32 vcc, -1, v130
	v_exp_f32_e32 v134, v134
	v_lshlrev_b32_e32 v50, 1, v122
	v_cndmask_b32_e32 v126, 0, v126, vcc
	v_cmp_lt_i32_e32 vcc, -1, v37
	v_mov_b32_e32 v51, v69
	v_lshl_add_u64 v[86:87], v[80:81], 0, v[50:51]
	v_cndmask_b32_e32 v129, 0, v128, vcc
	v_cmp_lt_i32_e32 vcc, -1, v125
	v_lshl_add_u64 v[84:85], v[78:79], 0, v[38:39]
	v_cvt_pk_bf16_f32 v11, v11, s0
	v_cndmask_b32_e32 v128, 0, v135, vcc
	v_cmp_gt_i32_e32 vcc, 1, v131
	v_lshl_add_u64 v[48:49], v[76:77], 0, v[38:39]
	s_nop 0
	v_cndmask_b32_e32 v131, 0, v133, vcc
	v_cmp_gt_i32_e32 vcc, 1, v130
	s_nop 1
	v_cndmask_b32_e32 v130, 0, v132, vcc
	v_cmp_gt_i32_e32 vcc, 1, v37
	v_pk_add_f32 v[126:127], v[126:127], v[130:131]
	v_sub_u32_e32 v37, v98, v123
	v_cndmask_b32_e32 v133, 0, v134, vcc
	v_cmp_gt_i32_e32 vcc, 1, v125
	v_pk_mul_f32 v[44:45], v[44:45], v[126:127]
	v_sub_u32_e32 v125, v96, v121
	v_cndmask_b32_e32 v132, 0, v136, vcc
	v_pk_add_f32 v[128:129], v[128:129], v[132:133]
	v_cmp_lt_i32_e32 vcc, -1, v37
	v_pk_mul_f32 v[46:47], v[46:47], v[128:129]
	v_sub_u32_e32 v128, v96, v122
	v_cvt_pk_bf16_f32 v47, v46, v47
	v_cvt_pk_bf16_f32 v46, v44, v45
	v_cvt_f32_u32_e32 v44, v37
	v_sub_u32_e32 v45, 0, v37
	v_cvt_f32_u32_e32 v45, v45
	global_store_dwordx2 v[86:87], v[46:47], off
	v_mul_f32_e32 v44, v95, v44
	v_sub_u32_e32 v47, 0, v128
	v_sub_u32_e32 v129, v96, v120
	v_exp_f32_e32 v44, v44
	v_mul_f32_e32 v45, v71, v45
	v_cvt_f32_u32_e32 v47, v47
	v_sub_u32_e32 v127, 0, v129
	v_exp_f32_e32 v45, v45
	v_cvt_f32_u32_e32 v126, v129
	v_cvt_f32_u32_e32 v127, v127
	v_cndmask_b32_e32 v44, 0, v44, vcc
	v_cmp_gt_i32_e32 vcc, 1, v37
	v_mul_f32_e32 v47, v71, v47
	v_exp_f32_e32 v130, v47
	v_cndmask_b32_e32 v37, 0, v45, vcc
	v_mul_f32_e32 v47, v95, v126
	v_mul_f32_e32 v126, v71, v127
	v_add_f32_e32 v37, v44, v37
	v_cvt_f32_u32_e32 v127, v125
	v_exp_f32_e32 v131, v126
	v_sub_u32_e32 v126, 0, v125
	v_mul_f32_e32 v27, v27, v37
	v_sub_u32_e32 v37, v96, v123
	v_cvt_f32_u32_e32 v46, v128
	v_cvt_f32_u32_e32 v126, v126
	v_cvt_f32_u32_e32 v132, v37
	v_mul_f32_e32 v127, v95, v127
	v_mul_f32_e32 v46, v95, v46
	v_exp_f32_e32 v47, v47
	v_exp_f32_e32 v133, v127
	v_mul_f32_e32 v126, v71, v126
	v_sub_u32_e32 v127, 0, v37
	v_exp_f32_e32 v46, v46
	v_exp_f32_e32 v134, v126
	v_mul_f32_e32 v126, v95, v132
	v_cvt_f32_u32_e32 v132, v127
	v_exp_f32_e32 v126, v126
	v_cmp_lt_i32_e32 vcc, -1, v129
	v_lshl_add_u64 v[86:87], v[78:79], 0, v[50:51]
	v_mul_f32_e32 v132, v71, v132
	v_cndmask_b32_e32 v47, 0, v47, vcc
	v_cmp_lt_i32_e32 vcc, -1, v128
	v_exp_f32_e32 v132, v132
	v_cvt_pk_bf16_f32 v27, v27, s0
	v_cndmask_b32_e32 v46, 0, v46, vcc
	v_cmp_lt_i32_e32 vcc, -1, v37
	v_lshl_add_u64 v[44:45], v[76:77], 0, v[50:51]
	v_lshl_add_u64 v[50:51], v[74:75], 0, v[50:51]
	v_cndmask_b32_e32 v127, 0, v126, vcc
	v_cmp_lt_i32_e32 vcc, -1, v125
	s_nop 1
	v_cndmask_b32_e32 v126, 0, v133, vcc
	v_cmp_gt_i32_e32 vcc, 1, v129
	v_or_b32_e32 v133, 51, v124
	s_nop 0
	v_cndmask_b32_e32 v129, 0, v131, vcc
	v_cmp_gt_i32_e32 vcc, 1, v128
	s_nop 1
	v_cndmask_b32_e32 v128, 0, v130, vcc
	v_cmp_gt_i32_e32 vcc, 1, v37
	v_pk_add_f32 v[46:47], v[46:47], v[128:129]
	v_sub_u32_e32 v37, v96, v133
	v_cndmask_b32_e32 v131, 0, v132, vcc
	v_cmp_gt_i32_e32 vcc, 1, v125
	v_pk_mul_f32 v[40:41], v[40:41], v[46:47]
	v_or_b32_e32 v132, 50, v124
	v_cndmask_b32_e32 v130, 0, v134, vcc
	v_pk_add_f32 v[126:127], v[126:127], v[130:131]
	v_or_b32_e32 v130, 48, v124
	v_or_b32_e32 v131, 49, v124
	v_sub_u32_e32 v124, v103, v124
	v_pk_mul_f32 v[42:43], v[42:43], v[126:127]
	v_cvt_pk_bf16_f32 v46, v40, v41
	v_sub_u32_e32 v41, 0, v124
	v_sub_u32_e32 v125, v96, v131
	v_cvt_pk_bf16_f32 v47, v42, v43
	v_cvt_f32_u32_e32 v41, v41
	v_sub_u32_e32 v43, 0, v125
	v_cvt_f32_u32_e32 v42, v125
	v_cvt_f32_u32_e32 v43, v43
	v_cvt_f32_u32_e32 v40, v124
	v_mul_f32_e32 v41, v71, v41
	v_sub_u32_e32 v126, v96, v132
	v_exp_f32_e32 v127, v41
	v_mul_f32_e32 v41, v95, v42
	v_mul_f32_e32 v42, v71, v43
	v_exp_f32_e32 v128, v42
	v_sub_u32_e32 v42, 0, v126
	v_cvt_f32_u32_e32 v43, v126
	v_cvt_f32_u32_e32 v42, v42
	v_mul_f32_e32 v40, v95, v40
	v_exp_f32_e32 v41, v41
	v_cvt_f32_u32_e32 v129, v37
	v_exp_f32_e32 v40, v40
	v_mul_f32_e32 v43, v95, v43
	v_mul_f32_e32 v42, v71, v42
	v_cmp_lt_i32_e32 vcc, -1, v125
	v_exp_f32_e32 v134, v43
	v_exp_f32_e32 v135, v42
	v_mul_f32_e32 v42, v95, v129
	v_cndmask_b32_e32 v43, 0, v41, vcc
	v_cmp_lt_i32_e32 vcc, -1, v124
	v_exp_f32_e32 v129, v42
	s_nop 0
	v_cndmask_b32_e32 v42, 0, v40, vcc
	v_sub_u32_e32 v40, 0, v37
	v_cvt_f32_u32_e32 v136, v40
	v_cmp_lt_i32_e32 vcc, -1, v37
	s_nop 1
	v_cndmask_b32_e32 v41, 0, v129, vcc
	v_mul_f32_e32 v129, v71, v136
	v_cmp_lt_i32_e32 vcc, -1, v126
	v_exp_f32_e32 v129, v129
	s_nop 0
	v_cndmask_b32_e32 v40, 0, v134, vcc
	v_cmp_gt_i32_e32 vcc, 1, v125
	v_sub_u32_e32 v134, v103, v132
	s_nop 0
	v_cndmask_b32_e32 v125, 0, v128, vcc
	v_cmp_gt_i32_e32 vcc, 1, v124
	v_sub_u32_e32 v128, v103, v133
	s_nop 0
	v_cndmask_b32_e32 v124, 0, v127, vcc
	v_cmp_gt_i32_e32 vcc, 1, v37
	v_pk_add_f32 v[42:43], v[42:43], v[124:125]
	v_mov_b32_e32 v37, v69
	v_cndmask_b32_e32 v127, 0, v129, vcc
	v_cmp_gt_i32_e32 vcc, 1, v126
	v_mul_f32_e32 v36, v36, v42
	v_cvt_pk_bf16_f32 v36, v36, s0
	v_cndmask_b32_e32 v126, 0, v135, vcc
	v_pk_add_f32 v[40:41], v[40:41], v[126:127]
	v_sub_u32_e32 v126, v103, v130
	global_store_short v[82:83], v36, off
	v_sub_u32_e32 v83, 0, v126
	v_sub_u32_e32 v103, v103, v131
	v_cvt_f32_u32_e32 v83, v83
	v_sub_u32_e32 v125, 0, v103
	v_cvt_f32_u32_e32 v124, v103
	v_cvt_f32_u32_e32 v125, v125
	v_mul_f32_e32 v83, v71, v83
	v_exp_f32_e32 v129, v83
	v_mul_f32_e32 v83, v95, v124
	v_mul_f32_e32 v124, v71, v125
	v_cvt_f32_u32_e32 v125, v134
	v_exp_f32_e32 v127, v124
	v_sub_u32_e32 v124, 0, v134
	v_cvt_f32_u32_e32 v82, v126
	v_cvt_f32_u32_e32 v124, v124
	v_cvt_f32_u32_e32 v135, v128
	v_mul_f32_e32 v125, v95, v125
	v_mul_f32_e32 v82, v95, v82
	v_exp_f32_e32 v83, v83
	v_exp_f32_e32 v136, v125
	v_mul_f32_e32 v124, v71, v124
	v_sub_u32_e32 v125, 0, v128
	v_exp_f32_e32 v82, v82
	v_exp_f32_e32 v137, v124
	v_mul_f32_e32 v124, v95, v135
	v_cvt_f32_u32_e32 v135, v125
	v_exp_f32_e32 v124, v124
	v_cmp_lt_i32_e32 vcc, -1, v103
	v_lshlrev_b32_e32 v36, 1, v130
	v_mul_f32_e32 v135, v71, v135
	v_cndmask_b32_e32 v83, 0, v83, vcc
	v_cmp_lt_i32_e32 vcc, -1, v126
	v_exp_f32_e32 v135, v135
	v_lshl_add_u64 v[80:81], v[80:81], 0, v[36:37]
	v_cndmask_b32_e32 v82, 0, v82, vcc
	v_cmp_lt_i32_e32 vcc, -1, v128
	v_mul_f32_e32 v24, v24, v42
	v_mul_f32_e32 v8, v8, v42
	v_cndmask_b32_e32 v125, 0, v124, vcc
	v_cmp_lt_i32_e32 vcc, -1, v134
	v_pk_mul_f32 v[0:1], v[0:1], v[42:43]
	v_pk_mul_f32 v[2:3], v[2:3], v[40:41]
	v_cndmask_b32_e32 v124, 0, v136, vcc
	v_cmp_gt_i32_e32 vcc, 1, v103
	v_cvt_pk_bf16_f32 v103, v24, s0
	v_sub_u32_e32 v24, v97, v132
	v_cndmask_b32_e32 v127, 0, v127, vcc
	v_cmp_gt_i32_e32 vcc, 1, v126
	v_cvt_pk_bf16_f32 v3, v2, v3
	v_cvt_pk_bf16_f32 v2, v0, v1
	v_cndmask_b32_e32 v126, 0, v129, vcc
	v_cmp_gt_i32_e32 vcc, 1, v128
	v_pk_add_f32 v[82:83], v[82:83], v[126:127]
	v_lshl_add_u64 v[0:1], v[74:75], 0, v[36:37]
	v_cndmask_b32_e32 v129, 0, v135, vcc
	v_cmp_gt_i32_e32 vcc, 1, v134
	v_pk_mul_f32 v[32:33], v[32:33], v[82:83]
	s_nop 0
	v_cndmask_b32_e32 v128, 0, v137, vcc
	v_pk_add_f32 v[124:125], v[124:125], v[128:129]
	s_nop 0
	v_pk_mul_f32 v[34:35], v[34:35], v[124:125]
	v_cvt_pk_bf16_f32 v124, v8, s0
	v_cvt_pk_bf16_f32 v35, v34, v35
	v_cvt_pk_bf16_f32 v34, v32, v33
	global_store_dwordx2 v[80:81], v[34:35], off
	v_sub_u32_e32 v80, v97, v130
	v_sub_u32_e32 v35, 0, v80
	v_sub_u32_e32 v81, v97, v131
	v_lshl_add_u64 v[32:33], v[78:79], 0, v[36:37]
	v_cvt_f32_u32_e32 v35, v35
	v_sub_u32_e32 v79, 0, v81
	v_cvt_f32_u32_e32 v78, v81
	v_cvt_f32_u32_e32 v79, v79
	v_mul_f32_e32 v35, v71, v35
	v_exp_f32_e32 v82, v35
	v_mul_f32_e32 v35, v95, v78
	v_mul_f32_e32 v78, v71, v79
	v_cvt_f32_u32_e32 v79, v24
	v_exp_f32_e32 v83, v78
	v_sub_u32_e32 v78, 0, v24
	v_sub_u32_e32 v8, v97, v133
	v_cvt_f32_u32_e32 v34, v80
	v_cvt_f32_u32_e32 v78, v78
	v_cvt_f32_u32_e32 v125, v8
	v_mul_f32_e32 v79, v95, v79
	v_mul_f32_e32 v34, v95, v34
	v_exp_f32_e32 v35, v35
	v_exp_f32_e32 v126, v79
	v_mul_f32_e32 v78, v71, v78
	v_sub_u32_e32 v79, 0, v8
	v_exp_f32_e32 v34, v34
	v_exp_f32_e32 v127, v78
	v_mul_f32_e32 v78, v95, v125
	v_cvt_f32_u32_e32 v125, v79
	v_exp_f32_e32 v78, v78
	v_cmp_lt_i32_e32 vcc, -1, v81
	global_store_dwordx2 v[62:63], v[60:61], off
	v_mul_f32_e32 v125, v71, v125
	v_cndmask_b32_e32 v35, 0, v35, vcc
	v_cmp_lt_i32_e32 vcc, -1, v80
	v_exp_f32_e32 v125, v125
	s_mov_b32 s0, 0x5040100
	v_cndmask_b32_e32 v34, 0, v34, vcc
	v_cmp_lt_i32_e32 vcc, -1, v8
	s_nop 1
	v_cndmask_b32_e32 v79, 0, v78, vcc
	v_cmp_lt_i32_e32 vcc, -1, v24
	s_nop 1
	v_cndmask_b32_e32 v78, 0, v126, vcc
	v_cmp_gt_i32_e32 vcc, 1, v81
	s_nop 1
	v_cndmask_b32_e32 v81, 0, v83, vcc
	v_cmp_gt_i32_e32 vcc, 1, v80
	s_nop 1
	v_cndmask_b32_e32 v80, 0, v82, vcc
	v_cmp_gt_i32_e32 vcc, 1, v8
	v_sub_u32_e32 v8, v98, v121
	v_cvt_f32_u32_e32 v60, v8
	v_cndmask_b32_e32 v83, 0, v125, vcc
	v_cmp_gt_i32_e32 vcc, 1, v24
	v_pk_add_f32 v[34:35], v[34:35], v[80:81]
	v_sub_u32_e32 v24, v98, v120
	v_cndmask_b32_e32 v82, 0, v127, vcc
	v_pk_add_f32 v[78:79], v[78:79], v[82:83]
	v_pk_mul_f32 v[34:35], v[28:29], v[34:35]
	v_pk_mul_f32 v[28:29], v[30:31], v[78:79]
	v_mul_f32_e32 v60, v95, v60
	v_cvt_pk_bf16_f32 v29, v28, v29
	v_cvt_pk_bf16_f32 v28, v34, v35
	v_sub_u32_e32 v35, 0, v24
	v_cvt_f32_u32_e32 v34, v24
	v_cvt_f32_u32_e32 v35, v35
	v_sub_u32_e32 v61, 0, v8
	v_exp_f32_e32 v60, v60
	v_cvt_f32_u32_e32 v61, v61
	v_mul_f32_e32 v34, v95, v34
	v_mul_f32_e32 v35, v71, v35
	v_cmp_lt_i32_e32 vcc, -1, v8
	v_exp_f32_e32 v34, v34
	v_exp_f32_e32 v62, v35
	v_cndmask_b32_e32 v35, 0, v60, vcc
	v_mul_f32_e32 v60, v71, v61
	v_exp_f32_e32 v60, v60
	v_cmp_lt_i32_e32 vcc, -1, v24
	v_lshl_add_u64 v[30:31], v[76:77], 0, v[36:37]
	s_nop 0
	v_cndmask_b32_e32 v34, 0, v34, vcc
	v_cmp_gt_i32_e32 vcc, 1, v8
	s_nop 1
	v_cndmask_b32_e32 v61, 0, v60, vcc
	v_cmp_gt_i32_e32 vcc, 1, v24
	v_mov_b32_e32 v24, v25
	v_mov_b32_e32 v25, v26
	v_cndmask_b32_e32 v60, 0, v62, vcc
	v_pk_add_f32 v[34:35], v[34:35], v[60:61]
	v_sub_u32_e32 v60, v98, v100
	v_pk_mul_f32 v[24:25], v[24:25], v[34:35]
	v_sub_u32_e32 v34, v98, v101
	v_cvt_pk_bf16_f32 v8, v24, v25
	v_perm_b32 v24, v8, v103, s0
	v_alignbit_b32 v25, v27, v8, 16
	global_store_dwordx2 v[86:87], v[24:25], off
	v_sub_u32_e32 v25, 0, v34
	v_sub_u32_e32 v35, v98, v99
	v_cvt_f32_u32_e32 v25, v25
	v_sub_u32_e32 v27, 0, v35
	v_cvt_f32_u32_e32 v26, v35
	v_cvt_f32_u32_e32 v27, v27
	v_mul_f32_e32 v25, v71, v25
	v_exp_f32_e32 v61, v25
	v_mul_f32_e32 v25, v95, v26
	v_mul_f32_e32 v26, v71, v27
	v_cvt_f32_u32_e32 v27, v60
	v_exp_f32_e32 v62, v26
	v_sub_u32_e32 v26, 0, v60
	v_sub_u32_e32 v8, v98, v102
	v_cvt_f32_u32_e32 v24, v34
	v_cvt_f32_u32_e32 v26, v26
	v_cvt_f32_u32_e32 v63, v8
	v_mul_f32_e32 v27, v95, v27
	v_mul_f32_e32 v24, v95, v24
	v_exp_f32_e32 v25, v25
	v_exp_f32_e32 v76, v27
	v_mul_f32_e32 v26, v71, v26
	v_sub_u32_e32 v27, 0, v8
	v_exp_f32_e32 v24, v24
	v_exp_f32_e32 v77, v26
	v_mul_f32_e32 v26, v95, v63
	v_cvt_f32_u32_e32 v63, v27
	v_exp_f32_e32 v26, v26
	v_cmp_lt_i32_e32 vcc, -1, v35
	v_mul_f32_e32 v63, v71, v63
	s_nop 0
	v_cndmask_b32_e32 v25, 0, v25, vcc
	v_cmp_lt_i32_e32 vcc, -1, v34
	v_exp_f32_e32 v63, v63
	s_nop 0
	v_cndmask_b32_e32 v24, 0, v24, vcc
	v_cmp_lt_i32_e32 vcc, -1, v8
	s_nop 1
	v_cndmask_b32_e32 v27, 0, v26, vcc
	v_cmp_lt_i32_e32 vcc, -1, v60
	s_nop 1
	v_cndmask_b32_e32 v26, 0, v76, vcc
	v_cmp_gt_i32_e32 vcc, 1, v35
	s_nop 1
	v_cndmask_b32_e32 v35, 0, v62, vcc
	v_cmp_gt_i32_e32 vcc, 1, v34
	s_nop 1
	v_cndmask_b32_e32 v34, 0, v61, vcc
	v_cmp_gt_i32_e32 vcc, 1, v8
	v_pk_add_f32 v[24:25], v[24:25], v[34:35]
	v_sub_u32_e32 v8, v98, v133
	v_cndmask_b32_e32 v61, 0, v63, vcc
	v_cmp_gt_i32_e32 vcc, 1, v60
	v_pk_mul_f32 v[20:21], v[20:21], v[24:25]
	v_sub_u32_e32 v24, v98, v130
	v_cndmask_b32_e32 v60, 0, v77, vcc
	v_pk_add_f32 v[26:27], v[26:27], v[60:61]
	v_sub_u32_e32 v25, v98, v131
	v_pk_mul_f32 v[22:23], v[22:23], v[26:27]
	v_sub_u32_e32 v26, v98, v132
	v_cvt_pk_bf16_f32 v23, v22, v23
	v_cvt_pk_bf16_f32 v22, v20, v21
	v_sub_u32_e32 v21, 0, v24
	global_store_dwordx2 v[84:85], v[22:23], off
	v_cvt_f32_u32_e32 v21, v21
	v_sub_u32_e32 v23, 0, v25
	v_cvt_f32_u32_e32 v22, v25
	v_cvt_f32_u32_e32 v23, v23
	v_mul_f32_e32 v21, v71, v21
	v_exp_f32_e32 v27, v21
	v_mul_f32_e32 v21, v95, v22
	v_mul_f32_e32 v22, v71, v23
	v_cvt_f32_u32_e32 v23, v26
	v_exp_f32_e32 v34, v22
	v_sub_u32_e32 v22, 0, v26
	v_cvt_f32_u32_e32 v20, v24
	v_cvt_f32_u32_e32 v22, v22
	v_cvt_f32_u32_e32 v35, v8
	v_mul_f32_e32 v23, v95, v23
	v_mul_f32_e32 v20, v95, v20
	v_exp_f32_e32 v21, v21
	v_exp_f32_e32 v60, v23
	v_mul_f32_e32 v22, v71, v22
	v_sub_u32_e32 v23, 0, v8
	v_exp_f32_e32 v20, v20
	v_exp_f32_e32 v61, v22
	v_mul_f32_e32 v22, v95, v35
	v_cvt_f32_u32_e32 v35, v23
	v_exp_f32_e32 v22, v22
	v_cmp_lt_i32_e32 vcc, -1, v25
	v_mul_f32_e32 v35, v71, v35
	s_nop 0
	v_cndmask_b32_e32 v21, 0, v21, vcc
	v_cmp_lt_i32_e32 vcc, -1, v24
	v_exp_f32_e32 v35, v35
	s_nop 0
	v_cndmask_b32_e32 v20, 0, v20, vcc
	v_cmp_lt_i32_e32 vcc, -1, v8
	s_nop 1
	v_cndmask_b32_e32 v23, 0, v22, vcc
	v_cmp_lt_i32_e32 vcc, -1, v26
	s_nop 1
	v_cndmask_b32_e32 v22, 0, v60, vcc
	v_cmp_gt_i32_e32 vcc, 1, v25
	s_nop 1
	v_cndmask_b32_e32 v25, 0, v34, vcc
	v_cmp_gt_i32_e32 vcc, 1, v24
	s_nop 1
	v_cndmask_b32_e32 v24, 0, v27, vcc
	v_cmp_gt_i32_e32 vcc, 1, v8
	v_pk_add_f32 v[20:21], v[20:21], v[24:25]
	v_sub_u32_e32 v8, v97, v123
	v_cndmask_b32_e32 v27, 0, v35, vcc
	v_cmp_gt_i32_e32 vcc, 1, v26
	v_pk_mul_f32 v[16:17], v[16:17], v[20:21]
	v_sub_u32_e32 v20, v97, v122
	v_cndmask_b32_e32 v26, 0, v61, vcc
	v_pk_add_f32 v[22:23], v[22:23], v[26:27]
	v_sub_u32_e32 v21, v97, v120
	v_pk_mul_f32 v[18:19], v[18:19], v[22:23]
	v_sub_u32_e32 v22, v97, v121
	v_cvt_pk_bf16_f32 v19, v18, v19
	v_cvt_pk_bf16_f32 v18, v16, v17
	v_sub_u32_e32 v17, 0, v20
	global_store_dwordx2 v[32:33], v[18:19], off
	global_store_dwordx2 v[58:59], v[56:57], off
	v_cvt_f32_u32_e32 v17, v17
	v_sub_u32_e32 v19, 0, v21
	v_cvt_f32_u32_e32 v18, v21
	v_cvt_f32_u32_e32 v19, v19
	v_mul_f32_e32 v17, v71, v17
	v_exp_f32_e32 v23, v17
	v_mul_f32_e32 v17, v95, v18
	v_mul_f32_e32 v18, v71, v19
	v_cvt_f32_u32_e32 v19, v22
	v_exp_f32_e32 v24, v18
	v_sub_u32_e32 v18, 0, v22
	v_cvt_f32_u32_e32 v16, v20
	v_cvt_f32_u32_e32 v18, v18
	v_cvt_f32_u32_e32 v25, v8
	v_mul_f32_e32 v19, v95, v19
	v_mul_f32_e32 v16, v95, v16
	v_exp_f32_e32 v17, v17
	v_exp_f32_e32 v26, v19
	v_mul_f32_e32 v18, v71, v18
	v_sub_u32_e32 v19, 0, v8
	v_exp_f32_e32 v16, v16
	v_exp_f32_e32 v27, v18
	v_mul_f32_e32 v18, v95, v25
	v_cvt_f32_u32_e32 v25, v19
	v_exp_f32_e32 v18, v18
	v_cmp_lt_i32_e32 vcc, -1, v21
	v_mul_f32_e32 v25, v71, v25
	s_nop 0
	v_cndmask_b32_e32 v17, 0, v17, vcc
	v_cmp_lt_i32_e32 vcc, -1, v20
	v_exp_f32_e32 v25, v25
	s_nop 0
	v_cndmask_b32_e32 v16, 0, v16, vcc
	v_cmp_lt_i32_e32 vcc, -1, v8
	s_nop 1
	v_cndmask_b32_e32 v19, 0, v18, vcc
	v_cmp_lt_i32_e32 vcc, -1, v22
	s_nop 1
	v_cndmask_b32_e32 v18, 0, v26, vcc
	v_cmp_gt_i32_e32 vcc, 1, v21
	s_nop 1
	v_cndmask_b32_e32 v21, 0, v24, vcc
	v_cmp_gt_i32_e32 vcc, 1, v20
	s_nop 1
	v_cndmask_b32_e32 v20, 0, v23, vcc
	v_cmp_gt_i32_e32 vcc, 1, v8
	v_pk_add_f32 v[16:17], v[16:17], v[20:21]
	v_sub_u32_e32 v8, v97, v100
	v_cndmask_b32_e32 v23, 0, v25, vcc
	v_cmp_gt_i32_e32 vcc, 1, v22
	v_pk_mul_f32 v[12:13], v[12:13], v[16:17]
	v_sub_u32_e32 v16, 0, v8
	v_cndmask_b32_e32 v22, 0, v27, vcc
	v_pk_add_f32 v[18:19], v[18:19], v[22:23]
	v_cvt_f32_u32_e32 v16, v16
	v_pk_mul_f32 v[14:15], v[14:15], v[18:19]
	v_cmp_lt_i32_e32 vcc, -1, v8
	v_cvt_pk_bf16_f32 v15, v14, v15
	v_cvt_pk_bf16_f32 v14, v12, v13
	global_store_dwordx2 v[44:45], v[14:15], off
	v_cvt_f32_u32_e32 v15, v8
	v_sub_u32_e32 v14, v97, v99
	v_sub_u32_e32 v13, 0, v14
	v_cvt_f32_u32_e32 v12, v14
	v_cvt_f32_u32_e32 v13, v13
	v_mul_f32_e32 v15, v95, v15
	v_exp_f32_e32 v15, v15
	v_mul_f32_e32 v12, v95, v12
	v_mul_f32_e32 v13, v71, v13
	v_exp_f32_e32 v12, v12
	v_exp_f32_e32 v17, v13
	v_cndmask_b32_e32 v13, 0, v15, vcc
	v_mul_f32_e32 v15, v71, v16
	v_exp_f32_e32 v15, v15
	v_cmp_lt_i32_e32 vcc, -1, v14
	v_sub_u32_e32 v16, v96, v100
	s_nop 0
	v_cndmask_b32_e32 v12, 0, v12, vcc
	v_cmp_gt_i32_e32 vcc, 1, v8
	v_mov_b32_e32 v8, v9
	v_mov_b32_e32 v9, v10
	v_cndmask_b32_e32 v15, 0, v15, vcc
	v_cmp_gt_i32_e32 vcc, 1, v14
	s_nop 1
	v_cndmask_b32_e32 v14, 0, v17, vcc
	v_pk_add_f32 v[12:13], v[12:13], v[14:15]
	v_sub_u32_e32 v14, v96, v102
	v_pk_mul_f32 v[8:9], v[8:9], v[12:13]
	v_sub_u32_e32 v12, v96, v101
	v_cvt_pk_bf16_f32 v9, v8, v9
	v_perm_b32 v8, v9, v124, s0
	v_alignbit_b32 v9, v11, v9, 16
	global_store_dwordx2 v[48:49], v[8:9], off
	global_store_dwordx2 v[30:31], v[28:29], off
	global_store_dwordx2 v[54:55], v[52:53], off
	global_store_dwordx2 v[50:51], v[46:47], off
	v_sub_u32_e32 v9, 0, v12
	v_sub_u32_e32 v13, v96, v99
	v_cvt_f32_u32_e32 v9, v9
	v_sub_u32_e32 v11, 0, v13
	v_cvt_f32_u32_e32 v10, v13
	v_cvt_f32_u32_e32 v11, v11
	v_mul_f32_e32 v9, v71, v9
	v_exp_f32_e32 v15, v9
	v_mul_f32_e32 v9, v95, v10
	v_mul_f32_e32 v10, v71, v11
	v_cvt_f32_u32_e32 v11, v16
	v_exp_f32_e32 v17, v10
	v_sub_u32_e32 v10, 0, v16
	v_cvt_f32_u32_e32 v8, v12
	v_cvt_f32_u32_e32 v10, v10
	v_cvt_f32_u32_e32 v18, v14
	v_mul_f32_e32 v11, v95, v11
	v_mul_f32_e32 v8, v95, v8
	v_exp_f32_e32 v9, v9
	v_exp_f32_e32 v19, v11
	v_mul_f32_e32 v10, v71, v10
	v_sub_u32_e32 v11, 0, v14
	v_exp_f32_e32 v8, v8
	v_exp_f32_e32 v20, v10
	v_mul_f32_e32 v10, v95, v18
	v_cvt_f32_u32_e32 v18, v11
	v_exp_f32_e32 v10, v10
	v_cmp_lt_i32_e32 vcc, -1, v13
	v_readlane_b32 s0, v181, 50
	v_mul_f32_e32 v18, v71, v18
	v_cndmask_b32_e32 v9, 0, v9, vcc
	v_cmp_lt_i32_e32 vcc, -1, v12
	v_exp_f32_e32 v18, v18
	s_add_i32 s9, s9, s0
	v_cndmask_b32_e32 v8, 0, v8, vcc
	v_cmp_lt_i32_e32 vcc, -1, v14
	s_cmpk_lt_i32 s8, 0x820
	s_nop 0
	v_cndmask_b32_e32 v11, 0, v10, vcc
	v_cmp_lt_i32_e32 vcc, -1, v16
	s_nop 1
	v_cndmask_b32_e32 v10, 0, v19, vcc
	v_cmp_gt_i32_e32 vcc, 1, v13
	s_nop 1
	v_cndmask_b32_e32 v13, 0, v17, vcc
	v_cmp_gt_i32_e32 vcc, 1, v12
	s_nop 1
	v_cndmask_b32_e32 v12, 0, v15, vcc
	v_cmp_gt_i32_e32 vcc, 1, v14
	v_pk_add_f32 v[8:9], v[8:9], v[12:13]
	s_nop 0
	v_cndmask_b32_e32 v15, 0, v18, vcc
	v_cmp_gt_i32_e32 vcc, 1, v16
	v_pk_mul_f32 v[4:5], v[4:5], v[8:9]
	s_nop 0
	v_cndmask_b32_e32 v14, 0, v20, vcc
	v_pk_add_f32 v[10:11], v[10:11], v[14:15]
	s_nop 0
	v_pk_mul_f32 v[6:7], v[6:7], v[10:11]
	s_nop 0
	v_cvt_pk_bf16_f32 v7, v6, v7
	v_cvt_pk_bf16_f32 v6, v4, v5
	v_lshl_add_u64 v[4:5], v[74:75], 0, v[38:39]
	global_store_dwordx2 v[4:5], v[6:7], off
	global_store_dwordx2 v[0:1], v[2:3], off
	s_cbranch_scc0 .LBB0_1308

.LBB0_1375:
	s_lshl_b32 s8, s22, 1
	v_add_u32_e32 v158, s8, v102
	v_add_u32_e32 v159, s8, v101
	v_add_u32_e32 v138, v158, v73
	v_add_u32_e32 v154, v159, v73
	ds_read_b128 v[126:129], v138
	ds_read_b128 v[130:133], v138 offset:2048
	ds_read_b128 v[134:137], v138 offset:4096
	ds_read_b128 v[138:141], v138 offset:6144
	ds_read_b128 v[142:145], v154 offset:32768
	ds_read_b128 v[146:149], v154 offset:34816
	ds_read_b128 v[150:153], v154 offset:36864
	ds_read_b128 v[154:157], v154 offset:38912
	s_setprio 0
	s_waitcnt lgkmcnt(0)
	v_mfma_f32_16x16x32_bf16 v[60:63], v[142:145], v[126:129], v[60:63]
	v_mfma_f32_16x16x32_bf16 v[56:59], v[146:149], v[126:129], v[56:59]
	v_mfma_f32_16x16x32_bf16 v[52:55], v[150:153], v[126:129], v[52:55]
	v_mfma_f32_16x16x32_bf16 v[48:51], v[154:157], v[126:129], v[48:51]
	v_mfma_f32_16x16x32_bf16 v[44:47], v[142:145], v[130:133], v[44:47]
	v_mfma_f32_16x16x32_bf16 v[40:43], v[146:149], v[130:133], v[40:43]
	v_mfma_f32_16x16x32_bf16 v[36:39], v[150:153], v[130:133], v[36:39]
	v_mfma_f32_16x16x32_bf16 v[32:35], v[154:157], v[130:133], v[32:35]
	v_mfma_f32_16x16x32_bf16 v[28:31], v[142:145], v[134:137], v[28:31]
	v_mfma_f32_16x16x32_bf16 v[24:27], v[146:149], v[134:137], v[24:27]
	v_mfma_f32_16x16x32_bf16 v[20:23], v[150:153], v[134:137], v[20:23]
	v_mfma_f32_16x16x32_bf16 v[16:19], v[154:157], v[134:137], v[16:19]
	v_mfma_f32_16x16x32_bf16 v[12:15], v[142:145], v[138:141], v[12:15]
	v_mfma_f32_16x16x32_bf16 v[8:11], v[146:149], v[138:141], v[8:11]
	v_mfma_f32_16x16x32_bf16 v[4:7], v[150:153], v[138:141], v[4:7]
	v_mfma_f32_16x16x32_bf16 v[0:3], v[154:157], v[138:141], v[0:3]
	s_setprio 1
	v_add_u32_e32 v138, v158, v77
	v_add_u32_e32 v154, v159, v77
	ds_read_b128 v[126:129], v138
	ds_read_b128 v[130:133], v138 offset:2048
	ds_read_b128 v[134:137], v138 offset:4096
	ds_read_b128 v[138:141], v138 offset:6144
	ds_read_b128 v[142:145], v154 offset:32768
	ds_read_b128 v[146:149], v154 offset:34816
	ds_read_b128 v[150:153], v154 offset:36864
	ds_read_b128 v[154:157], v154 offset:38912
	s_setprio 0
	s_waitcnt lgkmcnt(0)
	v_mfma_f32_16x16x32_bf16 v[60:63], v[142:145], v[126:129], v[60:63]
	v_mfma_f32_16x16x32_bf16 v[56:59], v[146:149], v[126:129], v[56:59]
	v_mfma_f32_16x16x32_bf16 v[52:55], v[150:153], v[126:129], v[52:55]
	v_mfma_f32_16x16x32_bf16 v[48:51], v[154:157], v[126:129], v[48:51]
	v_mfma_f32_16x16x32_bf16 v[44:47], v[142:145], v[130:133], v[44:47]
	v_mfma_f32_16x16x32_bf16 v[40:43], v[146:149], v[130:133], v[40:43]
	v_mfma_f32_16x16x32_bf16 v[36:39], v[150:153], v[130:133], v[36:39]
	v_mfma_f32_16x16x32_bf16 v[32:35], v[154:157], v[130:133], v[32:35]
	v_mfma_f32_16x16x32_bf16 v[28:31], v[142:145], v[134:137], v[28:31]
	v_mfma_f32_16x16x32_bf16 v[24:27], v[146:149], v[134:137], v[24:27]
	v_mfma_f32_16x16x32_bf16 v[20:23], v[150:153], v[134:137], v[20:23]
	v_mfma_f32_16x16x32_bf16 v[16:19], v[154:157], v[134:137], v[16:19]
	v_mfma_f32_16x16x32_bf16 v[12:15], v[142:145], v[138:141], v[12:15]
	v_mfma_f32_16x16x32_bf16 v[8:11], v[146:149], v[138:141], v[8:11]
	v_mfma_f32_16x16x32_bf16 v[4:7], v[150:153], v[138:141], v[4:7]
	v_mfma_f32_16x16x32_bf16 v[0:3], v[154:157], v[138:141], v[0:3]
	s_setprio 1
	s_waitcnt vmcnt(0)
	v_lshl_add_u64 v[84:85], v[84:85], 0, s[92:93]
	v_lshl_add_u64 v[86:87], v[86:87], 0, s[92:93]
	v_lshl_add_u64 v[88:89], v[88:89], 0, s[92:93]
	v_lshl_add_u64 v[90:91], v[90:91], 0, s[92:93]
	v_lshl_add_u64 v[92:93], v[92:93], 0, s[92:93]
	v_lshl_add_u64 v[94:95], v[94:95], 0, s[92:93]
	v_lshl_add_u64 v[96:97], v[96:97], 0, s[92:93]
	s_cmp_lg_u32 s18, s6
	v_lshl_add_u64 v[98:99], v[98:99], 0, s[92:93]
	s_waitcnt vmcnt(0)
	s_barrier
	s_cbranch_scc0 .LBB0_1380

.LBB0_1487:
	s_setprio 3
	s_and_b32 s6, s0, 0x2000
	s_xor_b32 s8, s6, 0x2000
	s_lshl_b32 s101, s8, 1
	s_add_u32 s101, s101, s100
	s_add_u32 m0, s101, 0x0
	s_nop 0
	global_load_lds_dwordx4 v[184:185], off
	s_add_u32 m0, s101, 0x1000
	v_lshl_add_u64 v[184:185], v[184:185], 0, vcc
	global_load_lds_dwordx4 v[186:187], off
	s_add_u32 m0, s101, 0x2000
	v_lshl_add_u64 v[186:187], v[186:187], 0, vcc
	global_load_lds_dwordx4 v[188:189], off
	s_add_u32 m0, s101, 0x3000
	v_lshl_add_u64 v[188:189], v[188:189], 0, vcc
	global_load_lds_dwordx4 v[190:191], off
	s_add_u32 m0, s101, 0x8000
	v_lshl_add_u64 v[190:191], v[190:191], 0, vcc
	global_load_lds_dwordx4 v[192:193], off
	s_add_u32 m0, s101, 0x9000
	v_lshl_add_u64 v[192:193], v[192:193], 0, vcc
	global_load_lds_dwordx4 v[194:195], off
	s_add_u32 m0, s101, 0xa000
	v_lshl_add_u64 v[194:195], v[194:195], 0, vcc
	global_load_lds_dwordx4 v[196:197], off
	s_add_u32 m0, s101, 0xb000
	v_lshl_add_u64 v[196:197], v[196:197], 0, vcc
	global_load_lds_dwordx4 v[198:199], off
	v_lshl_add_u64 v[198:199], v[198:199], 0, vcc
	s_lshl_b32 s6, s6, 1
	v_add_u32_e32 v148, s6, v92
	v_add_u32_e32 v149, s6, v71
	v_add_u32_e32 v128, v148, v98
	v_add_u32_e32 v144, v149, v98
	ds_read_b128 v[100:103], v128
	ds_read_b128 v[120:123], v128 offset:2048
	ds_read_b128 v[124:127], v128 offset:4096
	ds_read_b128 v[128:131], v128 offset:6144
	ds_read_b128 v[132:135], v144 offset:32768
	ds_read_b128 v[136:139], v144 offset:34816
	ds_read_b128 v[140:143], v144 offset:36864
	ds_read_b128 v[144:147], v144 offset:38912
	s_setprio 0
	s_waitcnt lgkmcnt(0)
	v_mfma_f32_16x16x32_bf16 v[60:63], v[132:135], v[100:103], v[60:63]
	v_mfma_f32_16x16x32_bf16 v[56:59], v[136:139], v[100:103], v[56:59]
	v_mfma_f32_16x16x32_bf16 v[52:55], v[140:143], v[100:103], v[52:55]
	v_mfma_f32_16x16x32_bf16 v[48:51], v[144:147], v[100:103], v[48:51]
	v_mfma_f32_16x16x32_bf16 v[44:47], v[132:135], v[120:123], v[44:47]
	v_mfma_f32_16x16x32_bf16 v[40:43], v[136:139], v[120:123], v[40:43]
	v_mfma_f32_16x16x32_bf16 v[36:39], v[140:143], v[120:123], v[36:39]
	v_mfma_f32_16x16x32_bf16 v[32:35], v[144:147], v[120:123], v[32:35]
	v_mfma_f32_16x16x32_bf16 v[28:31], v[132:135], v[124:127], v[28:31]
	v_mfma_f32_16x16x32_bf16 v[24:27], v[136:139], v[124:127], v[24:27]
	v_mfma_f32_16x16x32_bf16 v[20:23], v[140:143], v[124:127], v[20:23]
	v_mfma_f32_16x16x32_bf16 v[16:19], v[144:147], v[124:127], v[16:19]
	v_mfma_f32_16x16x32_bf16 v[12:15], v[132:135], v[128:131], v[12:15]
	v_mfma_f32_16x16x32_bf16 v[8:11], v[136:139], v[128:131], v[8:11]
	v_mfma_f32_16x16x32_bf16 v[4:7], v[140:143], v[128:131], v[4:7]
	v_mfma_f32_16x16x32_bf16 v[0:3], v[144:147], v[128:131], v[0:3]
	s_setprio 2
	v_add_u32_e32 v128, v148, v99
	v_add_u32_e32 v144, v149, v99
	ds_read_b128 v[100:103], v128
	ds_read_b128 v[120:123], v128 offset:2048
	ds_read_b128 v[124:127], v128 offset:4096
	ds_read_b128 v[128:131], v128 offset:6144
	ds_read_b128 v[132:135], v144 offset:32768
	ds_read_b128 v[136:139], v144 offset:34816
	ds_read_b128 v[140:143], v144 offset:36864
	ds_read_b128 v[144:147], v144 offset:38912
	s_setprio 0
	s_waitcnt lgkmcnt(0)
	v_mfma_f32_16x16x32_bf16 v[60:63], v[132:135], v[100:103], v[60:63]
	v_mfma_f32_16x16x32_bf16 v[56:59], v[136:139], v[100:103], v[56:59]
	v_mfma_f32_16x16x32_bf16 v[52:55], v[140:143], v[100:103], v[52:55]
	v_mfma_f32_16x16x32_bf16 v[48:51], v[144:147], v[100:103], v[48:51]
	v_mfma_f32_16x16x32_bf16 v[44:47], v[132:135], v[120:123], v[44:47]
	v_mfma_f32_16x16x32_bf16 v[40:43], v[136:139], v[120:123], v[40:43]
	v_mfma_f32_16x16x32_bf16 v[36:39], v[140:143], v[120:123], v[36:39]
	v_mfma_f32_16x16x32_bf16 v[32:35], v[144:147], v[120:123], v[32:35]
	v_mfma_f32_16x16x32_bf16 v[28:31], v[132:135], v[124:127], v[28:31]
	v_mfma_f32_16x16x32_bf16 v[24:27], v[136:139], v[124:127], v[24:27]
	v_mfma_f32_16x16x32_bf16 v[20:23], v[140:143], v[124:127], v[20:23]
	v_mfma_f32_16x16x32_bf16 v[16:19], v[144:147], v[124:127], v[16:19]
	v_mfma_f32_16x16x32_bf16 v[12:15], v[132:135], v[128:131], v[12:15]
	v_mfma_f32_16x16x32_bf16 v[8:11], v[136:139], v[128:131], v[8:11]
	v_mfma_f32_16x16x32_bf16 v[4:7], v[140:143], v[128:131], v[4:7]
	v_mfma_f32_16x16x32_bf16 v[0:3], v[144:147], v[128:131], v[0:3]
	s_setprio 1
	s_waitcnt vmcnt(0)
	s_add_u32 s36, s36, 0x80
	s_addc_u32 s37, s37, 0
	s_addk_i32 s0, 0x2000
	s_cmpk_lg_i32 s36, 0xf80
	s_waitcnt vmcnt(0)
	s_barrier
	s_cbranch_scc1 .LBB0_1487
	ds_read_b128 v[88:91], v94 offset:16384
	ds_read_b128 v[100:103], v94 offset:18432
	ds_read_b128 v[120:123], v94 offset:20480
	ds_read_b128 v[124:127], v94 offset:22528
	ds_read_b128 v[128:131], v95 offset:49152
	ds_read_b128 v[132:135], v95 offset:51200
	ds_read_b128 v[136:139], v95 offset:53248
	ds_read_b128 v[140:143], v95 offset:55296
	s_setprio 0
	s_waitcnt lgkmcnt(3)
	v_mfma_f32_16x16x32_bf16 v[60:63], v[128:131], v[88:91], v[60:63]
	s_waitcnt lgkmcnt(2)
	v_mfma_f32_16x16x32_bf16 v[56:59], v[132:135], v[88:91], v[56:59]
	s_waitcnt lgkmcnt(1)
	v_mfma_f32_16x16x32_bf16 v[52:55], v[136:139], v[88:91], v[52:55]
	s_waitcnt lgkmcnt(0)
	v_mfma_f32_16x16x32_bf16 v[48:51], v[140:143], v[88:91], v[48:51]
	v_mfma_f32_16x16x32_bf16 v[40:43], v[132:135], v[100:103], v[40:43]
	v_mfma_f32_16x16x32_bf16 v[36:39], v[136:139], v[100:103], v[36:39]
	v_mfma_f32_16x16x32_bf16 v[32:35], v[140:143], v[100:103], v[32:35]
	v_mfma_f32_16x16x32_bf16 v[20:23], v[136:139], v[120:123], v[20:23]
	v_mfma_f32_16x16x32_bf16 v[16:19], v[140:143], v[120:123], v[16:19]
	v_mfma_f32_16x16x32_bf16 v[0:3], v[140:143], v[124:127], v[0:3]
	v_mfma_f32_16x16x32_bf16 v[88:91], v[128:131], v[100:103], v[44:47]
	v_mfma_f32_16x16x32_bf16 v[100:103], v[128:131], v[120:123], v[28:31]
	v_mfma_f32_16x16x32_bf16 v[144:147], v[132:135], v[120:123], v[24:27]
	v_mfma_f32_16x16x32_bf16 v[120:123], v[128:131], v[124:127], v[12:15]
	v_mfma_f32_16x16x32_bf16 v[128:131], v[132:135], v[124:127], v[8:11]
	v_mfma_f32_16x16x32_bf16 v[132:135], v[136:139], v[124:127], v[4:7]
	s_setprio 1
	s_nop 1
	ds_read_b128 v[4:7], v96 offset:16384
	ds_read_b128 v[8:11], v96 offset:18432
	ds_read_b128 v[124:127], v96 offset:20480
	ds_read_b128 v[136:139], v96 offset:22528
	ds_read_b128 v[140:143], v97 offset:49152
	ds_read_b128 v[148:151], v97 offset:51200
	ds_read_b128 v[152:155], v97 offset:53248
	ds_read_b128 v[156:159], v97 offset:55296
	s_setprio 0
	s_waitcnt lgkmcnt(3)
	v_mfma_f32_16x16x32_bf16 v[60:63], v[140:143], v[4:7], v[60:63]
	s_waitcnt lgkmcnt(2)
	v_mfma_f32_16x16x32_bf16 v[44:47], v[148:151], v[4:7], v[56:59]
	s_waitcnt lgkmcnt(1)
	v_mfma_f32_16x16x32_bf16 v[28:31], v[152:155], v[4:7], v[52:55]
	s_waitcnt lgkmcnt(0)
	v_mfma_f32_16x16x32_bf16 v[12:15], v[156:159], v[4:7], v[48:51]
	v_mfma_f32_16x16x32_bf16 v[56:59], v[140:143], v[8:11], v[88:91]
	v_mfma_f32_16x16x32_bf16 v[40:43], v[148:151], v[8:11], v[40:43]
	v_mfma_f32_16x16x32_bf16 v[24:27], v[152:155], v[8:11], v[36:39]
	v_mfma_f32_16x16x32_bf16 v[8:11], v[156:159], v[8:11], v[32:35]
	v_mfma_f32_16x16x32_bf16 v[52:55], v[140:143], v[124:127], v[100:103]
	v_mfma_f32_16x16x32_bf16 v[36:39], v[148:151], v[124:127], v[144:147]
	v_mfma_f32_16x16x32_bf16 v[20:23], v[152:155], v[124:127], v[20:23]
	v_mfma_f32_16x16x32_bf16 v[4:7], v[156:159], v[124:127], v[16:19]
	v_mfma_f32_16x16x32_bf16 v[48:51], v[140:143], v[136:139], v[120:123]
	v_mfma_f32_16x16x32_bf16 v[32:35], v[148:151], v[136:139], v[128:131]
	v_mfma_f32_16x16x32_bf16 v[16:19], v[152:155], v[136:139], v[132:135]
	v_mfma_f32_16x16x32_bf16 v[0:3], v[156:159], v[136:139], v[0:3]
	s_setprio 1
	s_waitcnt vmcnt(0)
	s_cmpk_gt_i32 s1, 0x7f
	s_barrier
	s_cbranch_scc0 .LBB0_1490
	s_add_i32 s0, s24, 0xffffc000
	s_lshr_b32 s0, s0, 8
	v_readlane_b32 s6, v180, 24
	s_add_i32 s6, s0, s6
	s_and_b32 s10, s24, 0x80
	s_lshl_b64 s[8:9], s[6:7], 8
	v_readlane_b32 s36, v182, 19
	s_or_b32 s8, s8, s10
	s_mov_b64 s[10:11], 0
	v_readlane_b32 s37, v182, 20
	s_branch .LBB0_1491

.LBB0_1498:
	s_setprio 3
	s_and_b32 s10, s6, 0x2000
	s_xor_b32 s8, s10, 0x2000
	s_lshl_b32 s101, s8, 1
	s_add_u32 s101, s101, s100
	s_add_u32 m0, s101, 0x0
	s_nop 0
	global_load_lds_dwordx4 v[184:185], off
	s_add_u32 m0, s101, 0x1000
	v_lshl_add_u64 v[184:185], v[184:185], 0, vcc
	global_load_lds_dwordx4 v[186:187], off
	s_add_u32 m0, s101, 0x2000
	v_lshl_add_u64 v[186:187], v[186:187], 0, vcc
	global_load_lds_dwordx4 v[188:189], off
	s_add_u32 m0, s101, 0x3000
	v_lshl_add_u64 v[188:189], v[188:189], 0, vcc
	global_load_lds_dwordx4 v[190:191], off
	s_add_u32 m0, s101, 0x8000
	v_lshl_add_u64 v[190:191], v[190:191], 0, vcc
	global_load_lds_dwordx4 v[192:193], off
	s_add_u32 m0, s101, 0x9000
	v_lshl_add_u64 v[192:193], v[192:193], 0, vcc
	global_load_lds_dwordx4 v[194:195], off
	s_add_u32 m0, s101, 0xa000
	v_lshl_add_u64 v[194:195], v[194:195], 0, vcc
	global_load_lds_dwordx4 v[196:197], off
	s_add_u32 m0, s101, 0xb000
	v_lshl_add_u64 v[196:197], v[196:197], 0, vcc
	global_load_lds_dwordx4 v[198:199], off
	v_lshl_add_u64 v[198:199], v[198:199], 0, vcc
	s_lshl_b32 s8, s10, 1
	v_add_u32_e32 v68, s8, v84
	v_add_u32_e32 v140, s8, v83
	v_add_u32_e32 v120, v68, v90
	v_add_u32_e32 v136, v140, v90
	ds_read_b128 v[92:95], v120
	ds_read_b128 v[96:99], v120 offset:2048
	ds_read_b128 v[100:103], v120 offset:4096
	ds_read_b128 v[120:123], v120 offset:6144
	ds_read_b128 v[124:127], v136 offset:32768
	ds_read_b128 v[128:131], v136 offset:34816
	ds_read_b128 v[132:135], v136 offset:36864
	ds_read_b128 v[136:139], v136 offset:38912
	s_setprio 0
	s_waitcnt lgkmcnt(0)
	v_mfma_f32_16x16x32_bf16 v[60:63], v[124:127], v[92:95], v[60:63]
	v_mfma_f32_16x16x32_bf16 v[56:59], v[128:131], v[92:95], v[56:59]
	v_mfma_f32_16x16x32_bf16 v[52:55], v[132:135], v[92:95], v[52:55]
	v_mfma_f32_16x16x32_bf16 v[48:51], v[136:139], v[92:95], v[48:51]
	v_mfma_f32_16x16x32_bf16 v[44:47], v[124:127], v[96:99], v[44:47]
	v_mfma_f32_16x16x32_bf16 v[40:43], v[128:131], v[96:99], v[40:43]
	v_mfma_f32_16x16x32_bf16 v[36:39], v[132:135], v[96:99], v[36:39]
	v_mfma_f32_16x16x32_bf16 v[32:35], v[136:139], v[96:99], v[32:35]
	v_mfma_f32_16x16x32_bf16 v[28:31], v[124:127], v[100:103], v[28:31]
	v_mfma_f32_16x16x32_bf16 v[24:27], v[128:131], v[100:103], v[24:27]
	v_mfma_f32_16x16x32_bf16 v[20:23], v[132:135], v[100:103], v[20:23]
	v_mfma_f32_16x16x32_bf16 v[16:19], v[136:139], v[100:103], v[16:19]
	v_mfma_f32_16x16x32_bf16 v[12:15], v[124:127], v[120:123], v[12:15]
	v_mfma_f32_16x16x32_bf16 v[8:11], v[128:131], v[120:123], v[8:11]
	v_mfma_f32_16x16x32_bf16 v[4:7], v[132:135], v[120:123], v[4:7]
	v_mfma_f32_16x16x32_bf16 v[0:3], v[136:139], v[120:123], v[0:3]
	s_setprio 2
	v_add_u32_e32 v68, v68, v91
	ds_read_b128 v[92:95], v68
	ds_read_b128 v[96:99], v68 offset:2048
	ds_read_b128 v[100:103], v68 offset:4096
	ds_read_b128 v[120:123], v68 offset:6144
	v_add_u32_e32 v68, v140, v91
	ds_read_b128 v[124:127], v68 offset:32768
	ds_read_b128 v[128:131], v68 offset:34816
	ds_read_b128 v[132:135], v68 offset:36864
	ds_read_b128 v[136:139], v68 offset:38912
	s_setprio 0
	s_waitcnt lgkmcnt(0)
	v_mfma_f32_16x16x32_bf16 v[60:63], v[124:127], v[92:95], v[60:63]
	v_mfma_f32_16x16x32_bf16 v[56:59], v[128:131], v[92:95], v[56:59]
	v_mfma_f32_16x16x32_bf16 v[52:55], v[132:135], v[92:95], v[52:55]
	v_mfma_f32_16x16x32_bf16 v[48:51], v[136:139], v[92:95], v[48:51]
	v_mfma_f32_16x16x32_bf16 v[44:47], v[124:127], v[96:99], v[44:47]
	v_mfma_f32_16x16x32_bf16 v[40:43], v[128:131], v[96:99], v[40:43]
	v_mfma_f32_16x16x32_bf16 v[36:39], v[132:135], v[96:99], v[36:39]
	v_mfma_f32_16x16x32_bf16 v[32:35], v[136:139], v[96:99], v[32:35]
	v_mfma_f32_16x16x32_bf16 v[28:31], v[124:127], v[100:103], v[28:31]
	v_mfma_f32_16x16x32_bf16 v[24:27], v[128:131], v[100:103], v[24:27]
	v_mfma_f32_16x16x32_bf16 v[20:23], v[132:135], v[100:103], v[20:23]
	v_mfma_f32_16x16x32_bf16 v[16:19], v[136:139], v[100:103], v[16:19]
	v_mfma_f32_16x16x32_bf16 v[12:15], v[124:127], v[120:123], v[12:15]
	v_mfma_f32_16x16x32_bf16 v[8:11], v[128:131], v[120:123], v[8:11]
	v_mfma_f32_16x16x32_bf16 v[4:7], v[132:135], v[120:123], v[4:7]
	v_mfma_f32_16x16x32_bf16 v[0:3], v[136:139], v[120:123], v[0:3]
	s_setprio 1
	s_addk_i32 s6, 0x2000
	s_waitcnt vmcnt(0)
	s_add_u32 s36, s36, 0x80
	s_addc_u32 s37, s37, 0
	s_cmpk_lg_i32 s36, 0x780
	s_waitcnt vmcnt(0)
	s_barrier
	s_cbranch_scc1 .LBB0_1498
	ds_read_b128 v[78:81], v85 offset:55296
	ds_read_b128 v[92:95], v85 offset:53248
	ds_read_b128 v[96:99], v85 offset:51200
	ds_read_b128 v[100:103], v85 offset:49152
	ds_read_b128 v[120:123], v86 offset:22528
	ds_read_b128 v[124:127], v86 offset:20480
	ds_read_b128 v[128:131], v86 offset:18432
	ds_read_b128 v[132:135], v86 offset:16384
	s_setprio 0
	s_waitcnt lgkmcnt(0)
	v_mfma_f32_16x16x32_bf16 v[60:63], v[100:103], v[132:135], v[60:63]
	v_mfma_f32_16x16x32_bf16 v[56:59], v[96:99], v[132:135], v[56:59]
	v_mfma_f32_16x16x32_bf16 v[52:55], v[92:95], v[132:135], v[52:55]
	v_mfma_f32_16x16x32_bf16 v[48:51], v[78:81], v[132:135], v[48:51]
	v_mfma_f32_16x16x32_bf16 v[44:47], v[100:103], v[128:131], v[44:47]
	v_mfma_f32_16x16x32_bf16 v[40:43], v[96:99], v[128:131], v[40:43]
	v_mfma_f32_16x16x32_bf16 v[36:39], v[92:95], v[128:131], v[36:39]
	v_mfma_f32_16x16x32_bf16 v[32:35], v[78:81], v[128:131], v[32:35]
	v_mfma_f32_16x16x32_bf16 v[28:31], v[100:103], v[124:127], v[28:31]
	v_mfma_f32_16x16x32_bf16 v[24:27], v[96:99], v[124:127], v[24:27]
	v_mfma_f32_16x16x32_bf16 v[20:23], v[92:95], v[124:127], v[20:23]
	v_mfma_f32_16x16x32_bf16 v[16:19], v[78:81], v[124:127], v[16:19]
	v_mfma_f32_16x16x32_bf16 v[12:15], v[100:103], v[120:123], v[12:15]
	v_mfma_f32_16x16x32_bf16 v[8:11], v[96:99], v[120:123], v[8:11]
	v_mfma_f32_16x16x32_bf16 v[4:7], v[92:95], v[120:123], v[4:7]
	v_mfma_f32_16x16x32_bf16 v[0:3], v[78:81], v[120:123], v[0:3]
	s_setprio 1
	ds_read_b128 v[78:81], v87 offset:16384
	ds_read_b128 v[92:95], v87 offset:18432
	ds_read_b128 v[96:99], v87 offset:20480
	ds_read_b128 v[100:103], v87 offset:22528
	ds_read_b128 v[120:123], v88 offset:49152
	ds_read_b128 v[124:127], v88 offset:51200
	ds_read_b128 v[128:131], v88 offset:53248
	ds_read_b128 v[132:135], v88 offset:55296
	s_setprio 0
	s_waitcnt lgkmcnt(3)
	v_mfma_f32_16x16x32_bf16 v[60:63], v[120:123], v[78:81], v[60:63]
	s_waitcnt lgkmcnt(2)
	v_mfma_f32_16x16x32_bf16 v[56:59], v[124:127], v[78:81], v[56:59]
	s_waitcnt lgkmcnt(1)
	v_mfma_f32_16x16x32_bf16 v[52:55], v[128:131], v[78:81], v[52:55]
	s_waitcnt lgkmcnt(0)
	v_mfma_f32_16x16x32_bf16 v[48:51], v[132:135], v[78:81], v[48:51]
	v_mfma_f32_16x16x32_bf16 v[44:47], v[120:123], v[92:95], v[44:47]
	v_mfma_f32_16x16x32_bf16 v[40:43], v[124:127], v[92:95], v[40:43]
	v_mfma_f32_16x16x32_bf16 v[36:39], v[128:131], v[92:95], v[36:39]
	v_mfma_f32_16x16x32_bf16 v[32:35], v[132:135], v[92:95], v[32:35]
	v_mfma_f32_16x16x32_bf16 v[28:31], v[120:123], v[96:99], v[28:31]
	v_mfma_f32_16x16x32_bf16 v[24:27], v[124:127], v[96:99], v[24:27]
	v_mfma_f32_16x16x32_bf16 v[20:23], v[128:131], v[96:99], v[20:23]
	v_mfma_f32_16x16x32_bf16 v[16:19], v[132:135], v[96:99], v[16:19]
	v_mfma_f32_16x16x32_bf16 v[12:15], v[120:123], v[100:103], v[12:15]
	v_mfma_f32_16x16x32_bf16 v[8:11], v[124:127], v[100:103], v[8:11]
	v_mfma_f32_16x16x32_bf16 v[4:7], v[128:131], v[100:103], v[4:7]
	v_mfma_f32_16x16x32_bf16 v[0:3], v[132:135], v[100:103], v[0:3]
	s_setprio 1
	s_ashr_i32 s1, s1, 4
	s_mul_hi_i32 s6, s1, 0x4200000
	s_mul_i32 s1, s1, 0x4200000
	s_add_u32 s8, s90, s1
	v_add_u32_e32 v78, s20, v71
	s_addc_u32 s9, s91, s6
	s_and_b32 s1, s24, 0x780
	v_ashrrev_i32_e32 v79, 31, v78
	v_or_b32_e32 v68, s1, v89
	v_lshlrev_b64 v[80:81], 12, v[78:79]
	v_lshl_add_u64 v[80:81], s[8:9], 0, v[80:81]
	v_lshlrev_b32_e32 v68, 1, v68
	v_cvt_pk_bf16_f32 v60, v60, v61
	v_cvt_pk_bf16_f32 v61, v62, v63
	v_lshl_add_u64 v[62:63], v[80:81], 0, v[68:69]
	v_cvt_pk_bf16_f32 v48, v48, v49
	v_cvt_pk_bf16_f32 v49, v50, v51
	s_waitcnt vmcnt(0)
	s_barrier
	global_store_dwordx2 v[62:63], v[48:49], off offset:96
	v_or_b32_e32 v48, 16, v78
	v_ashrrev_i32_e32 v49, 31, v48
	v_lshlrev_b64 v[48:49], 12, v[48:49]
	v_lshl_add_u64 v[48:49], s[8:9], 0, v[48:49]
	v_cvt_pk_bf16_f32 v44, v44, v45
	v_cvt_pk_bf16_f32 v45, v46, v47
	v_lshl_add_u64 v[46:47], v[48:49], 0, v[68:69]
	v_cvt_pk_bf16_f32 v32, v32, v33
	v_cvt_pk_bf16_f32 v33, v34, v35
	global_store_dwordx2 v[46:47], v[32:33], off offset:96
	v_or_b32_e32 v32, 32, v78
	v_ashrrev_i32_e32 v33, 31, v32
	v_lshlrev_b64 v[32:33], 12, v[32:33]
	v_lshl_add_u64 v[32:33], s[8:9], 0, v[32:33]
	v_cvt_pk_bf16_f32 v28, v28, v29
	v_cvt_pk_bf16_f32 v29, v30, v31
	v_lshl_add_u64 v[30:31], v[32:33], 0, v[68:69]
	v_cvt_pk_bf16_f32 v16, v16, v17
	v_cvt_pk_bf16_f32 v17, v18, v19
	global_store_dwordx2 v[30:31], v[16:17], off offset:96
	v_or_b32_e32 v16, 48, v78
	v_ashrrev_i32_e32 v17, 31, v16
	v_lshlrev_b64 v[16:17], 12, v[16:17]
	v_lshl_add_u64 v[16:17], s[8:9], 0, v[16:17]
	s_add_i32 s0, s0, s84
	v_cvt_pk_bf16_f32 v56, v56, v57
	v_cvt_pk_bf16_f32 v57, v58, v59
	v_cvt_pk_bf16_f32 v52, v52, v53
	v_cvt_pk_bf16_f32 v53, v54, v55
	v_cvt_pk_bf16_f32 v40, v40, v41
	v_cvt_pk_bf16_f32 v41, v42, v43
	v_cvt_pk_bf16_f32 v36, v36, v37
	v_cvt_pk_bf16_f32 v37, v38, v39
	v_cvt_pk_bf16_f32 v24, v24, v25
	v_cvt_pk_bf16_f32 v25, v26, v27
	v_cvt_pk_bf16_f32 v20, v20, v21
	v_cvt_pk_bf16_f32 v21, v22, v23
	v_cvt_pk_bf16_f32 v12, v12, v13
	v_cvt_pk_bf16_f32 v13, v14, v15
	v_lshl_add_u64 v[14:15], v[16:17], 0, v[68:69]
	v_cvt_pk_bf16_f32 v8, v8, v9
	v_cvt_pk_bf16_f32 v9, v10, v11
	v_cvt_pk_bf16_f32 v4, v4, v5
	v_cvt_pk_bf16_f32 v5, v6, v7
	v_cvt_pk_bf16_f32 v0, v0, v1
	v_cvt_pk_bf16_f32 v1, v2, v3
	s_cmpk_lt_i32 s0, 0x18c0
	global_store_dwordx2 v[62:63], v[60:61], off
	global_store_dwordx2 v[62:63], v[56:57], off offset:32
	global_store_dwordx2 v[62:63], v[52:53], off offset:64
	global_store_dwordx2 v[46:47], v[44:45], off
	global_store_dwordx2 v[46:47], v[40:41], off offset:32
	global_store_dwordx2 v[46:47], v[36:37], off offset:64
	global_store_dwordx2 v[30:31], v[28:29], off
	global_store_dwordx2 v[30:31], v[24:25], off offset:32
	global_store_dwordx2 v[30:31], v[20:21], off offset:64
	global_store_dwordx2 v[14:15], v[12:13], off
	global_store_dwordx2 v[14:15], v[8:9], off offset:32
	global_store_dwordx2 v[14:15], v[4:5], off offset:64
	global_store_dwordx2 v[14:15], v[0:1], off offset:96
	s_cbranch_scc1 .LBB0_1497

.LBB0_1654:
	s_and_b32 s0, s8, 7
	s_mulk_i32 s0, 0x108
	s_ashr_i32 s6, s8, 3
	s_add_i32 s1, s0, s6
	s_bfe_u32 s9, s1, 0x30001
	s_lshl_b32 s6, s6, 7
	s_and_b32 s10, s6, 0x80
	s_lshl_b32 s6, s9, 15
	v_lshl_add_u64 v[0:1], v[60:61], 0, s[6:7]
	v_readfirstlane_b32 s6, v84
	v_add_u32_e32 v6, 0x1000, v84
	s_ashr_i32 s0, s1, 4
	s_mov_b32 m0, s6
	v_readfirstlane_b32 s6, v6
	v_add_u32_e32 v6, 0x2000, v84
	s_ashr_i32 s1, s0, 31
	global_load_lds_dwordx4 v[0:1], off
	v_lshl_add_u64 v[4:5], v[0:1], 0, s[20:21]
	s_mov_b32 m0, s6
	v_readfirstlane_b32 s6, v6
	v_add_u32_e32 v6, 0x3000, v84
	s_lshl_b64 s[12:13], s[0:1], 11
	s_lshl_b32 s1, s9, 8
	global_load_lds_dwordx4 v[4:5], off
	v_lshl_add_u64 v[4:5], v[0:1], 0, s[24:25]
	s_mov_b32 m0, s6
	v_readfirstlane_b32 s6, v6
	s_or_b32 s11, s12, s1
	global_load_lds_dwordx4 v[4:5], off
	v_lshl_add_u64 v[4:5], v[0:1], 0, s[36:37]
	s_mov_b32 m0, s6
	s_or_b32 s12, s11, s10
	global_load_lds_dwordx4 v[4:5], off
	v_add_u32_e32 v4, 0x8000, v84
	s_lshl_b64 s[12:13], s[12:13], 8
	v_readfirstlane_b32 s6, v4
	v_add_u32_e32 v6, 0x9000, v84
	v_lshl_add_u64 v[2:3], v[62:63], 0, s[12:13]
	s_mov_b32 m0, s6
	v_readfirstlane_b32 s6, v6
	v_add_u32_e32 v6, 0xa000, v84
	global_load_lds_dwordx4 v[2:3], off
	v_lshl_add_u64 v[4:5], v[2:3], 0, s[20:21]
	s_mov_b32 m0, s6
	v_readfirstlane_b32 s6, v6
	v_add_u32_e32 v6, 0xb000, v84
	global_load_lds_dwordx4 v[4:5], off
	v_lshl_add_u64 v[4:5], v[2:3], 0, s[24:25]
	s_mov_b32 m0, s6
	v_readfirstlane_b32 s6, v6
	v_add_u32_e32 v16, 0x4000, v84
	global_load_lds_dwordx4 v[4:5], off
	v_lshl_add_u64 v[4:5], v[2:3], 0, s[36:37]
	s_mov_b32 m0, s6
	v_readfirstlane_b32 s6, v16
	global_load_lds_dwordx4 v[4:5], off
	v_lshl_add_u64 v[10:11], v[0:1], 0, s[38:39]
	v_lshl_add_u64 v[12:13], v[0:1], 0, s[40:41]
	v_lshl_add_u64 v[14:15], v[0:1], 0, s[42:43]
	v_lshl_add_u64 v[0:1], v[0:1], 0, s[92:93]
	s_mov_b32 m0, s6
	s_waitcnt vmcnt(0)
	s_waitcnt vmcnt(0) lgkmcnt(0)
	s_barrier
	global_load_lds_dwordx4 v[0:1], off
	v_add_u32_e32 v0, 0x5000, v84
	v_lshl_add_u64 v[4:5], v[2:3], 0, s[38:39]
	v_readfirstlane_b32 s6, v0
	v_add_u32_e32 v0, 0x6000, v84
	s_mov_b32 m0, s6
	v_readfirstlane_b32 s6, v0
	v_add_u32_e32 v0, 0x7000, v84
	global_load_lds_dwordx4 v[14:15], off
	s_mov_b32 m0, s6
	v_readfirstlane_b32 s6, v0
	v_add_u32_e32 v0, 0xc000, v84
	global_load_lds_dwordx4 v[12:13], off
	s_mov_b32 m0, s6
	v_readfirstlane_b32 s6, v0
	v_add_u32_e32 v0, 0xd000, v84
	v_lshl_add_u64 v[6:7], v[2:3], 0, s[40:41]
	v_lshl_add_u64 v[8:9], v[2:3], 0, s[42:43]
	v_lshl_add_u64 v[2:3], v[2:3], 0, s[92:93]
	global_load_lds_dwordx4 v[10:11], off
	s_mov_b32 m0, s6
	v_readfirstlane_b32 s6, v0
	v_add_u32_e32 v0, 0xe000, v84
	global_load_lds_dwordx4 v[2:3], off
	s_mov_b32 m0, s6
	v_readfirstlane_b32 s6, v0
	v_add_u32_e32 v0, 0xf000, v84
	global_load_lds_dwordx4 v[8:9], off
	s_mov_b32 m0, s6
	v_readfirstlane_b32 s6, v0
	global_load_lds_dwordx4 v[6:7], off
	s_mov_b32 m0, s6
	s_nop 0
	global_load_lds_dwordx4 v[4:5], off
	ds_read_b128 v[0:3], v79
	ds_read_b128 v[4:7], v79 offset:2048
	ds_read_b128 v[8:11], v79 offset:4096
	ds_read_b128 v[12:15], v79 offset:6144
	ds_read_b128 v[16:19], v78 offset:32768
	ds_read_b128 v[20:23], v78 offset:34816
	ds_read_b128 v[24:27], v78 offset:36864
	ds_read_b128 v[28:31], v78 offset:38912
	s_setprio 0
	s_waitcnt lgkmcnt(0)
	v_mfma_f32_16x16x32_bf16 v[32:35], v[16:19], v[0:3], 0
	v_mfma_f32_16x16x32_bf16 v[36:39], v[20:23], v[0:3], 0
	v_mfma_f32_16x16x32_bf16 v[40:43], v[24:27], v[0:3], 0
	v_mfma_f32_16x16x32_bf16 v[0:3], v[28:31], v[0:3], 0
	v_mfma_f32_16x16x32_bf16 v[44:47], v[16:19], v[4:7], 0
	v_mfma_f32_16x16x32_bf16 v[48:51], v[20:23], v[4:7], 0
	v_mfma_f32_16x16x32_bf16 v[52:55], v[24:27], v[4:7], 0
	v_mfma_f32_16x16x32_bf16 v[4:7], v[28:31], v[4:7], 0
	v_mfma_f32_16x16x32_bf16 v[56:59], v[16:19], v[8:11], 0
	v_mfma_f32_16x16x32_bf16 v[72:75], v[20:23], v[8:11], 0
	v_mfma_f32_16x16x32_bf16 v[86:89], v[24:27], v[8:11], 0
	v_mfma_f32_16x16x32_bf16 v[8:11], v[28:31], v[8:11], 0
	v_mfma_f32_16x16x32_bf16 v[16:19], v[16:19], v[12:15], 0
	v_mfma_f32_16x16x32_bf16 v[20:23], v[20:23], v[12:15], 0
	v_mfma_f32_16x16x32_bf16 v[24:27], v[24:27], v[12:15], 0
	v_mfma_f32_16x16x32_bf16 v[12:15], v[28:31], v[12:15], 0
	s_setprio 1
	ds_read_b128 v[28:31], v80
	ds_read_b128 v[90:93], v80 offset:2048
	ds_read_b128 v[94:97], v80 offset:4096
	ds_read_b128 v[98:101], v80 offset:6144
	ds_read_b128 v[120:123], v81 offset:32768
	ds_read_b128 v[124:127], v81 offset:34816
	ds_read_b128 v[128:131], v81 offset:36864
	ds_read_b128 v[132:135], v81 offset:38912
	s_setprio 0
	s_waitcnt lgkmcnt(0)
	v_mfma_f32_16x16x32_bf16 v[32:35], v[120:123], v[28:31], v[32:35]
	v_mfma_f32_16x16x32_bf16 v[36:39], v[124:127], v[28:31], v[36:39]
	v_mfma_f32_16x16x32_bf16 v[40:43], v[128:131], v[28:31], v[40:43]
	v_mfma_f32_16x16x32_bf16 v[0:3], v[132:135], v[28:31], v[0:3]
	v_mfma_f32_16x16x32_bf16 v[28:31], v[120:123], v[90:93], v[44:47]
	v_mfma_f32_16x16x32_bf16 v[44:47], v[124:127], v[90:93], v[48:51]
	v_mfma_f32_16x16x32_bf16 v[48:51], v[128:131], v[90:93], v[52:55]
	v_mfma_f32_16x16x32_bf16 v[4:7], v[132:135], v[90:93], v[4:7]
	v_mfma_f32_16x16x32_bf16 v[52:55], v[120:123], v[94:97], v[56:59]
	v_mfma_f32_16x16x32_bf16 v[56:59], v[124:127], v[94:97], v[72:75]
	v_mfma_f32_16x16x32_bf16 v[72:75], v[128:131], v[94:97], v[86:89]
	v_mfma_f32_16x16x32_bf16 v[8:11], v[132:135], v[94:97], v[8:11]
	v_mfma_f32_16x16x32_bf16 v[16:19], v[120:123], v[98:101], v[16:19]
	v_mfma_f32_16x16x32_bf16 v[20:23], v[124:127], v[98:101], v[20:23]
	v_mfma_f32_16x16x32_bf16 v[24:27], v[128:131], v[98:101], v[24:27]
	v_mfma_f32_16x16x32_bf16 v[12:15], v[132:135], v[98:101], v[12:15]
	s_setprio 1
	s_waitcnt vmcnt(0)
	s_waitcnt vmcnt(0)
	s_barrier
	ds_read_b128 v[86:89], v78 offset:55296
	ds_read_b128 v[90:93], v78 offset:53248
	ds_read_b128 v[94:97], v78 offset:51200
	ds_read_b128 v[98:101], v78 offset:49152
	ds_read_b128 v[120:123], v79 offset:22528
	ds_read_b128 v[124:127], v79 offset:20480
	ds_read_b128 v[128:131], v79 offset:18432
	ds_read_b128 v[132:135], v79 offset:16384
	s_setprio 0
	s_waitcnt lgkmcnt(0)
	v_mfma_f32_16x16x32_bf16 v[32:35], v[98:101], v[132:135], v[32:35]
	v_mfma_f32_16x16x32_bf16 v[36:39], v[94:97], v[132:135], v[36:39]
	v_mfma_f32_16x16x32_bf16 v[40:43], v[90:93], v[132:135], v[40:43]
	v_mfma_f32_16x16x32_bf16 v[0:3], v[86:89], v[132:135], v[0:3]
	v_mfma_f32_16x16x32_bf16 v[28:31], v[98:101], v[128:131], v[28:31]
	v_mfma_f32_16x16x32_bf16 v[132:135], v[94:97], v[128:131], v[44:47]
	v_mfma_f32_16x16x32_bf16 v[136:139], v[90:93], v[128:131], v[48:51]
	v_mfma_f32_16x16x32_bf16 v[4:7], v[86:89], v[128:131], v[4:7]
	v_mfma_f32_16x16x32_bf16 v[128:131], v[98:101], v[124:127], v[52:55]
	v_mfma_f32_16x16x32_bf16 v[140:143], v[94:97], v[124:127], v[56:59]
	v_mfma_f32_16x16x32_bf16 v[72:75], v[90:93], v[124:127], v[72:75]
	v_mfma_f32_16x16x32_bf16 v[8:11], v[86:89], v[124:127], v[8:11]
	v_mfma_f32_16x16x32_bf16 v[98:101], v[98:101], v[120:123], v[16:19]
	v_mfma_f32_16x16x32_bf16 v[94:97], v[94:97], v[120:123], v[20:23]
	v_mfma_f32_16x16x32_bf16 v[90:93], v[90:93], v[120:123], v[24:27]
	v_mfma_f32_16x16x32_bf16 v[86:89], v[86:89], v[120:123], v[12:15]
	s_setprio 1
	s_nop 1
	ds_read_b128 v[12:15], v80 offset:16384
	ds_read_b128 v[16:19], v80 offset:18432
	ds_read_b128 v[120:123], v80 offset:20480
	ds_read_b128 v[124:127], v80 offset:22528
	ds_read_b128 v[144:147], v81 offset:49152
	ds_read_b128 v[148:151], v81 offset:51200
	ds_read_b128 v[152:155], v81 offset:53248
	ds_read_b128 v[156:159], v81 offset:55296
	s_setprio 0
	s_waitcnt lgkmcnt(3)
	v_mfma_f32_16x16x32_bf16 v[160:163], v[144:147], v[12:15], v[32:35]
	s_waitcnt lgkmcnt(2)
	v_mfma_f32_16x16x32_bf16 v[56:59], v[148:151], v[12:15], v[36:39]
	s_waitcnt lgkmcnt(1)
	v_mfma_f32_16x16x32_bf16 v[52:55], v[152:155], v[12:15], v[40:43]
	s_waitcnt lgkmcnt(0)
	v_mfma_f32_16x16x32_bf16 v[48:51], v[156:159], v[12:15], v[0:3]
	v_mfma_f32_16x16x32_bf16 v[44:47], v[144:147], v[16:19], v[28:31]
	v_mfma_f32_16x16x32_bf16 v[40:43], v[148:151], v[16:19], v[132:135]
	v_mfma_f32_16x16x32_bf16 v[36:39], v[152:155], v[16:19], v[136:139]
	v_mfma_f32_16x16x32_bf16 v[32:35], v[156:159], v[16:19], v[4:7]
	v_mfma_f32_16x16x32_bf16 v[28:31], v[144:147], v[120:123], v[128:131]
	v_mfma_f32_16x16x32_bf16 v[24:27], v[148:151], v[120:123], v[140:143]
	v_mfma_f32_16x16x32_bf16 v[20:23], v[152:155], v[120:123], v[72:75]
	v_mfma_f32_16x16x32_bf16 v[16:19], v[156:159], v[120:123], v[8:11]
	v_mfma_f32_16x16x32_bf16 v[12:15], v[144:147], v[124:127], v[98:101]
	v_mfma_f32_16x16x32_bf16 v[8:11], v[148:151], v[124:127], v[94:97]
	v_mfma_f32_16x16x32_bf16 v[4:7], v[152:155], v[124:127], v[90:93]
	v_mfma_f32_16x16x32_bf16 v[0:3], v[156:159], v[124:127], v[86:89]
	s_setprio 1
	s_lshl_b32 s0, s0, 7
	v_add_u32_e32 v74, s0, v71
	v_or_b32_e32 v68, s10, v76
	v_ashrrev_i32_e32 v75, 31, v74
	v_or_b32_e32 v86, s1, v68
	v_lshlrev_b64 v[74:75], 11, v[74:75]
	v_lshl_add_u32 v72, s9, 7, v71
	v_or_b32_e32 v88, v74, v86
	v_mov_b32_e32 v89, v75
	v_ashrrev_i32_e32 v73, 31, v72
	v_lshlrev_b64 v[88:89], 1, v[88:89]
	v_lshl_add_u64 v[72:73], v[72:73], 2, s[68:69]
	v_lshl_add_u64 v[90:91], s[90:91], 0, v[88:89]
	v_lshl_add_u64 v[88:89], s[86:87], 0, v[88:89]
	s_waitcnt vmcnt(0)
	s_barrier
	global_load_dword v68, v[72:73], off
	global_load_dwordx2 v[92:93], v[90:91], off
	s_nop 0
	global_load_dwordx2 v[88:89], v[88:89], off
	s_add_i32 s8, s8, s84
	s_cmpk_lt_i32 s8, 0x840
	s_waitcnt vmcnt(2)
	v_pk_add_f32 v[102:103], v[162:163], v[68:69] op_sel_hi:[1,0]
	s_waitcnt vmcnt(0)
	v_and_b32_e32 v95, 0xffff0000, v89
	v_lshlrev_b32_e32 v94, 16, v89
	v_and_b32_e32 v89, 0xffff0000, v88
	v_lshlrev_b32_e32 v88, 16, v88
	v_mul_f32_e32 v85, 0xbfb8aa3b, v88
	v_exp_f32_e32 v85, v85
	v_and_b32_e32 v101, 0xffff0000, v93
	v_lshlrev_b32_e32 v100, 16, v93
	v_and_b32_e32 v93, 0xffff0000, v92
	v_add_f32_e32 v85, 1.0, v85
	v_rcp_f32_e32 v96, v85
	v_mul_f32_e32 v85, 0xbfb8aa3b, v89
	v_exp_f32_e32 v85, v85
	v_lshlrev_b32_e32 v92, 16, v92
	v_pk_add_f32 v[120:121], v[160:161], v[68:69] op_sel_hi:[1,0]
	v_pk_mul_f32 v[100:101], v[102:103], v[100:101]
	v_add_f32_e32 v85, 1.0, v85
	v_rcp_f32_e32 v97, v85
	v_mul_f32_e32 v85, 0xbfb8aa3b, v94
	v_exp_f32_e32 v85, v85
	v_pk_mul_f32 v[92:93], v[120:121], v[92:93]
	v_pk_mul_f32 v[88:89], v[96:97], v[88:89]
	v_pk_add_f32 v[58:59], v[58:59], v[68:69] op_sel_hi:[1,0]
	v_add_f32_e32 v85, 1.0, v85
	v_rcp_f32_e32 v98, v85
	v_mul_f32_e32 v85, 0xbfb8aa3b, v95
	v_exp_f32_e32 v85, v85
	v_pk_mul_f32 v[88:89], v[92:93], v[88:89]
	v_pk_add_f32 v[56:57], v[56:57], v[68:69] op_sel_hi:[1,0]
	v_cvt_pk_bf16_f32 v88, v88, v89
	v_add_f32_e32 v85, 1.0, v85
	v_rcp_f32_e32 v99, v85
	v_or_b32_e32 v85, 16, v86
	v_pk_add_f32 v[54:55], v[54:55], v[68:69] op_sel_hi:[1,0]
	v_pk_add_f32 v[52:53], v[52:53], v[68:69] op_sel_hi:[1,0]
	v_pk_mul_f32 v[94:95], v[98:99], v[94:95]
	v_pk_add_f32 v[50:51], v[50:51], v[68:69] op_sel_hi:[1,0]
	v_pk_mul_f32 v[94:95], v[100:101], v[94:95]
	v_pk_add_f32 v[48:49], v[48:49], v[68:69] op_sel_hi:[1,0]
	v_cvt_pk_bf16_f32 v89, v94, v95
	global_store_dwordx2 v[90:91], v[88:89], off
	v_or_b32_e32 v88, v74, v85
	v_mov_b32_e32 v89, v75
	v_lshlrev_b64 v[88:89], 1, v[88:89]
	v_lshl_add_u64 v[90:91], s[90:91], 0, v[88:89]
	v_lshl_add_u64 v[88:89], s[86:87], 0, v[88:89]
	global_load_dwordx2 v[92:93], v[90:91], off
	s_nop 0
	global_load_dwordx2 v[88:89], v[88:89], off
	s_waitcnt vmcnt(1)
	v_and_b32_e32 v101, 0xffff0000, v93
	s_waitcnt vmcnt(0)
	v_and_b32_e32 v95, 0xffff0000, v89
	v_lshlrev_b32_e32 v94, 16, v89
	v_and_b32_e32 v89, 0xffff0000, v88
	v_lshlrev_b32_e32 v88, 16, v88
	v_mul_f32_e32 v87, 0xbfb8aa3b, v88
	v_exp_f32_e32 v87, v87
	v_lshlrev_b32_e32 v100, 16, v93
	v_and_b32_e32 v93, 0xffff0000, v92
	v_lshlrev_b32_e32 v92, 16, v92
	v_add_f32_e32 v87, 1.0, v87
	v_rcp_f32_e32 v96, v87
	v_mul_f32_e32 v87, 0xbfb8aa3b, v89
	v_exp_f32_e32 v87, v87
	v_pk_mul_f32 v[56:57], v[56:57], v[92:93]
	v_pk_mul_f32 v[58:59], v[58:59], v[100:101]
	v_add_f32_e32 v87, 1.0, v87
	v_rcp_f32_e32 v97, v87
	v_mul_f32_e32 v87, 0xbfb8aa3b, v94
	v_exp_f32_e32 v87, v87
	v_pk_mul_f32 v[88:89], v[96:97], v[88:89]
	s_nop 0
	v_pk_mul_f32 v[56:57], v[56:57], v[88:89]
	v_add_f32_e32 v87, 1.0, v87
	v_rcp_f32_e32 v98, v87
	v_mul_f32_e32 v87, 0xbfb8aa3b, v95
	v_exp_f32_e32 v87, v87
	v_cvt_pk_bf16_f32 v56, v56, v57
	v_add_f32_e32 v87, 1.0, v87
	v_rcp_f32_e32 v99, v87
	s_nop 0
	v_pk_mul_f32 v[92:93], v[98:99], v[94:95]
	s_nop 0
	v_pk_mul_f32 v[58:59], v[58:59], v[92:93]
	s_nop 0
	v_cvt_pk_bf16_f32 v57, v58, v59
	global_store_dwordx2 v[90:91], v[56:57], off
	v_or_b32_e32 v56, 32, v86
	v_or_b32_e32 v58, v74, v56
	v_mov_b32_e32 v59, v75
	v_lshlrev_b64 v[58:59], 1, v[58:59]
	v_lshl_add_u64 v[88:89], s[90:91], 0, v[58:59]
	v_lshl_add_u64 v[58:59], s[86:87], 0, v[58:59]
	global_load_dwordx2 v[90:91], v[88:89], off
	s_nop 0
	global_load_dwordx2 v[58:59], v[58:59], off
	s_waitcnt vmcnt(1)
	v_and_b32_e32 v99, 0xffff0000, v91
	s_waitcnt vmcnt(0)
	v_and_b32_e32 v93, 0xffff0000, v59
	v_lshlrev_b32_e32 v92, 16, v59
	v_and_b32_e32 v59, 0xffff0000, v58
	v_lshlrev_b32_e32 v58, 16, v58
	v_mul_f32_e32 v57, 0xbfb8aa3b, v58
	v_exp_f32_e32 v57, v57
	v_lshlrev_b32_e32 v98, 16, v91
	v_and_b32_e32 v91, 0xffff0000, v90
	v_lshlrev_b32_e32 v90, 16, v90
	v_add_f32_e32 v57, 1.0, v57
	v_rcp_f32_e32 v94, v57
	v_mul_f32_e32 v57, 0xbfb8aa3b, v59
	v_exp_f32_e32 v57, v57
	v_pk_mul_f32 v[52:53], v[52:53], v[90:91]
	v_pk_mul_f32 v[54:55], v[54:55], v[98:99]
	v_add_f32_e32 v57, 1.0, v57
	v_rcp_f32_e32 v95, v57
	v_mul_f32_e32 v57, 0xbfb8aa3b, v92
	v_exp_f32_e32 v57, v57
	v_pk_mul_f32 v[58:59], v[94:95], v[58:59]
	s_nop 0
	v_pk_mul_f32 v[52:53], v[52:53], v[58:59]
	v_add_f32_e32 v57, 1.0, v57
	v_rcp_f32_e32 v96, v57
	v_mul_f32_e32 v57, 0xbfb8aa3b, v93
	v_exp_f32_e32 v57, v57
	v_cvt_pk_bf16_f32 v52, v52, v53
	v_add_f32_e32 v57, 1.0, v57
	v_rcp_f32_e32 v97, v57
	s_nop 0
	v_pk_mul_f32 v[90:91], v[96:97], v[92:93]
	s_nop 0
	v_pk_mul_f32 v[54:55], v[54:55], v[90:91]
	s_nop 0
	v_cvt_pk_bf16_f32 v53, v54, v55
	global_store_dwordx2 v[88:89], v[52:53], off
	v_or_b32_e32 v52, 48, v86
	v_or_b32_e32 v74, v74, v52
	v_lshlrev_b64 v[54:55], 1, v[74:75]
	v_lshl_add_u64 v[58:59], s[90:91], 0, v[54:55]
	v_lshl_add_u64 v[54:55], s[86:87], 0, v[54:55]
	global_load_dwordx2 v[74:75], v[58:59], off
	s_nop 0
	global_load_dwordx2 v[54:55], v[54:55], off
	s_waitcnt vmcnt(1)
	v_and_b32_e32 v95, 0xffff0000, v75
	s_waitcnt vmcnt(0)
	v_and_b32_e32 v89, 0xffff0000, v55
	v_lshlrev_b32_e32 v88, 16, v55
	v_and_b32_e32 v55, 0xffff0000, v54
	v_lshlrev_b32_e32 v54, 16, v54
	v_mul_f32_e32 v53, 0xbfb8aa3b, v54
	v_exp_f32_e32 v53, v53
	v_lshlrev_b32_e32 v94, 16, v75
	v_and_b32_e32 v75, 0xffff0000, v74
	v_lshlrev_b32_e32 v74, 16, v74
	v_add_f32_e32 v53, 1.0, v53
	v_rcp_f32_e32 v90, v53
	v_mul_f32_e32 v53, 0xbfb8aa3b, v55
	v_exp_f32_e32 v53, v53
	v_pk_mul_f32 v[48:49], v[48:49], v[74:75]
	v_pk_mul_f32 v[50:51], v[50:51], v[94:95]
	v_add_f32_e32 v53, 1.0, v53
	v_rcp_f32_e32 v91, v53
	v_mul_f32_e32 v53, 0xbfb8aa3b, v88
	v_exp_f32_e32 v53, v53
	v_pk_mul_f32 v[54:55], v[90:91], v[54:55]
	s_nop 0
	v_pk_mul_f32 v[48:49], v[48:49], v[54:55]
	v_add_f32_e32 v53, 1.0, v53
	v_rcp_f32_e32 v92, v53
	v_mul_f32_e32 v53, 0xbfb8aa3b, v89
	v_exp_f32_e32 v53, v53
	v_cvt_pk_bf16_f32 v48, v48, v49
	v_add_f32_e32 v53, 1.0, v53
	v_rcp_f32_e32 v93, v53
	s_nop 0
	v_pk_mul_f32 v[74:75], v[92:93], v[88:89]
	s_nop 0
	v_pk_mul_f32 v[50:51], v[50:51], v[74:75]
	s_nop 0
	v_cvt_pk_bf16_f32 v49, v50, v51
	v_add_u32_e32 v50, s0, v82
	v_ashrrev_i32_e32 v51, 31, v50
	v_lshlrev_b64 v[50:51], 11, v[50:51]
	v_or_b32_e32 v54, v50, v86
	v_mov_b32_e32 v55, v51
	v_lshlrev_b64 v[54:55], 1, v[54:55]
	global_store_dwordx2 v[58:59], v[48:49], off
	v_lshl_add_u64 v[58:59], s[90:91], 0, v[54:55]
	v_lshl_add_u64 v[54:55], s[86:87], 0, v[54:55]
	global_load_dword v48, v[72:73], off offset:64
	global_load_dwordx2 v[74:75], v[58:59], off
	s_nop 0
	global_load_dwordx2 v[54:55], v[54:55], off
	s_waitcnt vmcnt(1)
	v_and_b32_e32 v95, 0xffff0000, v75
	s_waitcnt vmcnt(0)
	v_and_b32_e32 v89, 0xffff0000, v55
	v_lshlrev_b32_e32 v88, 16, v55
	v_and_b32_e32 v55, 0xffff0000, v54
	v_lshlrev_b32_e32 v54, 16, v54
	v_mul_f32_e32 v49, 0xbfb8aa3b, v54
	v_exp_f32_e32 v49, v49
	v_lshlrev_b32_e32 v94, 16, v75
	v_and_b32_e32 v75, 0xffff0000, v74
	v_lshlrev_b32_e32 v74, 16, v74
	v_add_f32_e32 v49, 1.0, v49
	v_rcp_f32_e32 v90, v49
	v_mul_f32_e32 v49, 0xbfb8aa3b, v55
	v_exp_f32_e32 v49, v49
	s_nop 0
	v_add_f32_e32 v49, 1.0, v49
	v_rcp_f32_e32 v91, v49
	v_mul_f32_e32 v49, 0xbfb8aa3b, v88
	v_exp_f32_e32 v49, v49
	v_pk_mul_f32 v[54:55], v[90:91], v[54:55]
	v_add_f32_e32 v49, 1.0, v49
	v_rcp_f32_e32 v92, v49
	v_pk_add_f32 v[46:47], v[46:47], v[48:49] op_sel_hi:[1,0]
	v_pk_add_f32 v[44:45], v[44:45], v[48:49] op_sel_hi:[1,0]
	v_mul_f32_e32 v49, 0xbfb8aa3b, v89
	v_exp_f32_e32 v49, v49
	v_pk_mul_f32 v[44:45], v[44:45], v[74:75]
	v_pk_mul_f32 v[46:47], v[46:47], v[94:95]
	v_pk_mul_f32 v[44:45], v[44:45], v[54:55]
	v_add_f32_e32 v49, 1.0, v49
	v_rcp_f32_e32 v93, v49
	v_cvt_pk_bf16_f32 v44, v44, v45
	v_pk_mul_f32 v[74:75], v[92:93], v[88:89]
	s_nop 0
	v_pk_mul_f32 v[46:47], v[46:47], v[74:75]
	s_nop 0
	v_cvt_pk_bf16_f32 v45, v46, v47
	global_store_dwordx2 v[58:59], v[44:45], off
	v_or_b32_e32 v44, v50, v85
	v_mov_b32_e32 v45, v51
	v_lshlrev_b64 v[44:45], 1, v[44:45]
	v_lshl_add_u64 v[46:47], s[90:91], 0, v[44:45]
	v_lshl_add_u64 v[44:45], s[86:87], 0, v[44:45]
	global_load_dwordx2 v[54:55], v[46:47], off
	s_nop 0
	global_load_dwordx2 v[44:45], v[44:45], off
	s_waitcnt vmcnt(1)
	v_and_b32_e32 v91, 0xffff0000, v55
	s_waitcnt vmcnt(0)
	v_and_b32_e32 v59, 0xffff0000, v45
	v_lshlrev_b32_e32 v58, 16, v45
	v_and_b32_e32 v45, 0xffff0000, v44
	v_lshlrev_b32_e32 v44, 16, v44
	v_mul_f32_e32 v49, 0xbfb8aa3b, v44
	v_exp_f32_e32 v49, v49
	v_lshlrev_b32_e32 v90, 16, v55
	v_and_b32_e32 v55, 0xffff0000, v54
	v_lshlrev_b32_e32 v54, 16, v54
	v_add_f32_e32 v49, 1.0, v49
	v_rcp_f32_e32 v74, v49
	v_mul_f32_e32 v49, 0xbfb8aa3b, v45
	v_exp_f32_e32 v49, v49
	s_nop 0
	v_add_f32_e32 v49, 1.0, v49
	v_rcp_f32_e32 v75, v49
	v_mul_f32_e32 v49, 0xbfb8aa3b, v58
	v_exp_f32_e32 v49, v49
	v_pk_mul_f32 v[44:45], v[74:75], v[44:45]
	v_add_f32_e32 v49, 1.0, v49
	v_rcp_f32_e32 v88, v49
	v_pk_add_f32 v[42:43], v[42:43], v[48:49] op_sel_hi:[1,0]
	v_pk_add_f32 v[40:41], v[40:41], v[48:49] op_sel_hi:[1,0]
	v_mul_f32_e32 v49, 0xbfb8aa3b, v59
	v_exp_f32_e32 v49, v49
	v_pk_mul_f32 v[40:41], v[40:41], v[54:55]
	v_pk_mul_f32 v[42:43], v[42:43], v[90:91]
	v_pk_mul_f32 v[40:41], v[40:41], v[44:45]
	v_add_f32_e32 v49, 1.0, v49
	v_rcp_f32_e32 v89, v49
	v_cvt_pk_bf16_f32 v40, v40, v41
	v_pk_mul_f32 v[54:55], v[88:89], v[58:59]
	s_nop 0
	v_pk_mul_f32 v[42:43], v[42:43], v[54:55]
	s_nop 0
	v_cvt_pk_bf16_f32 v41, v42, v43
	global_store_dwordx2 v[46:47], v[40:41], off
	v_or_b32_e32 v40, v50, v56
	v_mov_b32_e32 v41, v51
	v_lshlrev_b64 v[40:41], 1, v[40:41]
	v_lshl_add_u64 v[42:43], s[90:91], 0, v[40:41]
	v_lshl_add_u64 v[40:41], s[86:87], 0, v[40:41]
	global_load_dwordx2 v[44:45], v[42:43], off
	s_nop 0
	global_load_dwordx2 v[40:41], v[40:41], off
	v_or_b32_e32 v50, v50, v52
	s_waitcnt vmcnt(1)
	v_and_b32_e32 v75, 0xffff0000, v45
	s_waitcnt vmcnt(0)
	v_and_b32_e32 v47, 0xffff0000, v41
	v_lshlrev_b32_e32 v46, 16, v41
	v_and_b32_e32 v41, 0xffff0000, v40
	v_lshlrev_b32_e32 v40, 16, v40
	v_mul_f32_e32 v49, 0xbfb8aa3b, v40
	v_exp_f32_e32 v49, v49
	v_lshlrev_b32_e32 v74, 16, v45
	v_and_b32_e32 v45, 0xffff0000, v44
	v_lshlrev_b32_e32 v44, 16, v44
	v_add_f32_e32 v49, 1.0, v49
	v_rcp_f32_e32 v54, v49
	v_mul_f32_e32 v49, 0xbfb8aa3b, v41
	v_exp_f32_e32 v49, v49
	s_nop 0
	v_add_f32_e32 v49, 1.0, v49
	v_rcp_f32_e32 v55, v49
	v_mul_f32_e32 v49, 0xbfb8aa3b, v46
	v_exp_f32_e32 v49, v49
	v_pk_mul_f32 v[40:41], v[54:55], v[40:41]
	v_add_f32_e32 v49, 1.0, v49
	v_pk_add_f32 v[36:37], v[36:37], v[48:49] op_sel_hi:[1,0]
	v_rcp_f32_e32 v58, v49
	v_pk_mul_f32 v[36:37], v[36:37], v[44:45]
	v_mul_f32_e32 v44, 0xbfb8aa3b, v47
	v_exp_f32_e32 v44, v44
	v_pk_add_f32 v[38:39], v[38:39], v[48:49] op_sel_hi:[1,0]
	v_pk_mul_f32 v[36:37], v[36:37], v[40:41]
	v_pk_mul_f32 v[38:39], v[38:39], v[74:75]
	v_add_f32_e32 v44, 1.0, v44
	v_rcp_f32_e32 v59, v44
	v_cvt_pk_bf16_f32 v36, v36, v37
	v_pk_add_f32 v[32:33], v[32:33], v[48:49] op_sel_hi:[1,0]
	v_pk_add_f32 v[34:35], v[34:35], v[48:49] op_sel_hi:[1,0]
	v_pk_mul_f32 v[44:45], v[58:59], v[46:47]
	s_nop 0
	v_pk_mul_f32 v[38:39], v[38:39], v[44:45]
	s_nop 0
	v_cvt_pk_bf16_f32 v37, v38, v39
	global_store_dwordx2 v[42:43], v[36:37], off
	v_lshlrev_b64 v[36:37], 1, v[50:51]
	v_lshl_add_u64 v[38:39], s[90:91], 0, v[36:37]
	v_lshl_add_u64 v[36:37], s[86:87], 0, v[36:37]
	global_load_dwordx2 v[40:41], v[38:39], off
	s_nop 0
	global_load_dwordx2 v[36:37], v[36:37], off
	s_waitcnt vmcnt(1)
	v_and_b32_e32 v51, 0xffff0000, v41
	s_waitcnt vmcnt(0)
	v_and_b32_e32 v43, 0xffff0000, v37
	v_lshlrev_b32_e32 v42, 16, v37
	v_and_b32_e32 v37, 0xffff0000, v36
	v_lshlrev_b32_e32 v36, 16, v36
	v_lshlrev_b32_e32 v50, 16, v41
	v_and_b32_e32 v41, 0xffff0000, v40
	v_lshlrev_b32_e32 v40, 16, v40
	v_mul_f32_e32 v44, 0xbfb8aa3b, v36
	v_mul_f32_e32 v45, 0xbfb8aa3b, v37
	v_mul_f32_e32 v46, 0xbfb8aa3b, v42
	v_pk_mul_f32 v[32:33], v[32:33], v[40:41]
	v_mul_f32_e32 v40, 0xbfb8aa3b, v43
	v_exp_f32_e32 v44, v44
	v_exp_f32_e32 v45, v45
	v_exp_f32_e32 v46, v46
	v_exp_f32_e32 v40, v40
	v_add_f32_e32 v44, 1.0, v44
	v_add_f32_e32 v45, 1.0, v45
	v_add_f32_e32 v46, 1.0, v46
	v_add_f32_e32 v40, 1.0, v40
	v_rcp_f32_e32 v44, v44
	v_rcp_f32_e32 v45, v45
	v_rcp_f32_e32 v46, v46
	v_rcp_f32_e32 v47, v40
	v_pk_mul_f32 v[34:35], v[34:35], v[50:51]
	v_pk_mul_f32 v[36:37], v[44:45], v[36:37]
	v_pk_mul_f32 v[40:41], v[46:47], v[42:43]
	s_nop 0
	v_pk_mul_f32 v[34:35], v[34:35], v[40:41]
	v_pk_mul_f32 v[32:33], v[32:33], v[36:37]
	s_nop 0
	v_cvt_pk_bf16_f32 v32, v32, v33
	v_cvt_pk_bf16_f32 v33, v34, v35
	v_add_u32_e32 v34, s0, v83
	v_ashrrev_i32_e32 v35, 31, v34
	v_lshlrev_b64 v[34:35], 11, v[34:35]
	v_or_b32_e32 v36, v34, v86
	v_mov_b32_e32 v37, v35
	v_lshlrev_b64 v[36:37], 1, v[36:37]
	global_store_dwordx2 v[38:39], v[32:33], off
	v_lshl_add_u64 v[38:39], s[90:91], 0, v[36:37]
	v_lshl_add_u64 v[36:37], s[86:87], 0, v[36:37]
	global_load_dword v32, v[72:73], off offset:128
	global_load_dwordx2 v[40:41], v[38:39], off
	s_nop 0
	global_load_dwordx2 v[36:37], v[36:37], off
	s_waitcnt vmcnt(1)
	v_and_b32_e32 v49, 0xffff0000, v41
	s_waitcnt vmcnt(0)
	v_and_b32_e32 v43, 0xffff0000, v37
	v_lshlrev_b32_e32 v42, 16, v37
	v_and_b32_e32 v37, 0xffff0000, v36
	v_lshlrev_b32_e32 v36, 16, v36
	v_mul_f32_e32 v33, 0xbfb8aa3b, v36
	v_exp_f32_e32 v33, v33
	v_lshlrev_b32_e32 v48, 16, v41
	v_and_b32_e32 v41, 0xffff0000, v40
	v_lshlrev_b32_e32 v40, 16, v40
	v_add_f32_e32 v33, 1.0, v33
	v_rcp_f32_e32 v44, v33
	v_mul_f32_e32 v33, 0xbfb8aa3b, v37
	v_exp_f32_e32 v33, v33
	s_nop 0
	v_add_f32_e32 v33, 1.0, v33
	v_rcp_f32_e32 v45, v33
	v_mul_f32_e32 v33, 0xbfb8aa3b, v42
	v_exp_f32_e32 v33, v33
	v_pk_mul_f32 v[36:37], v[44:45], v[36:37]
	v_add_f32_e32 v33, 1.0, v33
	v_rcp_f32_e32 v46, v33
	v_pk_add_f32 v[30:31], v[30:31], v[32:33] op_sel_hi:[1,0]
	v_pk_add_f32 v[28:29], v[28:29], v[32:33] op_sel_hi:[1,0]
	v_mul_f32_e32 v33, 0xbfb8aa3b, v43
	v_exp_f32_e32 v33, v33
	v_pk_mul_f32 v[28:29], v[28:29], v[40:41]
	v_pk_mul_f32 v[30:31], v[30:31], v[48:49]
	v_pk_mul_f32 v[28:29], v[28:29], v[36:37]
	v_add_f32_e32 v33, 1.0, v33
	v_rcp_f32_e32 v47, v33
	v_cvt_pk_bf16_f32 v28, v28, v29
	v_pk_mul_f32 v[40:41], v[46:47], v[42:43]
	s_nop 0
	v_pk_mul_f32 v[30:31], v[30:31], v[40:41]
	s_nop 0
	v_cvt_pk_bf16_f32 v29, v30, v31
	global_store_dwordx2 v[38:39], v[28:29], off
	v_or_b32_e32 v28, v34, v85
	v_mov_b32_e32 v29, v35
	v_lshlrev_b64 v[28:29], 1, v[28:29]
	v_lshl_add_u64 v[30:31], s[90:91], 0, v[28:29]
	v_lshl_add_u64 v[28:29], s[86:87], 0, v[28:29]
	global_load_dwordx2 v[36:37], v[30:31], off
	s_nop 0
	global_load_dwordx2 v[28:29], v[28:29], off
	s_waitcnt vmcnt(1)
	v_and_b32_e32 v45, 0xffff0000, v37
	s_waitcnt vmcnt(0)
	v_and_b32_e32 v39, 0xffff0000, v29
	v_lshlrev_b32_e32 v38, 16, v29
	v_and_b32_e32 v29, 0xffff0000, v28
	v_lshlrev_b32_e32 v28, 16, v28
	v_mul_f32_e32 v33, 0xbfb8aa3b, v28
	v_exp_f32_e32 v33, v33
	v_lshlrev_b32_e32 v44, 16, v37
	v_and_b32_e32 v37, 0xffff0000, v36
	v_lshlrev_b32_e32 v36, 16, v36
	v_add_f32_e32 v33, 1.0, v33
	v_rcp_f32_e32 v40, v33
	v_mul_f32_e32 v33, 0xbfb8aa3b, v29
	v_exp_f32_e32 v33, v33
	s_nop 0
	v_add_f32_e32 v33, 1.0, v33
	v_rcp_f32_e32 v41, v33
	v_mul_f32_e32 v33, 0xbfb8aa3b, v38
	v_exp_f32_e32 v33, v33
	v_pk_mul_f32 v[28:29], v[40:41], v[28:29]
	v_add_f32_e32 v33, 1.0, v33
	v_rcp_f32_e32 v42, v33
	v_pk_add_f32 v[26:27], v[26:27], v[32:33] op_sel_hi:[1,0]
	v_pk_add_f32 v[24:25], v[24:25], v[32:33] op_sel_hi:[1,0]
	v_mul_f32_e32 v33, 0xbfb8aa3b, v39
	v_exp_f32_e32 v33, v33
	v_pk_mul_f32 v[24:25], v[24:25], v[36:37]
	v_pk_mul_f32 v[26:27], v[26:27], v[44:45]
	v_pk_mul_f32 v[24:25], v[24:25], v[28:29]
	v_add_f32_e32 v33, 1.0, v33
	v_rcp_f32_e32 v43, v33
	v_cvt_pk_bf16_f32 v24, v24, v25
	v_pk_mul_f32 v[36:37], v[42:43], v[38:39]
	s_nop 0
	v_pk_mul_f32 v[26:27], v[26:27], v[36:37]
	s_nop 0
	v_cvt_pk_bf16_f32 v25, v26, v27
	global_store_dwordx2 v[30:31], v[24:25], off
	v_or_b32_e32 v24, v34, v56
	v_mov_b32_e32 v25, v35
	v_lshlrev_b64 v[24:25], 1, v[24:25]
	v_lshl_add_u64 v[26:27], s[90:91], 0, v[24:25]
	v_lshl_add_u64 v[24:25], s[86:87], 0, v[24:25]
	global_load_dwordx2 v[28:29], v[26:27], off
	s_nop 0
	global_load_dwordx2 v[24:25], v[24:25], off
	v_or_b32_e32 v34, v34, v52
	s_waitcnt vmcnt(1)
	v_and_b32_e32 v41, 0xffff0000, v29
	s_waitcnt vmcnt(0)
	v_and_b32_e32 v31, 0xffff0000, v25
	v_lshlrev_b32_e32 v30, 16, v25
	v_and_b32_e32 v25, 0xffff0000, v24
	v_lshlrev_b32_e32 v24, 16, v24
	v_mul_f32_e32 v33, 0xbfb8aa3b, v24
	v_exp_f32_e32 v33, v33
	v_lshlrev_b32_e32 v40, 16, v29
	v_and_b32_e32 v29, 0xffff0000, v28
	v_lshlrev_b32_e32 v28, 16, v28
	v_add_f32_e32 v33, 1.0, v33
	v_rcp_f32_e32 v36, v33
	v_mul_f32_e32 v33, 0xbfb8aa3b, v25
	v_exp_f32_e32 v33, v33
	s_nop 0
	v_add_f32_e32 v33, 1.0, v33
	v_rcp_f32_e32 v37, v33
	v_mul_f32_e32 v33, 0xbfb8aa3b, v30
	v_exp_f32_e32 v33, v33
	v_pk_mul_f32 v[24:25], v[36:37], v[24:25]
	v_add_f32_e32 v33, 1.0, v33
	v_pk_add_f32 v[20:21], v[20:21], v[32:33] op_sel_hi:[1,0]
	v_rcp_f32_e32 v38, v33
	v_pk_mul_f32 v[20:21], v[20:21], v[28:29]
	v_mul_f32_e32 v28, 0xbfb8aa3b, v31
	v_exp_f32_e32 v28, v28
	v_pk_add_f32 v[22:23], v[22:23], v[32:33] op_sel_hi:[1,0]
	v_pk_mul_f32 v[20:21], v[20:21], v[24:25]
	v_pk_mul_f32 v[22:23], v[22:23], v[40:41]
	v_add_f32_e32 v28, 1.0, v28
	v_rcp_f32_e32 v39, v28
	v_cvt_pk_bf16_f32 v20, v20, v21
	v_pk_add_f32 v[16:17], v[16:17], v[32:33] op_sel_hi:[1,0]
	v_pk_add_f32 v[18:19], v[18:19], v[32:33] op_sel_hi:[1,0]
	v_pk_mul_f32 v[28:29], v[38:39], v[30:31]
	s_nop 0
	v_pk_mul_f32 v[22:23], v[22:23], v[28:29]
	s_nop 0
	v_cvt_pk_bf16_f32 v21, v22, v23
	global_store_dwordx2 v[26:27], v[20:21], off
	v_lshlrev_b64 v[20:21], 1, v[34:35]
	v_lshl_add_u64 v[22:23], s[90:91], 0, v[20:21]
	v_lshl_add_u64 v[20:21], s[86:87], 0, v[20:21]
	global_load_dwordx2 v[24:25], v[22:23], off
	s_nop 0
	global_load_dwordx2 v[20:21], v[20:21], off
	s_waitcnt vmcnt(1)
	v_and_b32_e32 v35, 0xffff0000, v25
	s_waitcnt vmcnt(0)
	v_and_b32_e32 v27, 0xffff0000, v21
	v_lshlrev_b32_e32 v26, 16, v21
	v_and_b32_e32 v21, 0xffff0000, v20
	v_lshlrev_b32_e32 v20, 16, v20
	v_lshlrev_b32_e32 v34, 16, v25
	v_and_b32_e32 v25, 0xffff0000, v24
	v_lshlrev_b32_e32 v24, 16, v24
	v_mul_f32_e32 v28, 0xbfb8aa3b, v20
	v_mul_f32_e32 v29, 0xbfb8aa3b, v21
	v_mul_f32_e32 v30, 0xbfb8aa3b, v26
	v_pk_mul_f32 v[16:17], v[16:17], v[24:25]
	v_mul_f32_e32 v24, 0xbfb8aa3b, v27
	v_exp_f32_e32 v28, v28
	v_exp_f32_e32 v29, v29
	v_exp_f32_e32 v30, v30
	v_exp_f32_e32 v24, v24
	v_add_f32_e32 v28, 1.0, v28
	v_add_f32_e32 v29, 1.0, v29
	v_add_f32_e32 v30, 1.0, v30
	v_add_f32_e32 v24, 1.0, v24
	v_rcp_f32_e32 v28, v28
	v_rcp_f32_e32 v29, v29
	v_rcp_f32_e32 v30, v30
	v_rcp_f32_e32 v31, v24
	v_pk_mul_f32 v[18:19], v[18:19], v[34:35]
	v_pk_mul_f32 v[20:21], v[28:29], v[20:21]
	v_pk_mul_f32 v[24:25], v[30:31], v[26:27]
	s_nop 0
	v_pk_mul_f32 v[18:19], v[18:19], v[24:25]
	v_pk_mul_f32 v[16:17], v[16:17], v[20:21]
	s_nop 0
	v_cvt_pk_bf16_f32 v16, v16, v17
	v_cvt_pk_bf16_f32 v17, v18, v19
	v_add_u32_e32 v18, s0, v77
	v_ashrrev_i32_e32 v19, 31, v18
	v_lshlrev_b64 v[18:19], 11, v[18:19]
	v_or_b32_e32 v20, v18, v86
	v_mov_b32_e32 v21, v19
	v_lshlrev_b64 v[20:21], 1, v[20:21]
	global_store_dwordx2 v[22:23], v[16:17], off
	v_lshl_add_u64 v[22:23], s[90:91], 0, v[20:21]
	v_lshl_add_u64 v[20:21], s[86:87], 0, v[20:21]
	global_load_dword v16, v[72:73], off offset:192
	global_load_dwordx2 v[24:25], v[22:23], off
	s_nop 0
	global_load_dwordx2 v[20:21], v[20:21], off
	s_waitcnt vmcnt(1)
	v_and_b32_e32 v33, 0xffff0000, v25
	s_waitcnt vmcnt(0)
	v_and_b32_e32 v27, 0xffff0000, v21
	v_lshlrev_b32_e32 v26, 16, v21
	v_and_b32_e32 v21, 0xffff0000, v20
	v_lshlrev_b32_e32 v20, 16, v20
	v_mul_f32_e32 v17, 0xbfb8aa3b, v20
	v_exp_f32_e32 v17, v17
	v_lshlrev_b32_e32 v32, 16, v25
	v_and_b32_e32 v25, 0xffff0000, v24
	v_lshlrev_b32_e32 v24, 16, v24
	v_add_f32_e32 v17, 1.0, v17
	v_rcp_f32_e32 v28, v17
	v_mul_f32_e32 v17, 0xbfb8aa3b, v21
	v_exp_f32_e32 v17, v17
	s_nop 0
	v_add_f32_e32 v17, 1.0, v17
	v_rcp_f32_e32 v29, v17
	v_mul_f32_e32 v17, 0xbfb8aa3b, v26
	v_exp_f32_e32 v17, v17
	v_pk_mul_f32 v[20:21], v[28:29], v[20:21]
	v_add_f32_e32 v17, 1.0, v17
	v_rcp_f32_e32 v30, v17
	v_pk_add_f32 v[14:15], v[14:15], v[16:17] op_sel_hi:[1,0]
	v_pk_add_f32 v[12:13], v[12:13], v[16:17] op_sel_hi:[1,0]
	v_mul_f32_e32 v17, 0xbfb8aa3b, v27
	v_exp_f32_e32 v17, v17
	v_pk_mul_f32 v[12:13], v[12:13], v[24:25]
	v_pk_mul_f32 v[14:15], v[14:15], v[32:33]
	v_pk_mul_f32 v[12:13], v[12:13], v[20:21]
	v_add_f32_e32 v17, 1.0, v17
	v_rcp_f32_e32 v31, v17
	v_cvt_pk_bf16_f32 v12, v12, v13
	v_pk_mul_f32 v[24:25], v[30:31], v[26:27]
	s_nop 0
	v_pk_mul_f32 v[14:15], v[14:15], v[24:25]
	s_nop 0
	v_cvt_pk_bf16_f32 v13, v14, v15
	global_store_dwordx2 v[22:23], v[12:13], off
	v_or_b32_e32 v12, v18, v85
	v_mov_b32_e32 v13, v19
	v_lshlrev_b64 v[12:13], 1, v[12:13]
	v_lshl_add_u64 v[14:15], s[90:91], 0, v[12:13]
	v_lshl_add_u64 v[12:13], s[86:87], 0, v[12:13]
	global_load_dwordx2 v[20:21], v[14:15], off
	s_nop 0
	global_load_dwordx2 v[12:13], v[12:13], off
	s_waitcnt vmcnt(1)
	v_and_b32_e32 v29, 0xffff0000, v21
	s_waitcnt vmcnt(0)
	v_and_b32_e32 v23, 0xffff0000, v13
	v_lshlrev_b32_e32 v22, 16, v13
	v_and_b32_e32 v13, 0xffff0000, v12
	v_lshlrev_b32_e32 v12, 16, v12
	v_mul_f32_e32 v17, 0xbfb8aa3b, v12
	v_exp_f32_e32 v17, v17
	v_lshlrev_b32_e32 v28, 16, v21
	v_and_b32_e32 v21, 0xffff0000, v20
	v_lshlrev_b32_e32 v20, 16, v20
	v_add_f32_e32 v17, 1.0, v17
	v_rcp_f32_e32 v24, v17
	v_mul_f32_e32 v17, 0xbfb8aa3b, v13
	v_exp_f32_e32 v17, v17
	s_nop 0
	v_add_f32_e32 v17, 1.0, v17
	v_rcp_f32_e32 v25, v17
	v_mul_f32_e32 v17, 0xbfb8aa3b, v22
	v_exp_f32_e32 v17, v17
	v_pk_mul_f32 v[12:13], v[24:25], v[12:13]
	v_add_f32_e32 v17, 1.0, v17
	v_rcp_f32_e32 v26, v17
	v_pk_add_f32 v[10:11], v[10:11], v[16:17] op_sel_hi:[1,0]
	v_pk_add_f32 v[8:9], v[8:9], v[16:17] op_sel_hi:[1,0]
	v_mul_f32_e32 v17, 0xbfb8aa3b, v23
	v_exp_f32_e32 v17, v17
	v_pk_mul_f32 v[8:9], v[8:9], v[20:21]
	v_pk_mul_f32 v[10:11], v[10:11], v[28:29]
	v_pk_mul_f32 v[8:9], v[8:9], v[12:13]
	v_add_f32_e32 v17, 1.0, v17
	v_rcp_f32_e32 v27, v17
	v_cvt_pk_bf16_f32 v8, v8, v9
	v_pk_mul_f32 v[20:21], v[26:27], v[22:23]
	s_nop 0
	v_pk_mul_f32 v[10:11], v[10:11], v[20:21]
	s_nop 0
	v_cvt_pk_bf16_f32 v9, v10, v11
	global_store_dwordx2 v[14:15], v[8:9], off
	v_or_b32_e32 v8, v18, v56
	v_mov_b32_e32 v9, v19
	v_lshlrev_b64 v[8:9], 1, v[8:9]
	v_lshl_add_u64 v[10:11], s[90:91], 0, v[8:9]
	v_lshl_add_u64 v[8:9], s[86:87], 0, v[8:9]
	global_load_dwordx2 v[12:13], v[10:11], off
	s_nop 0
	global_load_dwordx2 v[8:9], v[8:9], off
	v_or_b32_e32 v18, v18, v52
	s_waitcnt vmcnt(1)
	v_and_b32_e32 v25, 0xffff0000, v13
	s_waitcnt vmcnt(0)
	v_and_b32_e32 v15, 0xffff0000, v9
	v_lshlrev_b32_e32 v14, 16, v9
	v_and_b32_e32 v9, 0xffff0000, v8
	v_lshlrev_b32_e32 v8, 16, v8
	v_mul_f32_e32 v17, 0xbfb8aa3b, v8
	v_exp_f32_e32 v17, v17
	v_lshlrev_b32_e32 v24, 16, v13
	v_and_b32_e32 v13, 0xffff0000, v12
	v_lshlrev_b32_e32 v12, 16, v12
	v_add_f32_e32 v17, 1.0, v17
	v_rcp_f32_e32 v20, v17
	v_mul_f32_e32 v17, 0xbfb8aa3b, v9
	v_exp_f32_e32 v17, v17
	s_nop 0
	v_add_f32_e32 v17, 1.0, v17
	v_rcp_f32_e32 v21, v17
	v_mul_f32_e32 v17, 0xbfb8aa3b, v14
	v_exp_f32_e32 v17, v17
	v_pk_mul_f32 v[8:9], v[20:21], v[8:9]
	v_add_f32_e32 v17, 1.0, v17
	v_pk_add_f32 v[4:5], v[4:5], v[16:17] op_sel_hi:[1,0]
	v_rcp_f32_e32 v22, v17
	v_pk_mul_f32 v[4:5], v[4:5], v[12:13]
	v_mul_f32_e32 v12, 0xbfb8aa3b, v15
	v_exp_f32_e32 v12, v12
	v_pk_add_f32 v[6:7], v[6:7], v[16:17] op_sel_hi:[1,0]
	v_pk_mul_f32 v[4:5], v[4:5], v[8:9]
	v_pk_mul_f32 v[6:7], v[6:7], v[24:25]
	v_add_f32_e32 v12, 1.0, v12
	v_rcp_f32_e32 v23, v12
	v_cvt_pk_bf16_f32 v4, v4, v5
	v_pk_add_f32 v[0:1], v[0:1], v[16:17] op_sel_hi:[1,0]
	v_pk_add_f32 v[2:3], v[2:3], v[16:17] op_sel_hi:[1,0]
	v_pk_mul_f32 v[12:13], v[22:23], v[14:15]
	s_nop 0
	v_pk_mul_f32 v[6:7], v[6:7], v[12:13]
	s_nop 0
	v_cvt_pk_bf16_f32 v5, v6, v7
	global_store_dwordx2 v[10:11], v[4:5], off
	v_lshlrev_b64 v[4:5], 1, v[18:19]
	v_lshl_add_u64 v[6:7], s[90:91], 0, v[4:5]
	v_lshl_add_u64 v[4:5], s[86:87], 0, v[4:5]
	global_load_dwordx2 v[8:9], v[6:7], off
	s_nop 0
	global_load_dwordx2 v[4:5], v[4:5], off
	s_waitcnt vmcnt(1)
	v_and_b32_e32 v19, 0xffff0000, v9
	s_waitcnt vmcnt(0)
	v_and_b32_e32 v11, 0xffff0000, v5
	v_lshlrev_b32_e32 v10, 16, v5
	v_and_b32_e32 v5, 0xffff0000, v4
	v_lshlrev_b32_e32 v4, 16, v4
	v_lshlrev_b32_e32 v18, 16, v9
	v_and_b32_e32 v9, 0xffff0000, v8
	v_lshlrev_b32_e32 v8, 16, v8
	v_mul_f32_e32 v12, 0xbfb8aa3b, v4
	v_mul_f32_e32 v13, 0xbfb8aa3b, v5
	v_mul_f32_e32 v14, 0xbfb8aa3b, v10
	v_pk_mul_f32 v[0:1], v[0:1], v[8:9]
	v_mul_f32_e32 v8, 0xbfb8aa3b, v11
	v_exp_f32_e32 v12, v12
	v_exp_f32_e32 v13, v13
	v_exp_f32_e32 v14, v14
	v_exp_f32_e32 v8, v8
	v_add_f32_e32 v12, 1.0, v12
	v_add_f32_e32 v13, 1.0, v13
	v_add_f32_e32 v14, 1.0, v14
	v_add_f32_e32 v8, 1.0, v8
	v_rcp_f32_e32 v12, v12
	v_rcp_f32_e32 v13, v13
	v_rcp_f32_e32 v14, v14
	v_rcp_f32_e32 v15, v8
	v_pk_mul_f32 v[2:3], v[2:3], v[18:19]
	v_pk_mul_f32 v[4:5], v[12:13], v[4:5]
	v_pk_mul_f32 v[8:9], v[14:15], v[10:11]
	s_nop 0
	v_pk_mul_f32 v[2:3], v[2:3], v[8:9]
	v_pk_mul_f32 v[0:1], v[0:1], v[4:5]
	s_nop 0
	v_cvt_pk_bf16_f32 v0, v0, v1
	v_cvt_pk_bf16_f32 v1, v2, v3
	global_store_dwordx2 v[6:7], v[0:1], off
	s_cbranch_scc1 .LBB0_1654

.LBB0_1707:
	s_setprio 3
	s_and_b32 s6, s0, 0x2000
	s_xor_b32 s8, s6, 0x2000
	s_lshl_b32 s101, s8, 1
	s_add_u32 s101, s101, s100
	s_add_u32 m0, s101, 0x0
	s_nop 0
	global_load_lds_dwordx4 v[184:185], off
	s_add_u32 m0, s101, 0x1000
	v_lshl_add_u64 v[184:185], v[184:185], 0, vcc
	global_load_lds_dwordx4 v[186:187], off
	s_add_u32 m0, s101, 0x2000
	v_lshl_add_u64 v[186:187], v[186:187], 0, vcc
	global_load_lds_dwordx4 v[188:189], off
	s_add_u32 m0, s101, 0x3000
	v_lshl_add_u64 v[188:189], v[188:189], 0, vcc
	global_load_lds_dwordx4 v[190:191], off
	s_add_u32 m0, s101, 0x8000
	v_lshl_add_u64 v[190:191], v[190:191], 0, vcc
	global_load_lds_dwordx4 v[192:193], off
	s_add_u32 m0, s101, 0x9000
	v_lshl_add_u64 v[192:193], v[192:193], 0, vcc
	global_load_lds_dwordx4 v[194:195], off
	s_add_u32 m0, s101, 0xa000
	v_lshl_add_u64 v[194:195], v[194:195], 0, vcc
	global_load_lds_dwordx4 v[196:197], off
	s_add_u32 m0, s101, 0xb000
	v_lshl_add_u64 v[196:197], v[196:197], 0, vcc
	global_load_lds_dwordx4 v[198:199], off
	v_lshl_add_u64 v[198:199], v[198:199], 0, vcc
	s_lshl_b32 s6, s6, 1
	v_add_u32_e32 v102, s6, v90
	v_add_u32_e32 v103, s6, v71
	v_add_u32_e32 v128, v102, v96
	v_add_u32_e32 v144, v103, v96
	ds_read_b128 v[98:101], v128
	ds_read_b128 v[120:123], v128 offset:2048
	ds_read_b128 v[124:127], v128 offset:4096
	ds_read_b128 v[128:131], v128 offset:6144
	ds_read_b128 v[132:135], v144 offset:32768
	ds_read_b128 v[136:139], v144 offset:34816
	ds_read_b128 v[140:143], v144 offset:36864
	ds_read_b128 v[144:147], v144 offset:38912
	s_setprio 0
	s_waitcnt lgkmcnt(0)
	v_mfma_f32_16x16x32_bf16 v[60:63], v[132:135], v[98:101], v[60:63]
	v_mfma_f32_16x16x32_bf16 v[56:59], v[136:139], v[98:101], v[56:59]
	v_mfma_f32_16x16x32_bf16 v[52:55], v[140:143], v[98:101], v[52:55]
	v_mfma_f32_16x16x32_bf16 v[48:51], v[144:147], v[98:101], v[48:51]
	v_mfma_f32_16x16x32_bf16 v[44:47], v[132:135], v[120:123], v[44:47]
	v_mfma_f32_16x16x32_bf16 v[40:43], v[136:139], v[120:123], v[40:43]
	v_mfma_f32_16x16x32_bf16 v[36:39], v[140:143], v[120:123], v[36:39]
	v_mfma_f32_16x16x32_bf16 v[32:35], v[144:147], v[120:123], v[32:35]
	v_mfma_f32_16x16x32_bf16 v[28:31], v[132:135], v[124:127], v[28:31]
	v_mfma_f32_16x16x32_bf16 v[24:27], v[136:139], v[124:127], v[24:27]
	v_mfma_f32_16x16x32_bf16 v[20:23], v[140:143], v[124:127], v[20:23]
	v_mfma_f32_16x16x32_bf16 v[16:19], v[144:147], v[124:127], v[16:19]
	v_mfma_f32_16x16x32_bf16 v[12:15], v[132:135], v[128:131], v[12:15]
	v_mfma_f32_16x16x32_bf16 v[8:11], v[136:139], v[128:131], v[8:11]
	v_mfma_f32_16x16x32_bf16 v[4:7], v[140:143], v[128:131], v[4:7]
	v_mfma_f32_16x16x32_bf16 v[0:3], v[144:147], v[128:131], v[0:3]
	s_setprio 2
	v_add_u32_e32 v102, v102, v97
	ds_read_b128 v[98:101], v102
	ds_read_b128 v[120:123], v102 offset:2048
	ds_read_b128 v[124:127], v102 offset:4096
	ds_read_b128 v[128:131], v102 offset:6144
	v_add_u32_e32 v102, v103, v97
	ds_read_b128 v[132:135], v102 offset:32768
	ds_read_b128 v[136:139], v102 offset:34816
	ds_read_b128 v[140:143], v102 offset:36864
	ds_read_b128 v[144:147], v102 offset:38912
	s_setprio 0
	s_waitcnt lgkmcnt(0)
	v_mfma_f32_16x16x32_bf16 v[60:63], v[132:135], v[98:101], v[60:63]
	v_mfma_f32_16x16x32_bf16 v[56:59], v[136:139], v[98:101], v[56:59]
	v_mfma_f32_16x16x32_bf16 v[52:55], v[140:143], v[98:101], v[52:55]
	v_mfma_f32_16x16x32_bf16 v[48:51], v[144:147], v[98:101], v[48:51]
	v_mfma_f32_16x16x32_bf16 v[44:47], v[132:135], v[120:123], v[44:47]
	v_mfma_f32_16x16x32_bf16 v[40:43], v[136:139], v[120:123], v[40:43]
	v_mfma_f32_16x16x32_bf16 v[36:39], v[140:143], v[120:123], v[36:39]
	v_mfma_f32_16x16x32_bf16 v[32:35], v[144:147], v[120:123], v[32:35]
	v_mfma_f32_16x16x32_bf16 v[28:31], v[132:135], v[124:127], v[28:31]
	v_mfma_f32_16x16x32_bf16 v[24:27], v[136:139], v[124:127], v[24:27]
	v_mfma_f32_16x16x32_bf16 v[20:23], v[140:143], v[124:127], v[20:23]
	v_mfma_f32_16x16x32_bf16 v[16:19], v[144:147], v[124:127], v[16:19]
	v_mfma_f32_16x16x32_bf16 v[12:15], v[132:135], v[128:131], v[12:15]
	v_mfma_f32_16x16x32_bf16 v[8:11], v[136:139], v[128:131], v[8:11]
	v_mfma_f32_16x16x32_bf16 v[4:7], v[140:143], v[128:131], v[4:7]
	v_mfma_f32_16x16x32_bf16 v[0:3], v[144:147], v[128:131], v[0:3]
	s_setprio 1
	s_waitcnt vmcnt(0)
	s_add_u32 s36, s36, 0x80
	s_addc_u32 s37, s37, 0
	s_addk_i32 s0, 0x2000
	s_cmpk_lg_i32 s36, 0xf80
	s_waitcnt vmcnt(0)
	s_barrier
	s_cbranch_scc1 .LBB0_1707
	ds_read_b128 v[86:89], v92 offset:16384
	ds_read_b128 v[98:101], v92 offset:18432
	ds_read_b128 v[120:123], v92 offset:20480
	ds_read_b128 v[124:127], v92 offset:22528
	ds_read_b128 v[128:131], v93 offset:49152
	ds_read_b128 v[132:135], v93 offset:51200
	ds_read_b128 v[136:139], v93 offset:53248
	ds_read_b128 v[140:143], v93 offset:55296
	s_setprio 0
	s_waitcnt lgkmcnt(3)
	v_mfma_f32_16x16x32_bf16 v[60:63], v[128:131], v[86:89], v[60:63]
	s_waitcnt lgkmcnt(2)
	v_mfma_f32_16x16x32_bf16 v[56:59], v[132:135], v[86:89], v[56:59]
	s_waitcnt lgkmcnt(1)
	v_mfma_f32_16x16x32_bf16 v[52:55], v[136:139], v[86:89], v[52:55]
	s_waitcnt lgkmcnt(0)
	v_mfma_f32_16x16x32_bf16 v[48:51], v[140:143], v[86:89], v[48:51]
	v_mfma_f32_16x16x32_bf16 v[40:43], v[132:135], v[98:101], v[40:43]
	v_mfma_f32_16x16x32_bf16 v[36:39], v[136:139], v[98:101], v[36:39]
	v_mfma_f32_16x16x32_bf16 v[32:35], v[140:143], v[98:101], v[32:35]
	v_mfma_f32_16x16x32_bf16 v[20:23], v[136:139], v[120:123], v[20:23]
	v_mfma_f32_16x16x32_bf16 v[16:19], v[140:143], v[120:123], v[16:19]
	v_mfma_f32_16x16x32_bf16 v[0:3], v[140:143], v[124:127], v[0:3]
	v_mfma_f32_16x16x32_bf16 v[86:89], v[128:131], v[98:101], v[44:47]
	v_mfma_f32_16x16x32_bf16 v[98:101], v[128:131], v[120:123], v[28:31]
	v_mfma_f32_16x16x32_bf16 v[144:147], v[132:135], v[120:123], v[24:27]
	v_mfma_f32_16x16x32_bf16 v[120:123], v[128:131], v[124:127], v[12:15]
	v_mfma_f32_16x16x32_bf16 v[128:131], v[132:135], v[124:127], v[8:11]
	v_mfma_f32_16x16x32_bf16 v[132:135], v[136:139], v[124:127], v[4:7]
	s_setprio 1
	s_nop 1
	ds_read_b128 v[4:7], v94 offset:16384
	ds_read_b128 v[8:11], v94 offset:18432
	ds_read_b128 v[124:127], v94 offset:20480
	ds_read_b128 v[136:139], v94 offset:22528
	ds_read_b128 v[140:143], v95 offset:49152
	ds_read_b128 v[148:151], v95 offset:51200
	ds_read_b128 v[152:155], v95 offset:53248
	ds_read_b128 v[156:159], v95 offset:55296
	s_setprio 0
	s_waitcnt lgkmcnt(3)
	v_mfma_f32_16x16x32_bf16 v[60:63], v[140:143], v[4:7], v[60:63]
	s_waitcnt lgkmcnt(2)
	v_mfma_f32_16x16x32_bf16 v[44:47], v[148:151], v[4:7], v[56:59]
	s_waitcnt lgkmcnt(1)
	v_mfma_f32_16x16x32_bf16 v[28:31], v[152:155], v[4:7], v[52:55]
	s_waitcnt lgkmcnt(0)
	v_mfma_f32_16x16x32_bf16 v[12:15], v[156:159], v[4:7], v[48:51]
	v_mfma_f32_16x16x32_bf16 v[56:59], v[140:143], v[8:11], v[86:89]
	v_mfma_f32_16x16x32_bf16 v[40:43], v[148:151], v[8:11], v[40:43]
	v_mfma_f32_16x16x32_bf16 v[24:27], v[152:155], v[8:11], v[36:39]
	v_mfma_f32_16x16x32_bf16 v[8:11], v[156:159], v[8:11], v[32:35]
	v_mfma_f32_16x16x32_bf16 v[52:55], v[140:143], v[124:127], v[98:101]
	v_mfma_f32_16x16x32_bf16 v[36:39], v[148:151], v[124:127], v[144:147]
	v_mfma_f32_16x16x32_bf16 v[20:23], v[152:155], v[124:127], v[20:23]
	v_mfma_f32_16x16x32_bf16 v[4:7], v[156:159], v[124:127], v[16:19]
	v_mfma_f32_16x16x32_bf16 v[48:51], v[140:143], v[136:139], v[120:123]
	v_mfma_f32_16x16x32_bf16 v[32:35], v[148:151], v[136:139], v[128:131]
	v_mfma_f32_16x16x32_bf16 v[16:19], v[152:155], v[136:139], v[132:135]
	v_mfma_f32_16x16x32_bf16 v[0:3], v[156:159], v[136:139], v[0:3]
	s_setprio 1
	s_waitcnt vmcnt(0)
	s_cmpk_gt_i32 s1, 0x7f
	s_barrier
	s_cbranch_scc0 .LBB0_1710
	s_add_i32 s0, s24, 0xffffc000
	s_lshr_b32 s0, s0, 8
	v_readlane_b32 s6, v180, 24
	s_add_i32 s6, s0, s6
	s_and_b32 s10, s24, 0x80
	s_lshl_b64 s[8:9], s[6:7], 8
	v_readlane_b32 s36, v182, 19
	s_or_b32 s8, s8, s10
	s_mov_b64 s[10:11], 0
	v_readlane_b32 s37, v182, 20
	s_branch .LBB0_1711
